# snake MFMA order, K-loop s_setprio toggles removed
# baseline (speedup 1.0000x reference)
.LBB0_142:
	ds_read_b128 v[168:171], v165
	ds_read_b128 v[172:175], v165 offset:1024
	ds_read_b128 v[176:179], v165 offset:2048
	ds_read_b128 v[180:183], v165 offset:3072
	ds_read_b128 v[184:187], v166
	ds_read_b128 v[188:191], v166 offset:1024
	ds_read_b128 v[192:195], v166 offset:2048
	ds_read_b128 v[196:199], v166 offset:3072
	s_add_i32 s54, s22, 2
	s_add_u32 s55, s20, 0x80
	s_addc_u32 s23, s21, 0
	s_cmp_eq_u32 s42, s22
	s_cselect_b32 s22, s4, s55
	s_cselect_b32 s23, s5, s23
	s_cselect_b32 s61, s19, s53
	s_cselect_b32 s60, s18, s52
	v_lshl_add_u64 v[234:235], s[20:21], 0, v[154:155]
	s_add_i32 m0, s31, 0xc000
	ds_read_b128 v[200:203], v167
	ds_read_b128 v[204:207], v167 offset:1024
	ds_read_b128 v[208:211], v167 offset:2048
	ds_read_b128 v[212:215], v167 offset:3072
	ds_read_b128 v[216:219], v167 offset:4096
	ds_read_b128 v[222:225], v167 offset:5120
	ds_read_b128 v[226:229], v167 offset:6144
	ds_read_b128 v[230:233], v167 offset:7168
	global_load_lds_dwordx4 v[234:235], off
	v_lshl_add_u64 v[234:235], s[20:21], 0, v[156:157]
	s_add_i32 m0, s31, 0xe000
	s_nop 0
	global_load_lds_dwordx4 v[234:235], off
	s_waitcnt vmcnt(8)
	s_waitcnt lgkmcnt(0)
	s_barrier
	s_waitcnt lgkmcnt(0)
	v_mfma_f32_16x16x32_bf16 v[120:123], v[168:171], v[200:203], v[120:123]
	v_mfma_f32_16x16x32_bf16 v[120:123], v[172:175], v[204:207], v[120:123]
	v_mfma_f32_16x16x32_bf16 v[116:119], v[180:183], v[204:207], v[116:119]
	v_mfma_f32_16x16x32_bf16 v[116:119], v[176:179], v[200:203], v[116:119]
	v_mfma_f32_16x16x32_bf16 v[124:127], v[184:187], v[200:203], v[124:127]
	v_mfma_f32_16x16x32_bf16 v[124:127], v[188:191], v[204:207], v[124:127]
	v_mfma_f32_16x16x32_bf16 v[112:115], v[196:199], v[204:207], v[112:115]
	v_mfma_f32_16x16x32_bf16 v[112:115], v[192:195], v[200:203], v[112:115]
	v_mfma_f32_16x16x32_bf16 v[96:99], v[192:195], v[208:211], v[96:99]
	v_mfma_f32_16x16x32_bf16 v[96:99], v[196:199], v[212:215], v[96:99]
	v_mfma_f32_16x16x32_bf16 v[104:107], v[188:191], v[212:215], v[104:107]
	v_mfma_f32_16x16x32_bf16 v[104:107], v[184:187], v[208:211], v[104:107]
	v_mfma_f32_16x16x32_bf16 v[100:103], v[176:179], v[208:211], v[100:103]
	v_mfma_f32_16x16x32_bf16 v[100:103], v[180:183], v[212:215], v[100:103]
	v_mfma_f32_16x16x32_bf16 v[108:111], v[172:175], v[212:215], v[108:111]
	v_mfma_f32_16x16x32_bf16 v[108:111], v[168:171], v[208:211], v[108:111]
	v_mfma_f32_16x16x32_bf16 v[92:95], v[168:171], v[216:219], v[92:95]
	v_mfma_f32_16x16x32_bf16 v[92:95], v[172:175], v[222:225], v[92:95]
	v_mfma_f32_16x16x32_bf16 v[84:87], v[180:183], v[222:225], v[84:87]
	v_mfma_f32_16x16x32_bf16 v[84:87], v[176:179], v[216:219], v[84:87]
	v_mfma_f32_16x16x32_bf16 v[88:91], v[184:187], v[216:219], v[88:91]
	v_mfma_f32_16x16x32_bf16 v[88:91], v[188:191], v[222:225], v[88:91]
	v_mfma_f32_16x16x32_bf16 v[80:83], v[196:199], v[222:225], v[80:83]
	v_mfma_f32_16x16x32_bf16 v[80:83], v[192:195], v[216:219], v[80:83]
	v_mfma_f32_16x16x32_bf16 v[64:67], v[192:195], v[226:229], v[64:67]
	v_mfma_f32_16x16x32_bf16 v[64:67], v[196:199], v[230:233], v[64:67]
	v_mfma_f32_16x16x32_bf16 v[72:75], v[188:191], v[230:233], v[72:75]
	v_mfma_f32_16x16x32_bf16 v[72:75], v[184:187], v[226:229], v[72:75]
	v_mfma_f32_16x16x32_bf16 v[68:71], v[176:179], v[226:229], v[68:71]
	v_mfma_f32_16x16x32_bf16 v[68:71], v[180:183], v[230:233], v[68:71]
	v_mfma_f32_16x16x32_bf16 v[76:79], v[172:175], v[230:233], v[76:79]
	v_mfma_f32_16x16x32_bf16 v[76:79], v[168:171], v[226:229], v[76:79]
	s_barrier
	s_add_i32 s55, s46, s28
	v_lshl_add_u64 v[234:235], s[60:61], 0, v[132:133]
	s_mov_b32 m0, s55
	ds_read_b128 v[200:203], v167 offset:16384
	ds_read_b128 v[204:207], v167 offset:17408
	ds_read_b128 v[208:211], v167 offset:18432
	ds_read_b128 v[212:215], v167 offset:19456
	ds_read_b128 v[216:219], v167 offset:20480
	ds_read_b128 v[222:225], v167 offset:21504
	ds_read_b128 v[226:229], v167 offset:22528
	ds_read_b128 v[230:233], v167 offset:23552
	global_load_lds_dwordx4 v[234:235], off
	s_add_i32 m0, s55, 0x2000
	v_lshl_add_u64 v[236:237], s[60:61], 0, v[128:129]
	s_add_u32 s60, s60, s10
	s_addc_u32 s61, s61, s11
	s_add_i32 s55, s47, s28
	global_load_lds_dwordx4 v[236:237], off
	v_lshl_add_u64 v[238:239], s[60:61], 0, v[132:133]
	s_mov_b32 m0, s55
	v_lshl_add_u64 v[240:241], s[60:61], 0, v[128:129]
	global_load_lds_dwordx4 v[238:239], off
	s_add_i32 m0, s55, 0x2000
	v_lshl_add_u64 v[242:243], s[22:23], 0, v[134:135]
	global_load_lds_dwordx4 v[240:241], off
	s_mov_b32 m0, s31
	v_lshl_add_u64 v[244:245], s[22:23], 0, v[130:131]
	global_load_lds_dwordx4 v[242:243], off
	s_mov_b32 m0, s33
	s_nop 0
	global_load_lds_dwordx4 v[244:245], off
	s_waitcnt vmcnt(8)
	s_waitcnt lgkmcnt(0)
	s_barrier
	s_waitcnt lgkmcnt(0)
	v_mfma_f32_16x16x32_bf16 v[60:63], v[168:171], v[200:203], v[60:63]
	v_mfma_f32_16x16x32_bf16 v[60:63], v[172:175], v[204:207], v[60:63]
	v_mfma_f32_16x16x32_bf16 v[52:55], v[180:183], v[204:207], v[52:55]
	v_mfma_f32_16x16x32_bf16 v[52:55], v[176:179], v[200:203], v[52:55]
	v_mfma_f32_16x16x32_bf16 v[56:59], v[184:187], v[200:203], v[56:59]
	v_mfma_f32_16x16x32_bf16 v[56:59], v[188:191], v[204:207], v[56:59]
	v_mfma_f32_16x16x32_bf16 v[48:51], v[196:199], v[204:207], v[48:51]
	v_mfma_f32_16x16x32_bf16 v[48:51], v[192:195], v[200:203], v[48:51]
	v_mfma_f32_16x16x32_bf16 v[32:35], v[192:195], v[208:211], v[32:35]
	v_mfma_f32_16x16x32_bf16 v[32:35], v[196:199], v[212:215], v[32:35]
	v_mfma_f32_16x16x32_bf16 v[40:43], v[188:191], v[212:215], v[40:43]
	v_mfma_f32_16x16x32_bf16 v[40:43], v[184:187], v[208:211], v[40:43]
	v_mfma_f32_16x16x32_bf16 v[36:39], v[176:179], v[208:211], v[36:39]
	v_mfma_f32_16x16x32_bf16 v[36:39], v[180:183], v[212:215], v[36:39]
	v_mfma_f32_16x16x32_bf16 v[44:47], v[172:175], v[212:215], v[44:47]
	v_mfma_f32_16x16x32_bf16 v[44:47], v[168:171], v[208:211], v[44:47]
	v_mfma_f32_16x16x32_bf16 v[28:31], v[168:171], v[216:219], v[28:31]
	v_mfma_f32_16x16x32_bf16 v[28:31], v[172:175], v[222:225], v[28:31]
	v_mfma_f32_16x16x32_bf16 v[20:23], v[180:183], v[222:225], v[20:23]
	v_mfma_f32_16x16x32_bf16 v[20:23], v[176:179], v[216:219], v[20:23]
	v_mfma_f32_16x16x32_bf16 v[24:27], v[184:187], v[216:219], v[24:27]
	v_mfma_f32_16x16x32_bf16 v[24:27], v[188:191], v[222:225], v[24:27]
	v_mfma_f32_16x16x32_bf16 v[16:19], v[196:199], v[222:225], v[16:19]
	v_mfma_f32_16x16x32_bf16 v[16:19], v[192:195], v[216:219], v[16:19]
	v_mfma_f32_16x16x32_bf16 v[0:3], v[192:195], v[226:229], v[0:3]
	v_mfma_f32_16x16x32_bf16 v[0:3], v[196:199], v[230:233], v[0:3]
	v_mfma_f32_16x16x32_bf16 v[8:11], v[188:191], v[230:233], v[8:11]
	v_mfma_f32_16x16x32_bf16 v[8:11], v[184:187], v[226:229], v[8:11]
	v_mfma_f32_16x16x32_bf16 v[4:7], v[176:179], v[226:229], v[4:7]
	v_mfma_f32_16x16x32_bf16 v[4:7], v[180:183], v[230:233], v[4:7]
	v_mfma_f32_16x16x32_bf16 v[12:15], v[172:175], v[230:233], v[12:15]
	v_mfma_f32_16x16x32_bf16 v[12:15], v[168:171], v[226:229], v[12:15]
	s_barrier
	s_add_i32 s55, 0, 0x18000
	s_add_i32 s60, 0, 0x1c000
	v_add_u32_e32 v180, s55, v164
	v_add_u32_e32 v196, s60, v164
	ds_read_b128 v[168:171], v180
	ds_read_b128 v[172:175], v180 offset:1024
	ds_read_b128 v[176:179], v180 offset:2048
	ds_read_b128 v[180:183], v180 offset:3072
	ds_read_b128 v[184:187], v196
	ds_read_b128 v[188:191], v196 offset:1024
	ds_read_b128 v[192:195], v196 offset:2048
	ds_read_b128 v[196:199], v196 offset:3072
	s_add_u32 s22, s22, s10
	s_addc_u32 s23, s23, s11
	s_mov_b32 m0, s34
	v_lshl_add_u64 v[246:247], s[22:23], 0, v[134:135]
	ds_read_b128 v[200:203], v167 offset:32768
	ds_read_b128 v[204:207], v167 offset:33792
	ds_read_b128 v[208:211], v167 offset:34816
	ds_read_b128 v[212:215], v167 offset:35840
	ds_read_b128 v[216:219], v167 offset:36864
	ds_read_b128 v[222:225], v167 offset:37888
	ds_read_b128 v[226:229], v167 offset:38912
	ds_read_b128 v[230:233], v167 offset:39936
	global_load_lds_dwordx4 v[246:247], off
	v_lshl_add_u64 v[246:247], s[22:23], 0, v[130:131]
	s_mov_b32 m0, s35
	s_nop 0
	global_load_lds_dwordx4 v[246:247], off
	s_waitcnt vmcnt(8)
	s_waitcnt lgkmcnt(0)
	s_barrier
	s_waitcnt lgkmcnt(0)
	v_mfma_f32_16x16x32_bf16 v[120:123], v[168:171], v[200:203], v[120:123]
	v_mfma_f32_16x16x32_bf16 v[120:123], v[172:175], v[204:207], v[120:123]
	v_mfma_f32_16x16x32_bf16 v[116:119], v[180:183], v[204:207], v[116:119]
	v_mfma_f32_16x16x32_bf16 v[116:119], v[176:179], v[200:203], v[116:119]
	v_mfma_f32_16x16x32_bf16 v[124:127], v[184:187], v[200:203], v[124:127]
	v_mfma_f32_16x16x32_bf16 v[124:127], v[188:191], v[204:207], v[124:127]
	v_mfma_f32_16x16x32_bf16 v[112:115], v[196:199], v[204:207], v[112:115]
	v_mfma_f32_16x16x32_bf16 v[112:115], v[192:195], v[200:203], v[112:115]
	v_mfma_f32_16x16x32_bf16 v[96:99], v[192:195], v[208:211], v[96:99]
	v_mfma_f32_16x16x32_bf16 v[96:99], v[196:199], v[212:215], v[96:99]
	v_mfma_f32_16x16x32_bf16 v[104:107], v[188:191], v[212:215], v[104:107]
	v_mfma_f32_16x16x32_bf16 v[104:107], v[184:187], v[208:211], v[104:107]
	v_mfma_f32_16x16x32_bf16 v[100:103], v[176:179], v[208:211], v[100:103]
	v_mfma_f32_16x16x32_bf16 v[100:103], v[180:183], v[212:215], v[100:103]
	v_mfma_f32_16x16x32_bf16 v[108:111], v[172:175], v[212:215], v[108:111]
	v_mfma_f32_16x16x32_bf16 v[108:111], v[168:171], v[208:211], v[108:111]
	v_mfma_f32_16x16x32_bf16 v[92:95], v[168:171], v[216:219], v[92:95]
	v_mfma_f32_16x16x32_bf16 v[92:95], v[172:175], v[222:225], v[92:95]
	v_mfma_f32_16x16x32_bf16 v[84:87], v[180:183], v[222:225], v[84:87]
	v_mfma_f32_16x16x32_bf16 v[84:87], v[176:179], v[216:219], v[84:87]
	v_mfma_f32_16x16x32_bf16 v[88:91], v[184:187], v[216:219], v[88:91]
	v_mfma_f32_16x16x32_bf16 v[88:91], v[188:191], v[222:225], v[88:91]
	v_mfma_f32_16x16x32_bf16 v[80:83], v[196:199], v[222:225], v[80:83]
	v_mfma_f32_16x16x32_bf16 v[80:83], v[192:195], v[216:219], v[80:83]
	v_mfma_f32_16x16x32_bf16 v[64:67], v[192:195], v[226:229], v[64:67]
	v_mfma_f32_16x16x32_bf16 v[64:67], v[196:199], v[230:233], v[64:67]
	v_mfma_f32_16x16x32_bf16 v[72:75], v[188:191], v[230:233], v[72:75]
	v_mfma_f32_16x16x32_bf16 v[72:75], v[184:187], v[226:229], v[72:75]
	v_mfma_f32_16x16x32_bf16 v[68:71], v[176:179], v[226:229], v[68:71]
	v_mfma_f32_16x16x32_bf16 v[68:71], v[180:183], v[230:233], v[68:71]
	v_mfma_f32_16x16x32_bf16 v[76:79], v[172:175], v[230:233], v[76:79]
	v_mfma_f32_16x16x32_bf16 v[76:79], v[168:171], v[226:229], v[76:79]
	s_barrier
	s_add_i32 s22, s55, s28
	v_lshl_add_u64 v[234:235], v[234:235], 0, s[14:15]
	s_mov_b32 m0, s22
	ds_read_b128 v[200:203], v167 offset:49152
	ds_read_b128 v[204:207], v167 offset:50176
	ds_read_b128 v[208:211], v167 offset:51200
	ds_read_b128 v[212:215], v167 offset:52224
	ds_read_b128 v[216:219], v167 offset:53248
	ds_read_b128 v[222:225], v167 offset:54272
	ds_read_b128 v[226:229], v167 offset:55296
	ds_read_b128 v[230:233], v167 offset:56320
	global_load_lds_dwordx4 v[234:235], off
	v_lshl_add_u64 v[234:235], v[236:237], 0, s[14:15]
	s_add_i32 m0, s22, 0x2000
	s_add_i32 s22, s60, s28
	global_load_lds_dwordx4 v[234:235], off
	v_lshl_add_u64 v[234:235], v[238:239], 0, s[14:15]
	s_mov_b32 m0, s22
	s_nop 0
	global_load_lds_dwordx4 v[234:235], off
	v_lshl_add_u64 v[234:235], v[240:241], 0, s[14:15]
	s_add_i32 m0, s22, 0x2000
	s_nop 0
	global_load_lds_dwordx4 v[234:235], off
	v_lshl_add_u64 v[234:235], v[242:243], 0, s[14:15]
	s_mov_b32 m0, s39
	s_nop 0
	global_load_lds_dwordx4 v[234:235], off
	v_lshl_add_u64 v[234:235], v[244:245], 0, s[14:15]
	s_mov_b32 m0, s40
	s_nop 0
	global_load_lds_dwordx4 v[234:235], off
	s_waitcnt vmcnt(8)
	s_waitcnt lgkmcnt(0)
	s_barrier
	s_waitcnt lgkmcnt(0)
	v_mfma_f32_16x16x32_bf16 v[60:63], v[168:171], v[200:203], v[60:63]
	v_mfma_f32_16x16x32_bf16 v[60:63], v[172:175], v[204:207], v[60:63]
	v_mfma_f32_16x16x32_bf16 v[52:55], v[180:183], v[204:207], v[52:55]
	v_mfma_f32_16x16x32_bf16 v[52:55], v[176:179], v[200:203], v[52:55]
	v_mfma_f32_16x16x32_bf16 v[56:59], v[184:187], v[200:203], v[56:59]
	v_mfma_f32_16x16x32_bf16 v[56:59], v[188:191], v[204:207], v[56:59]
	v_mfma_f32_16x16x32_bf16 v[48:51], v[196:199], v[204:207], v[48:51]
	v_mfma_f32_16x16x32_bf16 v[48:51], v[192:195], v[200:203], v[48:51]
	v_mfma_f32_16x16x32_bf16 v[32:35], v[192:195], v[208:211], v[32:35]
	v_mfma_f32_16x16x32_bf16 v[32:35], v[196:199], v[212:215], v[32:35]
	v_mfma_f32_16x16x32_bf16 v[40:43], v[188:191], v[212:215], v[40:43]
	v_mfma_f32_16x16x32_bf16 v[40:43], v[184:187], v[208:211], v[40:43]
	v_mfma_f32_16x16x32_bf16 v[36:39], v[176:179], v[208:211], v[36:39]
	v_mfma_f32_16x16x32_bf16 v[36:39], v[180:183], v[212:215], v[36:39]
	v_mfma_f32_16x16x32_bf16 v[44:47], v[172:175], v[212:215], v[44:47]
	v_mfma_f32_16x16x32_bf16 v[44:47], v[168:171], v[208:211], v[44:47]
	v_mfma_f32_16x16x32_bf16 v[28:31], v[168:171], v[216:219], v[28:31]
	v_mfma_f32_16x16x32_bf16 v[28:31], v[172:175], v[222:225], v[28:31]
	v_mfma_f32_16x16x32_bf16 v[20:23], v[180:183], v[222:225], v[20:23]
	v_mfma_f32_16x16x32_bf16 v[20:23], v[176:179], v[216:219], v[20:23]
	v_mfma_f32_16x16x32_bf16 v[24:27], v[184:187], v[216:219], v[24:27]
	v_mfma_f32_16x16x32_bf16 v[24:27], v[188:191], v[222:225], v[24:27]
	v_mfma_f32_16x16x32_bf16 v[16:19], v[196:199], v[222:225], v[16:19]
	v_mfma_f32_16x16x32_bf16 v[16:19], v[192:195], v[216:219], v[16:19]
	v_mfma_f32_16x16x32_bf16 v[0:3], v[192:195], v[226:229], v[0:3]
	v_mfma_f32_16x16x32_bf16 v[0:3], v[196:199], v[230:233], v[0:3]
	v_mfma_f32_16x16x32_bf16 v[8:11], v[188:191], v[230:233], v[8:11]
	v_mfma_f32_16x16x32_bf16 v[8:11], v[184:187], v[226:229], v[8:11]
	v_mfma_f32_16x16x32_bf16 v[4:7], v[176:179], v[226:229], v[4:7]
	v_mfma_f32_16x16x32_bf16 v[4:7], v[180:183], v[230:233], v[4:7]
	v_mfma_f32_16x16x32_bf16 v[12:15], v[172:175], v[230:233], v[12:15]
	v_mfma_f32_16x16x32_bf16 v[12:15], v[168:171], v[226:229], v[12:15]
	s_barrier
	s_add_u32 s20, s20, 0x100
	s_addc_u32 s21, s21, 0
	s_add_u32 s52, s52, 0x100
	s_addc_u32 s53, s53, 0
	s_cmp_ge_i32 s54, s41
	s_mov_b32 s22, s54
	s_cbranch_scc0 .LBB0_142

.LBB0_228:
	ds_read_b128 v[140:143], v219
	ds_read_b128 v[144:147], v219 offset:1024
	ds_read_b128 v[148:151], v219 offset:2048
	ds_read_b128 v[152:155], v219 offset:3072
	ds_read_b128 v[156:159], v221
	ds_read_b128 v[164:167], v221 offset:1024
	ds_read_b128 v[168:171], v221 offset:2048
	ds_read_b128 v[172:175], v221 offset:3072
	s_add_i32 s62, s26, 2
	s_add_u32 s27, s24, 0x4000
	s_addc_u32 s28, s25, 0
	s_cmp_eq_u32 s46, s26
	s_cselect_b32 s30, s0, s27
	s_cselect_b32 s31, s1, s28
	s_cselect_b32 s28, s22, s60
	s_cselect_b32 s29, s23, s61
	s_add_u32 s26, s30, 0x8000
	s_addc_u32 s27, s31, 0
	v_lshl_add_u64 v[160:161], s[24:25], 0, v[132:133]
	s_add_i32 m0, s38, 0xc000
	ds_read_b128 v[176:179], v222
	ds_read_b128 v[180:183], v222 offset:1024
	ds_read_b128 v[184:187], v222 offset:2048
	ds_read_b128 v[188:191], v222 offset:3072
	ds_read_b128 v[192:195], v222 offset:4096
	ds_read_b128 v[196:199], v222 offset:5120
	ds_read_b128 v[200:203], v222 offset:6144
	ds_read_b128 v[204:207], v222 offset:7168
	global_load_lds_dwordx4 v[160:161], off
	v_lshl_add_u64 v[160:161], s[24:25], 0, v[134:135]
	s_add_i32 m0, s38, 0xe000
	s_nop 0
	global_load_lds_dwordx4 v[160:161], off
	s_waitcnt vmcnt(8)
	s_waitcnt lgkmcnt(0)
	s_barrier
	s_waitcnt lgkmcnt(0)
	v_mfma_f32_16x16x32_bf16 v[124:127], v[140:143], v[176:179], v[124:127]
	v_mfma_f32_16x16x32_bf16 v[124:127], v[144:147], v[180:183], v[124:127]
	v_mfma_f32_16x16x32_bf16 v[120:123], v[152:155], v[180:183], v[120:123]
	v_mfma_f32_16x16x32_bf16 v[120:123], v[148:151], v[176:179], v[120:123]
	v_mfma_f32_16x16x32_bf16 v[108:111], v[156:159], v[176:179], v[108:111]
	v_mfma_f32_16x16x32_bf16 v[108:111], v[164:167], v[180:183], v[108:111]
	v_mfma_f32_16x16x32_bf16 v[100:103], v[172:175], v[180:183], v[100:103]
	v_mfma_f32_16x16x32_bf16 v[100:103], v[168:171], v[176:179], v[100:103]
	v_mfma_f32_16x16x32_bf16 v[84:87], v[168:171], v[184:187], v[84:87]
	v_mfma_f32_16x16x32_bf16 v[84:87], v[172:175], v[188:191], v[84:87]
	v_mfma_f32_16x16x32_bf16 v[92:95], v[164:167], v[188:191], v[92:95]
	v_mfma_f32_16x16x32_bf16 v[92:95], v[156:159], v[184:187], v[92:95]
	v_mfma_f32_16x16x32_bf16 v[112:115], v[148:151], v[184:187], v[112:115]
	v_mfma_f32_16x16x32_bf16 v[112:115], v[152:155], v[188:191], v[112:115]
	v_mfma_f32_16x16x32_bf16 v[116:119], v[144:147], v[188:191], v[116:119]
	v_mfma_f32_16x16x32_bf16 v[116:119], v[140:143], v[184:187], v[116:119]
	v_mfma_f32_16x16x32_bf16 v[104:107], v[140:143], v[192:195], v[104:107]
	v_mfma_f32_16x16x32_bf16 v[104:107], v[144:147], v[196:199], v[104:107]
	v_mfma_f32_16x16x32_bf16 v[96:99], v[152:155], v[196:199], v[96:99]
	v_mfma_f32_16x16x32_bf16 v[96:99], v[148:151], v[192:195], v[96:99]
	v_mfma_f32_16x16x32_bf16 v[76:79], v[156:159], v[192:195], v[76:79]
	v_mfma_f32_16x16x32_bf16 v[76:79], v[164:167], v[196:199], v[76:79]
	v_mfma_f32_16x16x32_bf16 v[72:75], v[172:175], v[196:199], v[72:75]
	v_mfma_f32_16x16x32_bf16 v[72:75], v[168:171], v[192:195], v[72:75]
	v_mfma_f32_16x16x32_bf16 v[64:67], v[168:171], v[200:203], v[64:67]
	v_mfma_f32_16x16x32_bf16 v[64:67], v[172:175], v[204:207], v[64:67]
	v_mfma_f32_16x16x32_bf16 v[68:71], v[164:167], v[204:207], v[68:71]
	v_mfma_f32_16x16x32_bf16 v[68:71], v[156:159], v[200:203], v[68:71]
	v_mfma_f32_16x16x32_bf16 v[80:83], v[148:151], v[200:203], v[80:83]
	v_mfma_f32_16x16x32_bf16 v[80:83], v[152:155], v[204:207], v[80:83]
	v_mfma_f32_16x16x32_bf16 v[88:91], v[144:147], v[204:207], v[88:91]
	v_mfma_f32_16x16x32_bf16 v[88:91], v[140:143], v[200:203], v[88:91]
	s_barrier
	s_add_i32 s63, s50, s37
	v_lshl_add_u64 v[160:161], s[28:29], 0, v[128:129]
	s_mov_b32 m0, s63
	ds_read_b128 v[176:179], v222 offset:16384
	ds_read_b128 v[180:183], v222 offset:17408
	ds_read_b128 v[184:187], v222 offset:18432
	ds_read_b128 v[188:191], v222 offset:19456
	ds_read_b128 v[192:195], v222 offset:20480
	ds_read_b128 v[196:199], v222 offset:21504
	ds_read_b128 v[200:203], v222 offset:22528
	ds_read_b128 v[204:207], v222 offset:23552
	global_load_lds_dwordx4 v[160:161], off
	s_add_i32 m0, s63, 0x2000
	s_add_u32 s64, s28, 0x4000
	v_lshl_add_u64 v[160:161], s[28:29], 0, v[130:131]
	s_addc_u32 s65, s29, 0
	s_add_i32 s63, s51, s37
	global_load_lds_dwordx4 v[160:161], off
	v_lshl_add_u64 v[160:161], s[64:65], 0, v[128:129]
	s_mov_b32 m0, s63
	s_nop 0
	global_load_lds_dwordx4 v[160:161], off
	v_lshl_add_u64 v[160:161], s[64:65], 0, v[130:131]
	s_add_i32 m0, s63, 0x2000
	s_nop 0
	global_load_lds_dwordx4 v[160:161], off
	v_lshl_add_u64 v[160:161], s[30:31], 0, v[128:129]
	s_mov_b32 m0, s38
	s_nop 0
	global_load_lds_dwordx4 v[160:161], off
	v_lshl_add_u64 v[160:161], s[30:31], 0, v[130:131]
	s_mov_b32 m0, s39
	s_nop 0
	global_load_lds_dwordx4 v[160:161], off
	s_waitcnt vmcnt(8)
	s_waitcnt lgkmcnt(0)
	s_barrier
	s_waitcnt lgkmcnt(0)
	v_mfma_f32_16x16x32_bf16 v[60:63], v[140:143], v[176:179], v[60:63]
	v_mfma_f32_16x16x32_bf16 v[60:63], v[144:147], v[180:183], v[60:63]
	v_mfma_f32_16x16x32_bf16 v[56:59], v[152:155], v[180:183], v[56:59]
	v_mfma_f32_16x16x32_bf16 v[56:59], v[148:151], v[176:179], v[56:59]
	v_mfma_f32_16x16x32_bf16 v[44:47], v[156:159], v[176:179], v[44:47]
	v_mfma_f32_16x16x32_bf16 v[44:47], v[164:167], v[180:183], v[44:47]
	v_mfma_f32_16x16x32_bf16 v[36:39], v[172:175], v[180:183], v[36:39]
	v_mfma_f32_16x16x32_bf16 v[36:39], v[168:171], v[176:179], v[36:39]
	v_mfma_f32_16x16x32_bf16 v[20:23], v[168:171], v[184:187], v[20:23]
	v_mfma_f32_16x16x32_bf16 v[20:23], v[172:175], v[188:191], v[20:23]
	v_mfma_f32_16x16x32_bf16 v[28:31], v[164:167], v[188:191], v[28:31]
	v_mfma_f32_16x16x32_bf16 v[28:31], v[156:159], v[184:187], v[28:31]
	v_mfma_f32_16x16x32_bf16 v[48:51], v[148:151], v[184:187], v[48:51]
	v_mfma_f32_16x16x32_bf16 v[48:51], v[152:155], v[188:191], v[48:51]
	v_mfma_f32_16x16x32_bf16 v[52:55], v[144:147], v[188:191], v[52:55]
	v_mfma_f32_16x16x32_bf16 v[52:55], v[140:143], v[184:187], v[52:55]
	v_mfma_f32_16x16x32_bf16 v[40:43], v[140:143], v[192:195], v[40:43]
	v_mfma_f32_16x16x32_bf16 v[40:43], v[144:147], v[196:199], v[40:43]
	v_mfma_f32_16x16x32_bf16 v[32:35], v[152:155], v[196:199], v[32:35]
	v_mfma_f32_16x16x32_bf16 v[32:35], v[148:151], v[192:195], v[32:35]
	v_mfma_f32_16x16x32_bf16 v[12:15], v[156:159], v[192:195], v[12:15]
	v_mfma_f32_16x16x32_bf16 v[12:15], v[164:167], v[196:199], v[12:15]
	v_mfma_f32_16x16x32_bf16 v[8:11], v[172:175], v[196:199], v[8:11]
	v_mfma_f32_16x16x32_bf16 v[8:11], v[168:171], v[192:195], v[8:11]
	v_mfma_f32_16x16x32_bf16 v[0:3], v[168:171], v[200:203], v[0:3]
	v_mfma_f32_16x16x32_bf16 v[0:3], v[172:175], v[204:207], v[0:3]
	v_mfma_f32_16x16x32_bf16 v[4:7], v[164:167], v[204:207], v[4:7]
	v_mfma_f32_16x16x32_bf16 v[4:7], v[156:159], v[200:203], v[4:7]
	v_mfma_f32_16x16x32_bf16 v[16:19], v[148:151], v[200:203], v[16:19]
	v_mfma_f32_16x16x32_bf16 v[16:19], v[152:155], v[204:207], v[16:19]
	v_mfma_f32_16x16x32_bf16 v[24:27], v[144:147], v[204:207], v[24:27]
	v_mfma_f32_16x16x32_bf16 v[24:27], v[140:143], v[200:203], v[24:27]
	s_barrier
	s_add_i32 s63, 0, 0x18000
	s_add_i32 s64, 0, 0x1c000
	v_add_u32_e32 v152, s63, v217
	v_add_u32_e32 v160, s64, v217
	ds_read_b128 v[140:143], v152
	ds_read_b128 v[144:147], v152 offset:1024
	ds_read_b128 v[148:151], v152 offset:2048
	ds_read_b128 v[152:155], v152 offset:3072
	ds_read_b128 v[156:159], v160
	ds_read_b128 v[164:167], v160 offset:1024
	ds_read_b128 v[168:171], v160 offset:2048
	ds_read_b128 v[172:175], v160 offset:3072
	s_add_u32 s30, s30, 0x4000
	s_addc_u32 s31, s31, 0
	s_mov_b32 m0, s40
	v_lshl_add_u64 v[160:161], s[30:31], 0, v[128:129]
	ds_read_b128 v[176:179], v222 offset:32768
	ds_read_b128 v[180:183], v222 offset:33792
	ds_read_b128 v[184:187], v222 offset:34816
	ds_read_b128 v[188:191], v222 offset:35840
	ds_read_b128 v[192:195], v222 offset:36864
	ds_read_b128 v[196:199], v222 offset:37888
	ds_read_b128 v[200:203], v222 offset:38912
	ds_read_b128 v[204:207], v222 offset:39936
	global_load_lds_dwordx4 v[160:161], off
	v_lshl_add_u64 v[160:161], s[30:31], 0, v[130:131]
	s_mov_b32 m0, s41
	s_nop 0
	global_load_lds_dwordx4 v[160:161], off
	s_waitcnt vmcnt(8)
	s_waitcnt lgkmcnt(0)
	s_barrier
	s_waitcnt lgkmcnt(0)
	v_mfma_f32_16x16x32_bf16 v[124:127], v[140:143], v[176:179], v[124:127]
	v_mfma_f32_16x16x32_bf16 v[124:127], v[144:147], v[180:183], v[124:127]
	v_mfma_f32_16x16x32_bf16 v[120:123], v[152:155], v[180:183], v[120:123]
	v_mfma_f32_16x16x32_bf16 v[120:123], v[148:151], v[176:179], v[120:123]
	v_mfma_f32_16x16x32_bf16 v[108:111], v[156:159], v[176:179], v[108:111]
	v_mfma_f32_16x16x32_bf16 v[108:111], v[164:167], v[180:183], v[108:111]
	v_mfma_f32_16x16x32_bf16 v[100:103], v[172:175], v[180:183], v[100:103]
	v_mfma_f32_16x16x32_bf16 v[100:103], v[168:171], v[176:179], v[100:103]
	v_mfma_f32_16x16x32_bf16 v[84:87], v[168:171], v[184:187], v[84:87]
	v_mfma_f32_16x16x32_bf16 v[84:87], v[172:175], v[188:191], v[84:87]
	v_mfma_f32_16x16x32_bf16 v[92:95], v[164:167], v[188:191], v[92:95]
	v_mfma_f32_16x16x32_bf16 v[92:95], v[156:159], v[184:187], v[92:95]
	v_mfma_f32_16x16x32_bf16 v[112:115], v[148:151], v[184:187], v[112:115]
	v_mfma_f32_16x16x32_bf16 v[112:115], v[152:155], v[188:191], v[112:115]
	v_mfma_f32_16x16x32_bf16 v[116:119], v[144:147], v[188:191], v[116:119]
	v_mfma_f32_16x16x32_bf16 v[116:119], v[140:143], v[184:187], v[116:119]
	v_mfma_f32_16x16x32_bf16 v[104:107], v[140:143], v[192:195], v[104:107]
	v_mfma_f32_16x16x32_bf16 v[104:107], v[144:147], v[196:199], v[104:107]
	v_mfma_f32_16x16x32_bf16 v[96:99], v[152:155], v[196:199], v[96:99]
	v_mfma_f32_16x16x32_bf16 v[96:99], v[148:151], v[192:195], v[96:99]
	v_mfma_f32_16x16x32_bf16 v[76:79], v[156:159], v[192:195], v[76:79]
	v_mfma_f32_16x16x32_bf16 v[76:79], v[164:167], v[196:199], v[76:79]
	v_mfma_f32_16x16x32_bf16 v[72:75], v[172:175], v[196:199], v[72:75]
	v_mfma_f32_16x16x32_bf16 v[72:75], v[168:171], v[192:195], v[72:75]
	v_mfma_f32_16x16x32_bf16 v[64:67], v[168:171], v[200:203], v[64:67]
	v_mfma_f32_16x16x32_bf16 v[64:67], v[172:175], v[204:207], v[64:67]
	v_mfma_f32_16x16x32_bf16 v[68:71], v[164:167], v[204:207], v[68:71]
	v_mfma_f32_16x16x32_bf16 v[68:71], v[156:159], v[200:203], v[68:71]
	v_mfma_f32_16x16x32_bf16 v[80:83], v[148:151], v[200:203], v[80:83]
	v_mfma_f32_16x16x32_bf16 v[80:83], v[152:155], v[204:207], v[80:83]
	v_mfma_f32_16x16x32_bf16 v[88:91], v[144:147], v[204:207], v[88:91]
	v_mfma_f32_16x16x32_bf16 v[88:91], v[140:143], v[200:203], v[88:91]
	s_barrier
	s_add_u32 s30, s28, 0x8000
	s_addc_u32 s31, s29, 0
	s_add_i32 s63, s63, s37
	v_lshl_add_u64 v[160:161], s[30:31], 0, v[128:129]
	s_mov_b32 m0, s63
	ds_read_b128 v[176:179], v222 offset:49152
	ds_read_b128 v[180:183], v222 offset:50176
	ds_read_b128 v[184:187], v222 offset:51200
	ds_read_b128 v[188:191], v222 offset:52224
	ds_read_b128 v[192:195], v222 offset:53248
	ds_read_b128 v[196:199], v222 offset:54272
	ds_read_b128 v[200:203], v222 offset:55296
	ds_read_b128 v[204:207], v222 offset:56320
	global_load_lds_dwordx4 v[160:161], off
	s_add_i32 m0, s63, 0x2000
	s_add_u32 s28, s28, 0xc000
	v_lshl_add_u64 v[160:161], s[30:31], 0, v[130:131]
	s_addc_u32 s29, s29, 0
	s_add_i32 s30, s64, s37
	global_load_lds_dwordx4 v[160:161], off
	v_lshl_add_u64 v[160:161], s[28:29], 0, v[128:129]
	s_mov_b32 m0, s30
	s_nop 0
	global_load_lds_dwordx4 v[160:161], off
	v_lshl_add_u64 v[160:161], s[28:29], 0, v[130:131]
	s_add_i32 m0, s30, 0x2000
	s_nop 0
	global_load_lds_dwordx4 v[160:161], off
	v_lshl_add_u64 v[160:161], s[26:27], 0, v[128:129]
	s_mov_b32 m0, s44
	s_nop 0
	global_load_lds_dwordx4 v[160:161], off
	v_lshl_add_u64 v[160:161], s[26:27], 0, v[130:131]
	s_mov_b32 m0, s45
	s_nop 0
	global_load_lds_dwordx4 v[160:161], off
	s_waitcnt vmcnt(8)
	s_waitcnt lgkmcnt(0)
	s_barrier
	s_waitcnt lgkmcnt(0)
	v_mfma_f32_16x16x32_bf16 v[60:63], v[140:143], v[176:179], v[60:63]
	v_mfma_f32_16x16x32_bf16 v[60:63], v[144:147], v[180:183], v[60:63]
	v_mfma_f32_16x16x32_bf16 v[56:59], v[152:155], v[180:183], v[56:59]
	v_mfma_f32_16x16x32_bf16 v[56:59], v[148:151], v[176:179], v[56:59]
	v_mfma_f32_16x16x32_bf16 v[44:47], v[156:159], v[176:179], v[44:47]
	v_mfma_f32_16x16x32_bf16 v[44:47], v[164:167], v[180:183], v[44:47]
	v_mfma_f32_16x16x32_bf16 v[36:39], v[172:175], v[180:183], v[36:39]
	v_mfma_f32_16x16x32_bf16 v[36:39], v[168:171], v[176:179], v[36:39]
	v_mfma_f32_16x16x32_bf16 v[20:23], v[168:171], v[184:187], v[20:23]
	v_mfma_f32_16x16x32_bf16 v[20:23], v[172:175], v[188:191], v[20:23]
	v_mfma_f32_16x16x32_bf16 v[28:31], v[164:167], v[188:191], v[28:31]
	v_mfma_f32_16x16x32_bf16 v[28:31], v[156:159], v[184:187], v[28:31]
	v_mfma_f32_16x16x32_bf16 v[48:51], v[148:151], v[184:187], v[48:51]
	v_mfma_f32_16x16x32_bf16 v[48:51], v[152:155], v[188:191], v[48:51]
	v_mfma_f32_16x16x32_bf16 v[52:55], v[144:147], v[188:191], v[52:55]
	v_mfma_f32_16x16x32_bf16 v[52:55], v[140:143], v[184:187], v[52:55]
	v_mfma_f32_16x16x32_bf16 v[40:43], v[140:143], v[192:195], v[40:43]
	v_mfma_f32_16x16x32_bf16 v[40:43], v[144:147], v[196:199], v[40:43]
	v_mfma_f32_16x16x32_bf16 v[32:35], v[152:155], v[196:199], v[32:35]
	v_mfma_f32_16x16x32_bf16 v[32:35], v[148:151], v[192:195], v[32:35]
	v_mfma_f32_16x16x32_bf16 v[12:15], v[156:159], v[192:195], v[12:15]
	v_mfma_f32_16x16x32_bf16 v[12:15], v[164:167], v[196:199], v[12:15]
	v_mfma_f32_16x16x32_bf16 v[8:11], v[172:175], v[196:199], v[8:11]
	v_mfma_f32_16x16x32_bf16 v[8:11], v[168:171], v[192:195], v[8:11]
	v_mfma_f32_16x16x32_bf16 v[0:3], v[168:171], v[200:203], v[0:3]
	v_mfma_f32_16x16x32_bf16 v[0:3], v[172:175], v[204:207], v[0:3]
	v_mfma_f32_16x16x32_bf16 v[4:7], v[164:167], v[204:207], v[4:7]
	v_mfma_f32_16x16x32_bf16 v[4:7], v[156:159], v[200:203], v[4:7]
	v_mfma_f32_16x16x32_bf16 v[16:19], v[148:151], v[200:203], v[16:19]
	v_mfma_f32_16x16x32_bf16 v[16:19], v[152:155], v[204:207], v[16:19]
	v_mfma_f32_16x16x32_bf16 v[24:27], v[144:147], v[204:207], v[24:27]
	v_mfma_f32_16x16x32_bf16 v[24:27], v[140:143], v[200:203], v[24:27]
	s_barrier
	s_add_u32 s24, s24, 0x10000
	s_addc_u32 s25, s25, 0
	s_add_u32 s60, s60, 0x10000
	s_addc_u32 s61, s61, 0
	s_cmp_ge_i32 s62, s43
	s_mov_b32 s26, s62
	s_cbranch_scc0 .LBB0_228
	v_pk_mul_f32 v[200:201], v[126:127], 0.5 op_sel_hi:[1,0]
	v_pk_mul_f32 v[202:203], v[124:125], 0.5 op_sel_hi:[1,0]
	v_pk_mul_f32 v[204:205], v[122:123], 0.5 op_sel_hi:[1,0]
	v_pk_mul_f32 v[206:207], v[120:121], 0.5 op_sel_hi:[1,0]
	v_pk_mul_f32 v[210:211], v[110:111], 0.5 op_sel_hi:[1,0]
	v_pk_mul_f32 v[208:209], v[108:109], 0.5 op_sel_hi:[1,0]
	v_pk_mul_f32 v[198:199], v[102:103], 0.5 op_sel_hi:[1,0]
	v_pk_mul_f32 v[196:197], v[100:101], 0.5 op_sel_hi:[1,0]
	v_pk_mul_f32 v[194:195], v[118:119], 0.5 op_sel_hi:[1,0]
	v_pk_mul_f32 v[192:193], v[116:117], 0.5 op_sel_hi:[1,0]
	v_pk_mul_f32 v[190:191], v[114:115], 0.5 op_sel_hi:[1,0]
	v_pk_mul_f32 v[188:189], v[112:113], 0.5 op_sel_hi:[1,0]
	v_pk_mul_f32 v[186:187], v[94:95], 0.5 op_sel_hi:[1,0]
	v_pk_mul_f32 v[184:185], v[92:93], 0.5 op_sel_hi:[1,0]
	v_pk_mul_f32 v[182:183], v[86:87], 0.5 op_sel_hi:[1,0]
	v_pk_mul_f32 v[180:181], v[84:85], 0.5 op_sel_hi:[1,0]
	v_pk_mul_f32 v[178:179], v[106:107], 0.5 op_sel_hi:[1,0]
	v_pk_mul_f32 v[176:177], v[104:105], 0.5 op_sel_hi:[1,0]
	v_pk_mul_f32 v[174:175], v[98:99], 0.5 op_sel_hi:[1,0]
	v_pk_mul_f32 v[172:173], v[96:97], 0.5 op_sel_hi:[1,0]
	v_pk_mul_f32 v[170:171], v[78:79], 0.5 op_sel_hi:[1,0]
	v_pk_mul_f32 v[168:169], v[76:77], 0.5 op_sel_hi:[1,0]
	v_pk_mul_f32 v[166:167], v[74:75], 0.5 op_sel_hi:[1,0]
	v_pk_mul_f32 v[164:165], v[72:73], 0.5 op_sel_hi:[1,0]
	v_pk_mul_f32 v[160:161], v[90:91], 0.5 op_sel_hi:[1,0]
	v_pk_mul_f32 v[158:159], v[88:89], 0.5 op_sel_hi:[1,0]
	v_pk_mul_f32 v[156:157], v[82:83], 0.5 op_sel_hi:[1,0]
	v_pk_mul_f32 v[154:155], v[80:81], 0.5 op_sel_hi:[1,0]
	v_pk_mul_f32 v[152:153], v[70:71], 0.5 op_sel_hi:[1,0]
	v_pk_mul_f32 v[150:151], v[68:69], 0.5 op_sel_hi:[1,0]
	v_pk_mul_f32 v[148:149], v[66:67], 0.5 op_sel_hi:[1,0]
	v_pk_mul_f32 v[146:147], v[64:65], 0.5 op_sel_hi:[1,0]
	v_pk_mul_f32 v[144:145], v[62:63], 0.5 op_sel_hi:[1,0]
	v_pk_mul_f32 v[142:143], v[60:61], 0.5 op_sel_hi:[1,0]
	v_pk_mul_f32 v[126:127], v[58:59], 0.5 op_sel_hi:[1,0]
	v_pk_mul_f32 v[124:125], v[56:57], 0.5 op_sel_hi:[1,0]
	v_pk_mul_f32 v[122:123], v[46:47], 0.5 op_sel_hi:[1,0]
	v_pk_mul_f32 v[120:121], v[44:45], 0.5 op_sel_hi:[1,0]
	v_pk_mul_f32 v[118:119], v[38:39], 0.5 op_sel_hi:[1,0]
	v_pk_mul_f32 v[116:117], v[36:37], 0.5 op_sel_hi:[1,0]
	v_pk_mul_f32 v[114:115], v[54:55], 0.5 op_sel_hi:[1,0]
	v_pk_mul_f32 v[112:113], v[52:53], 0.5 op_sel_hi:[1,0]
	v_pk_mul_f32 v[110:111], v[50:51], 0.5 op_sel_hi:[1,0]
	v_pk_mul_f32 v[108:109], v[48:49], 0.5 op_sel_hi:[1,0]
	v_pk_mul_f32 v[106:107], v[30:31], 0.5 op_sel_hi:[1,0]
	v_pk_mul_f32 v[104:105], v[28:29], 0.5 op_sel_hi:[1,0]
	v_pk_mul_f32 v[102:103], v[22:23], 0.5 op_sel_hi:[1,0]
	v_pk_mul_f32 v[100:101], v[20:21], 0.5 op_sel_hi:[1,0]
	v_pk_mul_f32 v[98:99], v[42:43], 0.5 op_sel_hi:[1,0]
	v_pk_mul_f32 v[96:97], v[40:41], 0.5 op_sel_hi:[1,0]
	v_pk_mul_f32 v[94:95], v[34:35], 0.5 op_sel_hi:[1,0]
	v_pk_mul_f32 v[92:93], v[32:33], 0.5 op_sel_hi:[1,0]
	v_pk_mul_f32 v[90:91], v[14:15], 0.5 op_sel_hi:[1,0]
	v_pk_mul_f32 v[88:89], v[12:13], 0.5 op_sel_hi:[1,0]
	v_pk_mul_f32 v[86:87], v[10:11], 0.5 op_sel_hi:[1,0]
	v_pk_mul_f32 v[84:85], v[8:9], 0.5 op_sel_hi:[1,0]
	v_pk_mul_f32 v[82:83], v[26:27], 0.5 op_sel_hi:[1,0]
	v_pk_mul_f32 v[80:81], v[24:25], 0.5 op_sel_hi:[1,0]
	v_pk_mul_f32 v[78:79], v[18:19], 0.5 op_sel_hi:[1,0]
	v_pk_mul_f32 v[76:77], v[16:17], 0.5 op_sel_hi:[1,0]
	v_pk_mul_f32 v[74:75], v[6:7], 0.5 op_sel_hi:[1,0]
	v_pk_mul_f32 v[72:73], v[4:5], 0.5 op_sel_hi:[1,0]
	v_pk_mul_f32 v[70:71], v[2:3], 0.5 op_sel_hi:[1,0]
	v_pk_mul_f32 v[68:69], v[0:1], 0.5 op_sel_hi:[1,0]

.LBB0_323:
	ds_read_b128 v[128:131], v222
	ds_read_b128 v[132:135], v222 offset:1024
	ds_read_b128 v[136:139], v222 offset:2048
	ds_read_b128 v[140:143], v222 offset:3072
	ds_read_b128 v[144:147], v223
	ds_read_b128 v[148:151], v223 offset:1024
	ds_read_b128 v[152:155], v223 offset:2048
	ds_read_b128 v[156:159], v223 offset:3072
	s_add_i32 s53, s50, 2
	s_add_u32 s54, s0, 0x80
	s_addc_u32 s51, s1, 0
	s_cmp_eq_u32 s78, s50
	s_cselect_b32 s50, s46, s54
	s_cselect_b32 s51, s47, s51
	s_cselect_b32 s55, s49, s52
	s_cselect_b32 s54, s48, s33
	v_lshl_add_u64 v[160:161], s[0:1], 0, v[176:177]
	s_add_i32 m0, s71, 0xc000
	ds_read_b128 v[184:187], v224
	ds_read_b128 v[188:191], v224 offset:1024
	ds_read_b128 v[192:195], v224 offset:2048
	ds_read_b128 v[196:199], v224 offset:3072
	ds_read_b128 v[200:203], v224 offset:4096
	ds_read_b128 v[204:207], v224 offset:5120
	ds_read_b128 v[208:211], v224 offset:6144
	ds_read_b128 v[212:215], v224 offset:7168
	global_load_lds_dwordx4 v[160:161], off
	v_lshl_add_u64 v[160:161], s[0:1], 0, v[178:179]
	s_add_i32 m0, s71, 0xe000
	s_nop 0
	global_load_lds_dwordx4 v[160:161], off
	s_waitcnt vmcnt(8)
	s_waitcnt lgkmcnt(0)
	s_barrier
	s_waitcnt lgkmcnt(0)
	v_mfma_f32_16x16x32_bf16 v[124:127], v[128:131], v[184:187], v[124:127]
	v_mfma_f32_16x16x32_bf16 v[124:127], v[132:135], v[188:191], v[124:127]
	v_mfma_f32_16x16x32_bf16 v[120:123], v[140:143], v[188:191], v[120:123]
	v_mfma_f32_16x16x32_bf16 v[120:123], v[136:139], v[184:187], v[120:123]
	v_mfma_f32_16x16x32_bf16 v[116:119], v[144:147], v[184:187], v[116:119]
	v_mfma_f32_16x16x32_bf16 v[116:119], v[148:151], v[188:191], v[116:119]
	v_mfma_f32_16x16x32_bf16 v[112:115], v[156:159], v[188:191], v[112:115]
	v_mfma_f32_16x16x32_bf16 v[112:115], v[152:155], v[184:187], v[112:115]
	v_mfma_f32_16x16x32_bf16 v[96:99], v[152:155], v[192:195], v[96:99]
	v_mfma_f32_16x16x32_bf16 v[96:99], v[156:159], v[196:199], v[96:99]
	v_mfma_f32_16x16x32_bf16 v[100:103], v[148:151], v[196:199], v[100:103]
	v_mfma_f32_16x16x32_bf16 v[100:103], v[144:147], v[192:195], v[100:103]
	v_mfma_f32_16x16x32_bf16 v[104:107], v[136:139], v[192:195], v[104:107]
	v_mfma_f32_16x16x32_bf16 v[104:107], v[140:143], v[196:199], v[104:107]
	v_mfma_f32_16x16x32_bf16 v[108:111], v[132:135], v[196:199], v[108:111]
	v_mfma_f32_16x16x32_bf16 v[108:111], v[128:131], v[192:195], v[108:111]
	v_mfma_f32_16x16x32_bf16 v[92:95], v[128:131], v[200:203], v[92:95]
	v_mfma_f32_16x16x32_bf16 v[92:95], v[132:135], v[204:207], v[92:95]
	v_mfma_f32_16x16x32_bf16 v[88:91], v[140:143], v[204:207], v[88:91]
	v_mfma_f32_16x16x32_bf16 v[88:91], v[136:139], v[200:203], v[88:91]
	v_mfma_f32_16x16x32_bf16 v[84:87], v[144:147], v[200:203], v[84:87]
	v_mfma_f32_16x16x32_bf16 v[84:87], v[148:151], v[204:207], v[84:87]
	v_mfma_f32_16x16x32_bf16 v[80:83], v[156:159], v[204:207], v[80:83]
	v_mfma_f32_16x16x32_bf16 v[80:83], v[152:155], v[200:203], v[80:83]
	v_mfma_f32_16x16x32_bf16 v[64:67], v[152:155], v[208:211], v[64:67]
	v_mfma_f32_16x16x32_bf16 v[64:67], v[156:159], v[212:215], v[64:67]
	v_mfma_f32_16x16x32_bf16 v[68:71], v[148:151], v[212:215], v[68:71]
	v_mfma_f32_16x16x32_bf16 v[68:71], v[144:147], v[208:211], v[68:71]
	v_mfma_f32_16x16x32_bf16 v[72:75], v[136:139], v[208:211], v[72:75]
	v_mfma_f32_16x16x32_bf16 v[72:75], v[140:143], v[212:215], v[72:75]
	v_mfma_f32_16x16x32_bf16 v[76:79], v[132:135], v[212:215], v[76:79]
	v_mfma_f32_16x16x32_bf16 v[76:79], v[128:131], v[208:211], v[76:79]
	s_barrier
	s_add_i32 s60, s82, s70
	v_lshl_add_u64 v[160:161], s[54:55], 0, v[166:167]
	s_mov_b32 m0, s60
	ds_read_b128 v[184:187], v224 offset:16384
	ds_read_b128 v[188:191], v224 offset:17408
	ds_read_b128 v[192:195], v224 offset:18432
	ds_read_b128 v[196:199], v224 offset:19456
	ds_read_b128 v[200:203], v224 offset:20480
	ds_read_b128 v[204:207], v224 offset:21504
	ds_read_b128 v[208:211], v224 offset:22528
	ds_read_b128 v[212:215], v224 offset:23552
	global_load_lds_dwordx4 v[160:161], off
	s_add_i32 m0, s60, 0x2000
	v_lshl_add_u64 v[216:217], s[54:55], 0, v[170:171]
	s_add_u32 s54, s54, s10
	s_addc_u32 s55, s55, s11
	s_add_i32 s60, s83, s70
	global_load_lds_dwordx4 v[216:217], off
	v_lshl_add_u64 v[218:219], s[54:55], 0, v[166:167]
	s_mov_b32 m0, s60
	v_lshl_add_u64 v[230:231], s[54:55], 0, v[170:171]
	global_load_lds_dwordx4 v[218:219], off
	s_add_i32 m0, s60, 0x2000
	v_lshl_add_u64 v[232:233], s[50:51], 0, v[164:165]
	global_load_lds_dwordx4 v[230:231], off
	s_mov_b32 m0, s71
	v_lshl_add_u64 v[234:235], s[50:51], 0, v[168:169]
	global_load_lds_dwordx4 v[232:233], off
	s_mov_b32 m0, s72
	s_nop 0
	global_load_lds_dwordx4 v[234:235], off
	s_waitcnt vmcnt(8)
	s_waitcnt lgkmcnt(0)
	s_barrier
	s_waitcnt lgkmcnt(0)
	v_mfma_f32_16x16x32_bf16 v[60:63], v[128:131], v[184:187], v[60:63]
	v_mfma_f32_16x16x32_bf16 v[60:63], v[132:135], v[188:191], v[60:63]
	v_mfma_f32_16x16x32_bf16 v[56:59], v[140:143], v[188:191], v[56:59]
	v_mfma_f32_16x16x32_bf16 v[56:59], v[136:139], v[184:187], v[56:59]
	v_mfma_f32_16x16x32_bf16 v[52:55], v[144:147], v[184:187], v[52:55]
	v_mfma_f32_16x16x32_bf16 v[52:55], v[148:151], v[188:191], v[52:55]
	v_mfma_f32_16x16x32_bf16 v[48:51], v[156:159], v[188:191], v[48:51]
	v_mfma_f32_16x16x32_bf16 v[48:51], v[152:155], v[184:187], v[48:51]
	v_mfma_f32_16x16x32_bf16 v[32:35], v[152:155], v[192:195], v[32:35]
	v_mfma_f32_16x16x32_bf16 v[32:35], v[156:159], v[196:199], v[32:35]
	v_mfma_f32_16x16x32_bf16 v[36:39], v[148:151], v[196:199], v[36:39]
	v_mfma_f32_16x16x32_bf16 v[36:39], v[144:147], v[192:195], v[36:39]
	v_mfma_f32_16x16x32_bf16 v[40:43], v[136:139], v[192:195], v[40:43]
	v_mfma_f32_16x16x32_bf16 v[40:43], v[140:143], v[196:199], v[40:43]
	v_mfma_f32_16x16x32_bf16 v[44:47], v[132:135], v[196:199], v[44:47]
	v_mfma_f32_16x16x32_bf16 v[44:47], v[128:131], v[192:195], v[44:47]
	v_mfma_f32_16x16x32_bf16 v[28:31], v[128:131], v[200:203], v[28:31]
	v_mfma_f32_16x16x32_bf16 v[28:31], v[132:135], v[204:207], v[28:31]
	v_mfma_f32_16x16x32_bf16 v[24:27], v[140:143], v[204:207], v[24:27]
	v_mfma_f32_16x16x32_bf16 v[24:27], v[136:139], v[200:203], v[24:27]
	v_mfma_f32_16x16x32_bf16 v[20:23], v[144:147], v[200:203], v[20:23]
	v_mfma_f32_16x16x32_bf16 v[20:23], v[148:151], v[204:207], v[20:23]
	v_mfma_f32_16x16x32_bf16 v[16:19], v[156:159], v[204:207], v[16:19]
	v_mfma_f32_16x16x32_bf16 v[16:19], v[152:155], v[200:203], v[16:19]
	v_mfma_f32_16x16x32_bf16 v[0:3], v[152:155], v[208:211], v[0:3]
	v_mfma_f32_16x16x32_bf16 v[0:3], v[156:159], v[212:215], v[0:3]
	v_mfma_f32_16x16x32_bf16 v[4:7], v[148:151], v[212:215], v[4:7]
	v_mfma_f32_16x16x32_bf16 v[4:7], v[144:147], v[208:211], v[4:7]
	v_mfma_f32_16x16x32_bf16 v[8:11], v[136:139], v[208:211], v[8:11]
	v_mfma_f32_16x16x32_bf16 v[8:11], v[140:143], v[212:215], v[8:11]
	v_mfma_f32_16x16x32_bf16 v[12:15], v[132:135], v[212:215], v[12:15]
	v_mfma_f32_16x16x32_bf16 v[12:15], v[128:131], v[208:211], v[12:15]
	s_barrier
	s_add_i32 s54, 0, 0x18000
	s_add_i32 s55, 0, 0x1c000
	v_add_u32_e32 v140, s54, v221
	v_add_u32_e32 v156, s55, v221
	ds_read_b128 v[128:131], v140
	ds_read_b128 v[132:135], v140 offset:1024
	ds_read_b128 v[136:139], v140 offset:2048
	ds_read_b128 v[140:143], v140 offset:3072
	ds_read_b128 v[144:147], v156
	ds_read_b128 v[148:151], v156 offset:1024
	ds_read_b128 v[152:155], v156 offset:2048
	ds_read_b128 v[156:159], v156 offset:3072
	s_add_u32 s50, s50, s10
	s_addc_u32 s51, s51, s11
	s_mov_b32 m0, s73
	v_lshl_add_u64 v[236:237], s[50:51], 0, v[164:165]
	ds_read_b128 v[184:187], v224 offset:32768
	ds_read_b128 v[188:191], v224 offset:33792
	ds_read_b128 v[192:195], v224 offset:34816
	ds_read_b128 v[196:199], v224 offset:35840
	ds_read_b128 v[200:203], v224 offset:36864
	ds_read_b128 v[204:207], v224 offset:37888
	ds_read_b128 v[208:211], v224 offset:38912
	ds_read_b128 v[212:215], v224 offset:39936
	global_load_lds_dwordx4 v[236:237], off
	v_lshl_add_u64 v[236:237], s[50:51], 0, v[168:169]
	s_mov_b32 m0, s74
	s_nop 0
	global_load_lds_dwordx4 v[236:237], off
	s_waitcnt vmcnt(8)
	s_waitcnt lgkmcnt(0)
	s_barrier
	s_waitcnt lgkmcnt(0)
	v_mfma_f32_16x16x32_bf16 v[124:127], v[128:131], v[184:187], v[124:127]
	v_mfma_f32_16x16x32_bf16 v[124:127], v[132:135], v[188:191], v[124:127]
	v_mfma_f32_16x16x32_bf16 v[120:123], v[140:143], v[188:191], v[120:123]
	v_mfma_f32_16x16x32_bf16 v[120:123], v[136:139], v[184:187], v[120:123]
	v_mfma_f32_16x16x32_bf16 v[116:119], v[144:147], v[184:187], v[116:119]
	v_mfma_f32_16x16x32_bf16 v[116:119], v[148:151], v[188:191], v[116:119]
	v_mfma_f32_16x16x32_bf16 v[112:115], v[156:159], v[188:191], v[112:115]
	v_mfma_f32_16x16x32_bf16 v[112:115], v[152:155], v[184:187], v[112:115]
	v_mfma_f32_16x16x32_bf16 v[96:99], v[152:155], v[192:195], v[96:99]
	v_mfma_f32_16x16x32_bf16 v[96:99], v[156:159], v[196:199], v[96:99]
	v_mfma_f32_16x16x32_bf16 v[100:103], v[148:151], v[196:199], v[100:103]
	v_mfma_f32_16x16x32_bf16 v[100:103], v[144:147], v[192:195], v[100:103]
	v_mfma_f32_16x16x32_bf16 v[104:107], v[136:139], v[192:195], v[104:107]
	v_mfma_f32_16x16x32_bf16 v[104:107], v[140:143], v[196:199], v[104:107]
	v_mfma_f32_16x16x32_bf16 v[108:111], v[132:135], v[196:199], v[108:111]
	v_mfma_f32_16x16x32_bf16 v[108:111], v[128:131], v[192:195], v[108:111]
	v_mfma_f32_16x16x32_bf16 v[92:95], v[128:131], v[200:203], v[92:95]
	v_mfma_f32_16x16x32_bf16 v[92:95], v[132:135], v[204:207], v[92:95]
	v_mfma_f32_16x16x32_bf16 v[88:91], v[140:143], v[204:207], v[88:91]
	v_mfma_f32_16x16x32_bf16 v[88:91], v[136:139], v[200:203], v[88:91]
	v_mfma_f32_16x16x32_bf16 v[84:87], v[144:147], v[200:203], v[84:87]
	v_mfma_f32_16x16x32_bf16 v[84:87], v[148:151], v[204:207], v[84:87]
	v_mfma_f32_16x16x32_bf16 v[80:83], v[156:159], v[204:207], v[80:83]
	v_mfma_f32_16x16x32_bf16 v[80:83], v[152:155], v[200:203], v[80:83]
	v_mfma_f32_16x16x32_bf16 v[64:67], v[152:155], v[208:211], v[64:67]
	v_mfma_f32_16x16x32_bf16 v[64:67], v[156:159], v[212:215], v[64:67]
	v_mfma_f32_16x16x32_bf16 v[68:71], v[148:151], v[212:215], v[68:71]
	v_mfma_f32_16x16x32_bf16 v[68:71], v[144:147], v[208:211], v[68:71]
	v_mfma_f32_16x16x32_bf16 v[72:75], v[136:139], v[208:211], v[72:75]
	v_mfma_f32_16x16x32_bf16 v[72:75], v[140:143], v[212:215], v[72:75]
	v_mfma_f32_16x16x32_bf16 v[76:79], v[132:135], v[212:215], v[76:79]
	v_mfma_f32_16x16x32_bf16 v[76:79], v[128:131], v[208:211], v[76:79]
	s_barrier
	s_add_i32 s50, s54, s70
	v_lshl_add_u64 v[160:161], v[160:161], 0, s[36:37]
	s_mov_b32 m0, s50
	ds_read_b128 v[184:187], v224 offset:49152
	ds_read_b128 v[188:191], v224 offset:50176
	ds_read_b128 v[192:195], v224 offset:51200
	ds_read_b128 v[196:199], v224 offset:52224
	ds_read_b128 v[200:203], v224 offset:53248
	ds_read_b128 v[204:207], v224 offset:54272
	ds_read_b128 v[208:211], v224 offset:55296
	ds_read_b128 v[212:215], v224 offset:56320
	global_load_lds_dwordx4 v[160:161], off
	v_lshl_add_u64 v[160:161], v[216:217], 0, s[36:37]
	s_add_i32 m0, s50, 0x2000
	s_add_i32 s50, s55, s70
	global_load_lds_dwordx4 v[160:161], off
	v_lshl_add_u64 v[160:161], v[218:219], 0, s[36:37]
	s_mov_b32 m0, s50
	s_nop 0
	global_load_lds_dwordx4 v[160:161], off
	v_lshl_add_u64 v[160:161], v[230:231], 0, s[36:37]
	s_add_i32 m0, s50, 0x2000
	s_nop 0
	global_load_lds_dwordx4 v[160:161], off
	v_lshl_add_u64 v[160:161], v[232:233], 0, s[36:37]
	s_mov_b32 m0, s76
	s_nop 0
	global_load_lds_dwordx4 v[160:161], off
	v_lshl_add_u64 v[160:161], v[234:235], 0, s[36:37]
	s_mov_b32 m0, s77
	s_nop 0
	global_load_lds_dwordx4 v[160:161], off
	s_waitcnt vmcnt(8)
	s_waitcnt lgkmcnt(0)
	s_barrier
	s_waitcnt lgkmcnt(0)
	v_mfma_f32_16x16x32_bf16 v[60:63], v[128:131], v[184:187], v[60:63]
	v_mfma_f32_16x16x32_bf16 v[60:63], v[132:135], v[188:191], v[60:63]
	v_mfma_f32_16x16x32_bf16 v[56:59], v[140:143], v[188:191], v[56:59]
	v_mfma_f32_16x16x32_bf16 v[56:59], v[136:139], v[184:187], v[56:59]
	v_mfma_f32_16x16x32_bf16 v[52:55], v[144:147], v[184:187], v[52:55]
	v_mfma_f32_16x16x32_bf16 v[52:55], v[148:151], v[188:191], v[52:55]
	v_mfma_f32_16x16x32_bf16 v[48:51], v[156:159], v[188:191], v[48:51]
	v_mfma_f32_16x16x32_bf16 v[48:51], v[152:155], v[184:187], v[48:51]
	v_mfma_f32_16x16x32_bf16 v[32:35], v[152:155], v[192:195], v[32:35]
	v_mfma_f32_16x16x32_bf16 v[32:35], v[156:159], v[196:199], v[32:35]
	v_mfma_f32_16x16x32_bf16 v[36:39], v[148:151], v[196:199], v[36:39]
	v_mfma_f32_16x16x32_bf16 v[36:39], v[144:147], v[192:195], v[36:39]
	v_mfma_f32_16x16x32_bf16 v[40:43], v[136:139], v[192:195], v[40:43]
	v_mfma_f32_16x16x32_bf16 v[40:43], v[140:143], v[196:199], v[40:43]
	v_mfma_f32_16x16x32_bf16 v[44:47], v[132:135], v[196:199], v[44:47]
	v_mfma_f32_16x16x32_bf16 v[44:47], v[128:131], v[192:195], v[44:47]
	v_mfma_f32_16x16x32_bf16 v[28:31], v[128:131], v[200:203], v[28:31]
	v_mfma_f32_16x16x32_bf16 v[28:31], v[132:135], v[204:207], v[28:31]
	v_mfma_f32_16x16x32_bf16 v[24:27], v[140:143], v[204:207], v[24:27]
	v_mfma_f32_16x16x32_bf16 v[24:27], v[136:139], v[200:203], v[24:27]
	v_mfma_f32_16x16x32_bf16 v[20:23], v[144:147], v[200:203], v[20:23]
	v_mfma_f32_16x16x32_bf16 v[20:23], v[148:151], v[204:207], v[20:23]
	v_mfma_f32_16x16x32_bf16 v[16:19], v[156:159], v[204:207], v[16:19]
	v_mfma_f32_16x16x32_bf16 v[16:19], v[152:155], v[200:203], v[16:19]
	v_mfma_f32_16x16x32_bf16 v[0:3], v[152:155], v[208:211], v[0:3]
	v_mfma_f32_16x16x32_bf16 v[0:3], v[156:159], v[212:215], v[0:3]
	v_mfma_f32_16x16x32_bf16 v[4:7], v[148:151], v[212:215], v[4:7]
	v_mfma_f32_16x16x32_bf16 v[4:7], v[144:147], v[208:211], v[4:7]
	v_mfma_f32_16x16x32_bf16 v[8:11], v[136:139], v[208:211], v[8:11]
	v_mfma_f32_16x16x32_bf16 v[8:11], v[140:143], v[212:215], v[8:11]
	v_mfma_f32_16x16x32_bf16 v[12:15], v[132:135], v[212:215], v[12:15]
	v_mfma_f32_16x16x32_bf16 v[12:15], v[128:131], v[208:211], v[12:15]
	s_barrier
	s_add_u32 s0, s0, 0x100
	s_addc_u32 s1, s1, 0
	s_add_u32 s33, s33, 0x100
	s_addc_u32 s52, s52, 0
	s_cmp_ge_i32 s53, s75
	s_mov_b32 s50, s53
	s_cbranch_scc0 .LBB0_323

.LBB0_592:
	ds_read_b128 v[144:147], v157
	ds_read_b128 v[148:151], v157 offset:1024
	ds_read_b128 v[164:167], v157 offset:2048
	ds_read_b128 v[168:171], v157 offset:3072
	ds_read_b128 v[172:175], v158
	ds_read_b128 v[176:179], v158 offset:1024
	ds_read_b128 v[180:183], v158 offset:2048
	ds_read_b128 v[184:187], v158 offset:3072
	s_add_i32 s64, s34, 2
	s_add_u32 s65, s30, 0x80
	s_addc_u32 s35, s31, 0
	s_cmp_eq_u32 s49, s34
	s_cselect_b32 s34, s2, s65
	s_cselect_b32 s35, s3, s35
	s_cselect_b32 s67, s29, s63
	s_cselect_b32 s66, s28, s62
	v_lshl_add_u64 v[152:153], s[30:31], 0, v[136:137]
	s_add_i32 m0, s41, 0xc000
	ds_read_b128 v[188:191], v159
	ds_read_b128 v[192:195], v159 offset:1024
	ds_read_b128 v[196:199], v159 offset:2048
	ds_read_b128 v[200:203], v159 offset:3072
	ds_read_b128 v[204:207], v159 offset:4096
	ds_read_b128 v[208:211], v159 offset:5120
	ds_read_b128 v[212:215], v159 offset:6144
	ds_read_b128 v[216:219], v159 offset:7168
	global_load_lds_dwordx4 v[152:153], off
	v_lshl_add_u64 v[152:153], s[30:31], 0, v[138:139]
	s_add_i32 m0, s41, 0xe000
	s_nop 0
	global_load_lds_dwordx4 v[152:153], off
	s_waitcnt vmcnt(8)
	s_waitcnt lgkmcnt(0)
	s_barrier
	s_waitcnt lgkmcnt(0)
	v_mfma_f32_16x16x32_bf16 v[120:123], v[144:147], v[188:191], v[120:123]
	v_mfma_f32_16x16x32_bf16 v[120:123], v[148:151], v[192:195], v[120:123]
	v_mfma_f32_16x16x32_bf16 v[124:127], v[168:171], v[192:195], v[124:127]
	v_mfma_f32_16x16x32_bf16 v[124:127], v[164:167], v[188:191], v[124:127]
	v_mfma_f32_16x16x32_bf16 v[116:119], v[172:175], v[188:191], v[116:119]
	v_mfma_f32_16x16x32_bf16 v[116:119], v[176:179], v[192:195], v[116:119]
	v_mfma_f32_16x16x32_bf16 v[112:115], v[184:187], v[192:195], v[112:115]
	v_mfma_f32_16x16x32_bf16 v[112:115], v[180:183], v[188:191], v[112:115]
	v_mfma_f32_16x16x32_bf16 v[96:99], v[180:183], v[196:199], v[96:99]
	v_mfma_f32_16x16x32_bf16 v[96:99], v[184:187], v[200:203], v[96:99]
	v_mfma_f32_16x16x32_bf16 v[100:103], v[176:179], v[200:203], v[100:103]
	v_mfma_f32_16x16x32_bf16 v[100:103], v[172:175], v[196:199], v[100:103]
	v_mfma_f32_16x16x32_bf16 v[104:107], v[164:167], v[196:199], v[104:107]
	v_mfma_f32_16x16x32_bf16 v[104:107], v[168:171], v[200:203], v[104:107]
	v_mfma_f32_16x16x32_bf16 v[108:111], v[148:151], v[200:203], v[108:111]
	v_mfma_f32_16x16x32_bf16 v[108:111], v[144:147], v[196:199], v[108:111]
	v_mfma_f32_16x16x32_bf16 v[92:95], v[144:147], v[204:207], v[92:95]
	v_mfma_f32_16x16x32_bf16 v[92:95], v[148:151], v[208:211], v[92:95]
	v_mfma_f32_16x16x32_bf16 v[88:91], v[168:171], v[208:211], v[88:91]
	v_mfma_f32_16x16x32_bf16 v[88:91], v[164:167], v[204:207], v[88:91]
	v_mfma_f32_16x16x32_bf16 v[84:87], v[172:175], v[204:207], v[84:87]
	v_mfma_f32_16x16x32_bf16 v[84:87], v[176:179], v[208:211], v[84:87]
	v_mfma_f32_16x16x32_bf16 v[80:83], v[184:187], v[208:211], v[80:83]
	v_mfma_f32_16x16x32_bf16 v[80:83], v[180:183], v[204:207], v[80:83]
	v_mfma_f32_16x16x32_bf16 v[64:67], v[180:183], v[212:215], v[64:67]
	v_mfma_f32_16x16x32_bf16 v[64:67], v[184:187], v[216:219], v[64:67]
	v_mfma_f32_16x16x32_bf16 v[68:71], v[176:179], v[216:219], v[68:71]
	v_mfma_f32_16x16x32_bf16 v[68:71], v[172:175], v[212:215], v[68:71]
	v_mfma_f32_16x16x32_bf16 v[72:75], v[164:167], v[212:215], v[72:75]
	v_mfma_f32_16x16x32_bf16 v[72:75], v[168:171], v[216:219], v[72:75]
	v_mfma_f32_16x16x32_bf16 v[76:79], v[148:151], v[216:219], v[76:79]
	v_mfma_f32_16x16x32_bf16 v[76:79], v[144:147], v[212:215], v[76:79]
	s_barrier
	s_add_i32 s65, s52, s40
	v_lshl_add_u64 v[152:153], s[66:67], 0, v[130:131]
	s_mov_b32 m0, s65
	ds_read_b128 v[188:191], v159 offset:16384
	ds_read_b128 v[192:195], v159 offset:17408
	ds_read_b128 v[196:199], v159 offset:18432
	ds_read_b128 v[200:203], v159 offset:19456
	ds_read_b128 v[204:207], v159 offset:20480
	ds_read_b128 v[208:211], v159 offset:21504
	ds_read_b128 v[212:215], v159 offset:22528
	ds_read_b128 v[216:219], v159 offset:23552
	global_load_lds_dwordx4 v[152:153], off
	s_add_i32 m0, s65, 0x2000
	v_lshl_add_u64 v[160:161], s[66:67], 0, v[134:135]
	s_add_u32 s66, s66, s8
	s_addc_u32 s67, s67, s9
	s_add_i32 s65, s53, s40
	global_load_lds_dwordx4 v[160:161], off
	v_lshl_add_u64 v[222:223], s[66:67], 0, v[130:131]
	s_mov_b32 m0, s65
	v_lshl_add_u64 v[224:225], s[66:67], 0, v[134:135]
	global_load_lds_dwordx4 v[222:223], off
	s_add_i32 m0, s65, 0x2000
	v_lshl_add_u64 v[226:227], s[34:35], 0, v[128:129]
	global_load_lds_dwordx4 v[224:225], off
	s_mov_b32 m0, s41
	v_lshl_add_u64 v[228:229], s[34:35], 0, v[132:133]
	global_load_lds_dwordx4 v[226:227], off
	s_mov_b32 m0, s42
	s_nop 0
	global_load_lds_dwordx4 v[228:229], off
	s_waitcnt vmcnt(8)
	s_waitcnt lgkmcnt(0)
	s_barrier
	s_waitcnt lgkmcnt(0)
	v_mfma_f32_16x16x32_bf16 v[60:63], v[144:147], v[188:191], v[60:63]
	v_mfma_f32_16x16x32_bf16 v[60:63], v[148:151], v[192:195], v[60:63]
	v_mfma_f32_16x16x32_bf16 v[56:59], v[168:171], v[192:195], v[56:59]
	v_mfma_f32_16x16x32_bf16 v[56:59], v[164:167], v[188:191], v[56:59]
	v_mfma_f32_16x16x32_bf16 v[52:55], v[172:175], v[188:191], v[52:55]
	v_mfma_f32_16x16x32_bf16 v[52:55], v[176:179], v[192:195], v[52:55]
	v_mfma_f32_16x16x32_bf16 v[48:51], v[184:187], v[192:195], v[48:51]
	v_mfma_f32_16x16x32_bf16 v[48:51], v[180:183], v[188:191], v[48:51]
	v_mfma_f32_16x16x32_bf16 v[32:35], v[180:183], v[196:199], v[32:35]
	v_mfma_f32_16x16x32_bf16 v[32:35], v[184:187], v[200:203], v[32:35]
	v_mfma_f32_16x16x32_bf16 v[36:39], v[176:179], v[200:203], v[36:39]
	v_mfma_f32_16x16x32_bf16 v[36:39], v[172:175], v[196:199], v[36:39]
	v_mfma_f32_16x16x32_bf16 v[40:43], v[164:167], v[196:199], v[40:43]
	v_mfma_f32_16x16x32_bf16 v[40:43], v[168:171], v[200:203], v[40:43]
	v_mfma_f32_16x16x32_bf16 v[44:47], v[148:151], v[200:203], v[44:47]
	v_mfma_f32_16x16x32_bf16 v[44:47], v[144:147], v[196:199], v[44:47]
	v_mfma_f32_16x16x32_bf16 v[28:31], v[144:147], v[204:207], v[28:31]
	v_mfma_f32_16x16x32_bf16 v[28:31], v[148:151], v[208:211], v[28:31]
	v_mfma_f32_16x16x32_bf16 v[24:27], v[168:171], v[208:211], v[24:27]
	v_mfma_f32_16x16x32_bf16 v[24:27], v[164:167], v[204:207], v[24:27]
	v_mfma_f32_16x16x32_bf16 v[20:23], v[172:175], v[204:207], v[20:23]
	v_mfma_f32_16x16x32_bf16 v[20:23], v[176:179], v[208:211], v[20:23]
	v_mfma_f32_16x16x32_bf16 v[16:19], v[184:187], v[208:211], v[16:19]
	v_mfma_f32_16x16x32_bf16 v[16:19], v[180:183], v[204:207], v[16:19]
	v_mfma_f32_16x16x32_bf16 v[0:3], v[180:183], v[212:215], v[0:3]
	v_mfma_f32_16x16x32_bf16 v[0:3], v[184:187], v[216:219], v[0:3]
	v_mfma_f32_16x16x32_bf16 v[4:7], v[176:179], v[216:219], v[4:7]
	v_mfma_f32_16x16x32_bf16 v[4:7], v[172:175], v[212:215], v[4:7]
	v_mfma_f32_16x16x32_bf16 v[8:11], v[164:167], v[212:215], v[8:11]
	v_mfma_f32_16x16x32_bf16 v[8:11], v[168:171], v[216:219], v[8:11]
	v_mfma_f32_16x16x32_bf16 v[12:15], v[148:151], v[216:219], v[12:15]
	v_mfma_f32_16x16x32_bf16 v[12:15], v[144:147], v[212:215], v[12:15]
	s_barrier
	s_add_i32 s65, 0, 0x18000
	s_add_i32 s66, 0, 0x1c000
	v_add_u32_e32 v168, s65, v155
	v_add_u32_e32 v184, s66, v155
	ds_read_b128 v[144:147], v168
	ds_read_b128 v[148:151], v168 offset:1024
	ds_read_b128 v[164:167], v168 offset:2048
	ds_read_b128 v[168:171], v168 offset:3072
	ds_read_b128 v[172:175], v184
	ds_read_b128 v[176:179], v184 offset:1024
	ds_read_b128 v[180:183], v184 offset:2048
	ds_read_b128 v[184:187], v184 offset:3072
	s_add_u32 s34, s34, s8
	s_addc_u32 s35, s35, s9
	s_mov_b32 m0, s43
	v_lshl_add_u64 v[230:231], s[34:35], 0, v[128:129]
	ds_read_b128 v[188:191], v159 offset:32768
	ds_read_b128 v[192:195], v159 offset:33792
	ds_read_b128 v[196:199], v159 offset:34816
	ds_read_b128 v[200:203], v159 offset:35840
	ds_read_b128 v[204:207], v159 offset:36864
	ds_read_b128 v[208:211], v159 offset:37888
	ds_read_b128 v[212:215], v159 offset:38912
	ds_read_b128 v[216:219], v159 offset:39936
	global_load_lds_dwordx4 v[230:231], off
	v_lshl_add_u64 v[230:231], s[34:35], 0, v[132:133]
	s_mov_b32 m0, s44
	s_nop 0
	global_load_lds_dwordx4 v[230:231], off
	s_waitcnt vmcnt(8)
	s_waitcnt lgkmcnt(0)
	s_barrier
	s_waitcnt lgkmcnt(0)
	v_mfma_f32_16x16x32_bf16 v[120:123], v[144:147], v[188:191], v[120:123]
	v_mfma_f32_16x16x32_bf16 v[120:123], v[148:151], v[192:195], v[120:123]
	v_mfma_f32_16x16x32_bf16 v[124:127], v[168:171], v[192:195], v[124:127]
	v_mfma_f32_16x16x32_bf16 v[124:127], v[164:167], v[188:191], v[124:127]
	v_mfma_f32_16x16x32_bf16 v[116:119], v[172:175], v[188:191], v[116:119]
	v_mfma_f32_16x16x32_bf16 v[116:119], v[176:179], v[192:195], v[116:119]
	v_mfma_f32_16x16x32_bf16 v[112:115], v[184:187], v[192:195], v[112:115]
	v_mfma_f32_16x16x32_bf16 v[112:115], v[180:183], v[188:191], v[112:115]
	v_mfma_f32_16x16x32_bf16 v[96:99], v[180:183], v[196:199], v[96:99]
	v_mfma_f32_16x16x32_bf16 v[96:99], v[184:187], v[200:203], v[96:99]
	v_mfma_f32_16x16x32_bf16 v[100:103], v[176:179], v[200:203], v[100:103]
	v_mfma_f32_16x16x32_bf16 v[100:103], v[172:175], v[196:199], v[100:103]
	v_mfma_f32_16x16x32_bf16 v[104:107], v[164:167], v[196:199], v[104:107]
	v_mfma_f32_16x16x32_bf16 v[104:107], v[168:171], v[200:203], v[104:107]
	v_mfma_f32_16x16x32_bf16 v[108:111], v[148:151], v[200:203], v[108:111]
	v_mfma_f32_16x16x32_bf16 v[108:111], v[144:147], v[196:199], v[108:111]
	v_mfma_f32_16x16x32_bf16 v[92:95], v[144:147], v[204:207], v[92:95]
	v_mfma_f32_16x16x32_bf16 v[92:95], v[148:151], v[208:211], v[92:95]
	v_mfma_f32_16x16x32_bf16 v[88:91], v[168:171], v[208:211], v[88:91]
	v_mfma_f32_16x16x32_bf16 v[88:91], v[164:167], v[204:207], v[88:91]
	v_mfma_f32_16x16x32_bf16 v[84:87], v[172:175], v[204:207], v[84:87]
	v_mfma_f32_16x16x32_bf16 v[84:87], v[176:179], v[208:211], v[84:87]
	v_mfma_f32_16x16x32_bf16 v[80:83], v[184:187], v[208:211], v[80:83]
	v_mfma_f32_16x16x32_bf16 v[80:83], v[180:183], v[204:207], v[80:83]
	v_mfma_f32_16x16x32_bf16 v[64:67], v[180:183], v[212:215], v[64:67]
	v_mfma_f32_16x16x32_bf16 v[64:67], v[184:187], v[216:219], v[64:67]
	v_mfma_f32_16x16x32_bf16 v[68:71], v[176:179], v[216:219], v[68:71]
	v_mfma_f32_16x16x32_bf16 v[68:71], v[172:175], v[212:215], v[68:71]
	v_mfma_f32_16x16x32_bf16 v[72:75], v[164:167], v[212:215], v[72:75]
	v_mfma_f32_16x16x32_bf16 v[72:75], v[168:171], v[216:219], v[72:75]
	v_mfma_f32_16x16x32_bf16 v[76:79], v[148:151], v[216:219], v[76:79]
	v_mfma_f32_16x16x32_bf16 v[76:79], v[144:147], v[212:215], v[76:79]
	s_barrier
	s_add_i32 s34, s65, s40
	v_lshl_add_u64 v[152:153], v[152:153], 0, s[14:15]
	s_mov_b32 m0, s34
	ds_read_b128 v[188:191], v159 offset:49152
	ds_read_b128 v[192:195], v159 offset:50176
	ds_read_b128 v[196:199], v159 offset:51200
	ds_read_b128 v[200:203], v159 offset:52224
	ds_read_b128 v[204:207], v159 offset:53248
	ds_read_b128 v[208:211], v159 offset:54272
	ds_read_b128 v[212:215], v159 offset:55296
	ds_read_b128 v[216:219], v159 offset:56320
	global_load_lds_dwordx4 v[152:153], off
	v_lshl_add_u64 v[152:153], v[160:161], 0, s[14:15]
	s_add_i32 m0, s34, 0x2000
	s_add_i32 s34, s66, s40
	global_load_lds_dwordx4 v[152:153], off
	v_lshl_add_u64 v[152:153], v[222:223], 0, s[14:15]
	s_mov_b32 m0, s34
	s_nop 0
	global_load_lds_dwordx4 v[152:153], off
	v_lshl_add_u64 v[152:153], v[224:225], 0, s[14:15]
	s_add_i32 m0, s34, 0x2000
	s_nop 0
	global_load_lds_dwordx4 v[152:153], off
	v_lshl_add_u64 v[152:153], v[226:227], 0, s[14:15]
	s_mov_b32 m0, s46
	s_nop 0
	global_load_lds_dwordx4 v[152:153], off
	v_lshl_add_u64 v[152:153], v[228:229], 0, s[14:15]
	s_mov_b32 m0, s47
	s_nop 0
	global_load_lds_dwordx4 v[152:153], off
	s_waitcnt vmcnt(8)
	s_waitcnt lgkmcnt(0)
	s_barrier
	s_waitcnt lgkmcnt(0)
	v_mfma_f32_16x16x32_bf16 v[60:63], v[144:147], v[188:191], v[60:63]
	v_mfma_f32_16x16x32_bf16 v[60:63], v[148:151], v[192:195], v[60:63]
	v_mfma_f32_16x16x32_bf16 v[56:59], v[168:171], v[192:195], v[56:59]
	v_mfma_f32_16x16x32_bf16 v[56:59], v[164:167], v[188:191], v[56:59]
	v_mfma_f32_16x16x32_bf16 v[52:55], v[172:175], v[188:191], v[52:55]
	v_mfma_f32_16x16x32_bf16 v[52:55], v[176:179], v[192:195], v[52:55]
	v_mfma_f32_16x16x32_bf16 v[48:51], v[184:187], v[192:195], v[48:51]
	v_mfma_f32_16x16x32_bf16 v[48:51], v[180:183], v[188:191], v[48:51]
	v_mfma_f32_16x16x32_bf16 v[32:35], v[180:183], v[196:199], v[32:35]
	v_mfma_f32_16x16x32_bf16 v[32:35], v[184:187], v[200:203], v[32:35]
	v_mfma_f32_16x16x32_bf16 v[36:39], v[176:179], v[200:203], v[36:39]
	v_mfma_f32_16x16x32_bf16 v[36:39], v[172:175], v[196:199], v[36:39]
	v_mfma_f32_16x16x32_bf16 v[40:43], v[164:167], v[196:199], v[40:43]
	v_mfma_f32_16x16x32_bf16 v[40:43], v[168:171], v[200:203], v[40:43]
	v_mfma_f32_16x16x32_bf16 v[44:47], v[148:151], v[200:203], v[44:47]
	v_mfma_f32_16x16x32_bf16 v[44:47], v[144:147], v[196:199], v[44:47]
	v_mfma_f32_16x16x32_bf16 v[28:31], v[144:147], v[204:207], v[28:31]
	v_mfma_f32_16x16x32_bf16 v[28:31], v[148:151], v[208:211], v[28:31]
	v_mfma_f32_16x16x32_bf16 v[24:27], v[168:171], v[208:211], v[24:27]
	v_mfma_f32_16x16x32_bf16 v[24:27], v[164:167], v[204:207], v[24:27]
	v_mfma_f32_16x16x32_bf16 v[20:23], v[172:175], v[204:207], v[20:23]
	v_mfma_f32_16x16x32_bf16 v[20:23], v[176:179], v[208:211], v[20:23]
	v_mfma_f32_16x16x32_bf16 v[16:19], v[184:187], v[208:211], v[16:19]
	v_mfma_f32_16x16x32_bf16 v[16:19], v[180:183], v[204:207], v[16:19]
	v_mfma_f32_16x16x32_bf16 v[0:3], v[180:183], v[212:215], v[0:3]
	v_mfma_f32_16x16x32_bf16 v[0:3], v[184:187], v[216:219], v[0:3]
	v_mfma_f32_16x16x32_bf16 v[4:7], v[176:179], v[216:219], v[4:7]
	v_mfma_f32_16x16x32_bf16 v[4:7], v[172:175], v[212:215], v[4:7]
	v_mfma_f32_16x16x32_bf16 v[8:11], v[164:167], v[212:215], v[8:11]
	v_mfma_f32_16x16x32_bf16 v[8:11], v[168:171], v[216:219], v[8:11]
	v_mfma_f32_16x16x32_bf16 v[12:15], v[148:151], v[216:219], v[12:15]
	v_mfma_f32_16x16x32_bf16 v[12:15], v[144:147], v[212:215], v[12:15]
	s_barrier
	s_add_u32 s30, s30, 0x100
	s_addc_u32 s31, s31, 0
	s_add_u32 s62, s62, 0x100
	s_addc_u32 s63, s63, 0
	s_cmp_ge_i32 s64, s48
	s_mov_b32 s34, s64
	s_cbranch_scc0 .LBB0_592

.LBB0_763:
	ds_read_b128 v[128:131], v181
	ds_read_b128 v[132:135], v181 offset:1024
	ds_read_b128 v[136:139], v181 offset:2048
	ds_read_b128 v[140:143], v181 offset:3072
	ds_read_b128 v[144:147], v182
	ds_read_b128 v[148:151], v182 offset:1024
	ds_read_b128 v[168:171], v182 offset:2048
	ds_read_b128 v[172:175], v182 offset:3072
	s_add_i32 s54, s26, 2
	s_add_u32 s55, s24, 0x80
	s_addc_u32 s27, s25, 0
	s_cmp_eq_u32 s43, s26
	s_cselect_b32 s26, s2, s55
	s_cselect_b32 s27, s3, s27
	s_cselect_b32 s61, s23, s53
	s_cselect_b32 s60, s22, s52
	v_lshl_add_u64 v[176:177], s[24:25], 0, v[160:161]
	s_add_i32 m0, s35, 0xc000
	ds_read_b128 v[184:187], v183
	ds_read_b128 v[188:191], v183 offset:1024
	ds_read_b128 v[192:195], v183 offset:2048
	ds_read_b128 v[196:199], v183 offset:3072
	ds_read_b128 v[200:203], v183 offset:4096
	ds_read_b128 v[204:207], v183 offset:5120
	ds_read_b128 v[208:211], v183 offset:6144
	ds_read_b128 v[212:215], v183 offset:7168
	global_load_lds_dwordx4 v[176:177], off
	v_lshl_add_u64 v[176:177], s[24:25], 0, v[162:163]
	s_add_i32 m0, s35, 0xe000
	s_nop 0
	global_load_lds_dwordx4 v[176:177], off
	s_waitcnt vmcnt(8)
	s_waitcnt lgkmcnt(0)
	s_barrier
	s_waitcnt lgkmcnt(0)
	v_mfma_f32_16x16x32_bf16 v[120:123], v[128:131], v[184:187], v[120:123]
	v_mfma_f32_16x16x32_bf16 v[120:123], v[132:135], v[188:191], v[120:123]
	v_mfma_f32_16x16x32_bf16 v[124:127], v[140:143], v[188:191], v[124:127]
	v_mfma_f32_16x16x32_bf16 v[124:127], v[136:139], v[184:187], v[124:127]
	v_mfma_f32_16x16x32_bf16 v[116:119], v[144:147], v[184:187], v[116:119]
	v_mfma_f32_16x16x32_bf16 v[116:119], v[148:151], v[188:191], v[116:119]
	v_mfma_f32_16x16x32_bf16 v[112:115], v[172:175], v[188:191], v[112:115]
	v_mfma_f32_16x16x32_bf16 v[112:115], v[168:171], v[184:187], v[112:115]
	v_mfma_f32_16x16x32_bf16 v[96:99], v[168:171], v[192:195], v[96:99]
	v_mfma_f32_16x16x32_bf16 v[96:99], v[172:175], v[196:199], v[96:99]
	v_mfma_f32_16x16x32_bf16 v[100:103], v[148:151], v[196:199], v[100:103]
	v_mfma_f32_16x16x32_bf16 v[100:103], v[144:147], v[192:195], v[100:103]
	v_mfma_f32_16x16x32_bf16 v[104:107], v[136:139], v[192:195], v[104:107]
	v_mfma_f32_16x16x32_bf16 v[104:107], v[140:143], v[196:199], v[104:107]
	v_mfma_f32_16x16x32_bf16 v[108:111], v[132:135], v[196:199], v[108:111]
	v_mfma_f32_16x16x32_bf16 v[108:111], v[128:131], v[192:195], v[108:111]
	v_mfma_f32_16x16x32_bf16 v[92:95], v[128:131], v[200:203], v[92:95]
	v_mfma_f32_16x16x32_bf16 v[92:95], v[132:135], v[204:207], v[92:95]
	v_mfma_f32_16x16x32_bf16 v[88:91], v[140:143], v[204:207], v[88:91]
	v_mfma_f32_16x16x32_bf16 v[88:91], v[136:139], v[200:203], v[88:91]
	v_mfma_f32_16x16x32_bf16 v[84:87], v[144:147], v[200:203], v[84:87]
	v_mfma_f32_16x16x32_bf16 v[84:87], v[148:151], v[204:207], v[84:87]
	v_mfma_f32_16x16x32_bf16 v[80:83], v[172:175], v[204:207], v[80:83]
	v_mfma_f32_16x16x32_bf16 v[80:83], v[168:171], v[200:203], v[80:83]
	v_mfma_f32_16x16x32_bf16 v[64:67], v[168:171], v[208:211], v[64:67]
	v_mfma_f32_16x16x32_bf16 v[64:67], v[172:175], v[212:215], v[64:67]
	v_mfma_f32_16x16x32_bf16 v[68:71], v[148:151], v[212:215], v[68:71]
	v_mfma_f32_16x16x32_bf16 v[68:71], v[144:147], v[208:211], v[68:71]
	v_mfma_f32_16x16x32_bf16 v[72:75], v[136:139], v[208:211], v[72:75]
	v_mfma_f32_16x16x32_bf16 v[72:75], v[140:143], v[212:215], v[72:75]
	v_mfma_f32_16x16x32_bf16 v[76:79], v[132:135], v[212:215], v[76:79]
	v_mfma_f32_16x16x32_bf16 v[76:79], v[128:131], v[208:211], v[76:79]
	s_barrier
	s_add_i32 s55, s46, s34
	v_lshl_add_u64 v[176:177], s[60:61], 0, v[154:155]
	s_mov_b32 m0, s55
	ds_read_b128 v[184:187], v183 offset:16384
	ds_read_b128 v[188:191], v183 offset:17408
	ds_read_b128 v[192:195], v183 offset:18432
	ds_read_b128 v[196:199], v183 offset:19456
	ds_read_b128 v[200:203], v183 offset:20480
	ds_read_b128 v[204:207], v183 offset:21504
	ds_read_b128 v[208:211], v183 offset:22528
	ds_read_b128 v[212:215], v183 offset:23552
	global_load_lds_dwordx4 v[176:177], off
	s_add_i32 m0, s55, 0x2000
	v_lshl_add_u64 v[216:217], s[60:61], 0, v[158:159]
	s_add_u32 s60, s60, s8
	s_addc_u32 s61, s61, s9
	s_add_i32 s55, s47, s34
	global_load_lds_dwordx4 v[216:217], off
	v_lshl_add_u64 v[218:219], s[60:61], 0, v[154:155]
	s_mov_b32 m0, s55
	v_lshl_add_u64 v[222:223], s[60:61], 0, v[158:159]
	global_load_lds_dwordx4 v[218:219], off
	s_add_i32 m0, s55, 0x2000
	v_lshl_add_u64 v[224:225], s[26:27], 0, v[152:153]
	global_load_lds_dwordx4 v[222:223], off
	s_mov_b32 m0, s35
	v_lshl_add_u64 v[226:227], s[26:27], 0, v[156:157]
	global_load_lds_dwordx4 v[224:225], off
	s_mov_b32 m0, s36
	s_nop 0
	global_load_lds_dwordx4 v[226:227], off
	s_waitcnt vmcnt(8)
	s_waitcnt lgkmcnt(0)
	s_barrier
	s_waitcnt lgkmcnt(0)
	v_mfma_f32_16x16x32_bf16 v[60:63], v[128:131], v[184:187], v[60:63]
	v_mfma_f32_16x16x32_bf16 v[60:63], v[132:135], v[188:191], v[60:63]
	v_mfma_f32_16x16x32_bf16 v[56:59], v[140:143], v[188:191], v[56:59]
	v_mfma_f32_16x16x32_bf16 v[56:59], v[136:139], v[184:187], v[56:59]
	v_mfma_f32_16x16x32_bf16 v[52:55], v[144:147], v[184:187], v[52:55]
	v_mfma_f32_16x16x32_bf16 v[52:55], v[148:151], v[188:191], v[52:55]
	v_mfma_f32_16x16x32_bf16 v[48:51], v[172:175], v[188:191], v[48:51]
	v_mfma_f32_16x16x32_bf16 v[48:51], v[168:171], v[184:187], v[48:51]
	v_mfma_f32_16x16x32_bf16 v[32:35], v[168:171], v[192:195], v[32:35]
	v_mfma_f32_16x16x32_bf16 v[32:35], v[172:175], v[196:199], v[32:35]
	v_mfma_f32_16x16x32_bf16 v[36:39], v[148:151], v[196:199], v[36:39]
	v_mfma_f32_16x16x32_bf16 v[36:39], v[144:147], v[192:195], v[36:39]
	v_mfma_f32_16x16x32_bf16 v[40:43], v[136:139], v[192:195], v[40:43]
	v_mfma_f32_16x16x32_bf16 v[40:43], v[140:143], v[196:199], v[40:43]
	v_mfma_f32_16x16x32_bf16 v[44:47], v[132:135], v[196:199], v[44:47]
	v_mfma_f32_16x16x32_bf16 v[44:47], v[128:131], v[192:195], v[44:47]
	v_mfma_f32_16x16x32_bf16 v[28:31], v[128:131], v[200:203], v[28:31]
	v_mfma_f32_16x16x32_bf16 v[28:31], v[132:135], v[204:207], v[28:31]
	v_mfma_f32_16x16x32_bf16 v[24:27], v[140:143], v[204:207], v[24:27]
	v_mfma_f32_16x16x32_bf16 v[24:27], v[136:139], v[200:203], v[24:27]
	v_mfma_f32_16x16x32_bf16 v[20:23], v[144:147], v[200:203], v[20:23]
	v_mfma_f32_16x16x32_bf16 v[20:23], v[148:151], v[204:207], v[20:23]
	v_mfma_f32_16x16x32_bf16 v[16:19], v[172:175], v[204:207], v[16:19]
	v_mfma_f32_16x16x32_bf16 v[16:19], v[168:171], v[200:203], v[16:19]
	v_mfma_f32_16x16x32_bf16 v[0:3], v[168:171], v[208:211], v[0:3]
	v_mfma_f32_16x16x32_bf16 v[0:3], v[172:175], v[212:215], v[0:3]
	v_mfma_f32_16x16x32_bf16 v[4:7], v[148:151], v[212:215], v[4:7]
	v_mfma_f32_16x16x32_bf16 v[4:7], v[144:147], v[208:211], v[4:7]
	v_mfma_f32_16x16x32_bf16 v[8:11], v[136:139], v[208:211], v[8:11]
	v_mfma_f32_16x16x32_bf16 v[8:11], v[140:143], v[212:215], v[8:11]
	v_mfma_f32_16x16x32_bf16 v[12:15], v[132:135], v[212:215], v[12:15]
	v_mfma_f32_16x16x32_bf16 v[12:15], v[128:131], v[208:211], v[12:15]
	s_barrier
	s_add_i32 s55, 0, 0x18000
	s_add_i32 s60, 0, 0x1c000
	v_add_u32_e32 v140, s55, v179
	v_add_u32_e32 v172, s60, v179
	ds_read_b128 v[128:131], v140
	ds_read_b128 v[132:135], v140 offset:1024
	ds_read_b128 v[136:139], v140 offset:2048
	ds_read_b128 v[140:143], v140 offset:3072
	ds_read_b128 v[144:147], v172
	ds_read_b128 v[148:151], v172 offset:1024
	ds_read_b128 v[168:171], v172 offset:2048
	ds_read_b128 v[172:175], v172 offset:3072
	s_add_u32 s26, s26, s8
	s_addc_u32 s27, s27, s9
	s_mov_b32 m0, s37
	v_lshl_add_u64 v[228:229], s[26:27], 0, v[152:153]
	ds_read_b128 v[184:187], v183 offset:32768
	ds_read_b128 v[188:191], v183 offset:33792
	ds_read_b128 v[192:195], v183 offset:34816
	ds_read_b128 v[196:199], v183 offset:35840
	ds_read_b128 v[200:203], v183 offset:36864
	ds_read_b128 v[204:207], v183 offset:37888
	ds_read_b128 v[208:211], v183 offset:38912
	ds_read_b128 v[212:215], v183 offset:39936
	global_load_lds_dwordx4 v[228:229], off
	v_lshl_add_u64 v[228:229], s[26:27], 0, v[156:157]
	s_mov_b32 m0, s38
	s_nop 0
	global_load_lds_dwordx4 v[228:229], off
	s_waitcnt vmcnt(8)
	s_waitcnt lgkmcnt(0)
	s_barrier
	s_waitcnt lgkmcnt(0)
	v_mfma_f32_16x16x32_bf16 v[120:123], v[128:131], v[184:187], v[120:123]
	v_mfma_f32_16x16x32_bf16 v[120:123], v[132:135], v[188:191], v[120:123]
	v_mfma_f32_16x16x32_bf16 v[124:127], v[140:143], v[188:191], v[124:127]
	v_mfma_f32_16x16x32_bf16 v[124:127], v[136:139], v[184:187], v[124:127]
	v_mfma_f32_16x16x32_bf16 v[116:119], v[144:147], v[184:187], v[116:119]
	v_mfma_f32_16x16x32_bf16 v[116:119], v[148:151], v[188:191], v[116:119]
	v_mfma_f32_16x16x32_bf16 v[112:115], v[172:175], v[188:191], v[112:115]
	v_mfma_f32_16x16x32_bf16 v[112:115], v[168:171], v[184:187], v[112:115]
	v_mfma_f32_16x16x32_bf16 v[96:99], v[168:171], v[192:195], v[96:99]
	v_mfma_f32_16x16x32_bf16 v[96:99], v[172:175], v[196:199], v[96:99]
	v_mfma_f32_16x16x32_bf16 v[100:103], v[148:151], v[196:199], v[100:103]
	v_mfma_f32_16x16x32_bf16 v[100:103], v[144:147], v[192:195], v[100:103]
	v_mfma_f32_16x16x32_bf16 v[104:107], v[136:139], v[192:195], v[104:107]
	v_mfma_f32_16x16x32_bf16 v[104:107], v[140:143], v[196:199], v[104:107]
	v_mfma_f32_16x16x32_bf16 v[108:111], v[132:135], v[196:199], v[108:111]
	v_mfma_f32_16x16x32_bf16 v[108:111], v[128:131], v[192:195], v[108:111]
	v_mfma_f32_16x16x32_bf16 v[92:95], v[128:131], v[200:203], v[92:95]
	v_mfma_f32_16x16x32_bf16 v[92:95], v[132:135], v[204:207], v[92:95]
	v_mfma_f32_16x16x32_bf16 v[88:91], v[140:143], v[204:207], v[88:91]
	v_mfma_f32_16x16x32_bf16 v[88:91], v[136:139], v[200:203], v[88:91]
	v_mfma_f32_16x16x32_bf16 v[84:87], v[144:147], v[200:203], v[84:87]
	v_mfma_f32_16x16x32_bf16 v[84:87], v[148:151], v[204:207], v[84:87]
	v_mfma_f32_16x16x32_bf16 v[80:83], v[172:175], v[204:207], v[80:83]
	v_mfma_f32_16x16x32_bf16 v[80:83], v[168:171], v[200:203], v[80:83]
	v_mfma_f32_16x16x32_bf16 v[64:67], v[168:171], v[208:211], v[64:67]
	v_mfma_f32_16x16x32_bf16 v[64:67], v[172:175], v[212:215], v[64:67]
	v_mfma_f32_16x16x32_bf16 v[68:71], v[148:151], v[212:215], v[68:71]
	v_mfma_f32_16x16x32_bf16 v[68:71], v[144:147], v[208:211], v[68:71]
	v_mfma_f32_16x16x32_bf16 v[72:75], v[136:139], v[208:211], v[72:75]
	v_mfma_f32_16x16x32_bf16 v[72:75], v[140:143], v[212:215], v[72:75]
	v_mfma_f32_16x16x32_bf16 v[76:79], v[132:135], v[212:215], v[76:79]
	v_mfma_f32_16x16x32_bf16 v[76:79], v[128:131], v[208:211], v[76:79]
	s_barrier
	s_add_i32 s26, s55, s34
	v_lshl_add_u64 v[176:177], v[176:177], 0, s[16:17]
	s_mov_b32 m0, s26
	ds_read_b128 v[184:187], v183 offset:49152
	ds_read_b128 v[188:191], v183 offset:50176
	ds_read_b128 v[192:195], v183 offset:51200
	ds_read_b128 v[196:199], v183 offset:52224
	ds_read_b128 v[200:203], v183 offset:53248
	ds_read_b128 v[204:207], v183 offset:54272
	ds_read_b128 v[208:211], v183 offset:55296
	ds_read_b128 v[212:215], v183 offset:56320
	global_load_lds_dwordx4 v[176:177], off
	v_lshl_add_u64 v[176:177], v[216:217], 0, s[16:17]
	s_add_i32 m0, s26, 0x2000
	s_add_i32 s26, s60, s34
	global_load_lds_dwordx4 v[176:177], off
	v_lshl_add_u64 v[176:177], v[218:219], 0, s[16:17]
	s_mov_b32 m0, s26
	s_nop 0
	global_load_lds_dwordx4 v[176:177], off
	v_lshl_add_u64 v[176:177], v[222:223], 0, s[16:17]
	s_add_i32 m0, s26, 0x2000
	s_nop 0
	global_load_lds_dwordx4 v[176:177], off
	v_lshl_add_u64 v[176:177], v[224:225], 0, s[16:17]
	s_mov_b32 m0, s40
	s_nop 0
	global_load_lds_dwordx4 v[176:177], off
	v_lshl_add_u64 v[176:177], v[226:227], 0, s[16:17]
	s_mov_b32 m0, s41
	s_nop 0
	global_load_lds_dwordx4 v[176:177], off
	s_waitcnt vmcnt(8)
	s_waitcnt lgkmcnt(0)
	s_barrier
	s_waitcnt lgkmcnt(0)
	v_mfma_f32_16x16x32_bf16 v[60:63], v[128:131], v[184:187], v[60:63]
	v_mfma_f32_16x16x32_bf16 v[60:63], v[132:135], v[188:191], v[60:63]
	v_mfma_f32_16x16x32_bf16 v[56:59], v[140:143], v[188:191], v[56:59]
	v_mfma_f32_16x16x32_bf16 v[56:59], v[136:139], v[184:187], v[56:59]
	v_mfma_f32_16x16x32_bf16 v[52:55], v[144:147], v[184:187], v[52:55]
	v_mfma_f32_16x16x32_bf16 v[52:55], v[148:151], v[188:191], v[52:55]
	v_mfma_f32_16x16x32_bf16 v[48:51], v[172:175], v[188:191], v[48:51]
	v_mfma_f32_16x16x32_bf16 v[48:51], v[168:171], v[184:187], v[48:51]
	v_mfma_f32_16x16x32_bf16 v[32:35], v[168:171], v[192:195], v[32:35]
	v_mfma_f32_16x16x32_bf16 v[32:35], v[172:175], v[196:199], v[32:35]
	v_mfma_f32_16x16x32_bf16 v[36:39], v[148:151], v[196:199], v[36:39]
	v_mfma_f32_16x16x32_bf16 v[36:39], v[144:147], v[192:195], v[36:39]
	v_mfma_f32_16x16x32_bf16 v[40:43], v[136:139], v[192:195], v[40:43]
	v_mfma_f32_16x16x32_bf16 v[40:43], v[140:143], v[196:199], v[40:43]
	v_mfma_f32_16x16x32_bf16 v[44:47], v[132:135], v[196:199], v[44:47]
	v_mfma_f32_16x16x32_bf16 v[44:47], v[128:131], v[192:195], v[44:47]
	v_mfma_f32_16x16x32_bf16 v[28:31], v[128:131], v[200:203], v[28:31]
	v_mfma_f32_16x16x32_bf16 v[28:31], v[132:135], v[204:207], v[28:31]
	v_mfma_f32_16x16x32_bf16 v[24:27], v[140:143], v[204:207], v[24:27]
	v_mfma_f32_16x16x32_bf16 v[24:27], v[136:139], v[200:203], v[24:27]
	v_mfma_f32_16x16x32_bf16 v[20:23], v[144:147], v[200:203], v[20:23]
	v_mfma_f32_16x16x32_bf16 v[20:23], v[148:151], v[204:207], v[20:23]
	v_mfma_f32_16x16x32_bf16 v[16:19], v[172:175], v[204:207], v[16:19]
	v_mfma_f32_16x16x32_bf16 v[16:19], v[168:171], v[200:203], v[16:19]
	v_mfma_f32_16x16x32_bf16 v[0:3], v[168:171], v[208:211], v[0:3]
	v_mfma_f32_16x16x32_bf16 v[0:3], v[172:175], v[212:215], v[0:3]
	v_mfma_f32_16x16x32_bf16 v[4:7], v[148:151], v[212:215], v[4:7]
	v_mfma_f32_16x16x32_bf16 v[4:7], v[144:147], v[208:211], v[4:7]
	v_mfma_f32_16x16x32_bf16 v[8:11], v[136:139], v[208:211], v[8:11]
	v_mfma_f32_16x16x32_bf16 v[8:11], v[140:143], v[212:215], v[8:11]
	v_mfma_f32_16x16x32_bf16 v[12:15], v[132:135], v[212:215], v[12:15]
	v_mfma_f32_16x16x32_bf16 v[12:15], v[128:131], v[208:211], v[12:15]
	s_barrier
	s_add_u32 s24, s24, 0x100
	s_addc_u32 s25, s25, 0
	s_add_u32 s52, s52, 0x100
	s_addc_u32 s53, s53, 0
	s_cmp_ge_i32 s54, s42
	s_mov_b32 s26, s54
	s_cbranch_scc0 .LBB0_763

.LBB0_849:
	ds_read_b128 v[112:115], v209
	ds_read_b128 v[116:119], v209 offset:1024
	ds_read_b128 v[120:123], v209 offset:2048
	ds_read_b128 v[128:131], v209 offset:3072
	ds_read_b128 v[144:147], v210
	ds_read_b128 v[148:151], v210 offset:1024
	ds_read_b128 v[152:155], v210 offset:2048
	ds_read_b128 v[156:159], v210 offset:3072
	s_add_i32 s62, s30, 2
	s_add_u32 s63, s28, 0x80
	s_addc_u32 s31, s29, 0
	s_cmp_eq_u32 s46, s30
	s_cselect_b32 s30, s4, s63
	s_cselect_b32 s31, s5, s31
	s_cselect_b32 s65, s27, s61
	s_cselect_b32 s64, s26, s60
	v_lshl_add_u64 v[204:205], s[28:29], 0, v[180:181]
	s_add_i32 m0, s38, 0xc000
	ds_read_b128 v[160:163], v211
	ds_read_b128 v[164:167], v211 offset:1024
	ds_read_b128 v[168:171], v211 offset:2048
	ds_read_b128 v[172:175], v211 offset:3072
	ds_read_b128 v[188:191], v211 offset:4096
	ds_read_b128 v[192:195], v211 offset:5120
	ds_read_b128 v[196:199], v211 offset:6144
	ds_read_b128 v[200:203], v211 offset:7168
	global_load_lds_dwordx4 v[204:205], off
	v_lshl_add_u64 v[204:205], s[28:29], 0, v[182:183]
	s_add_i32 m0, s38, 0xe000
	s_nop 0
	global_load_lds_dwordx4 v[204:205], off
	s_waitcnt vmcnt(8)
	s_waitcnt lgkmcnt(0)
	s_barrier
	s_waitcnt lgkmcnt(0)
	v_mfma_f32_16x16x32_bf16 v[136:139], v[112:115], v[160:163], v[136:139]
	v_mfma_f32_16x16x32_bf16 v[136:139], v[116:119], v[164:167], v[136:139]
	v_mfma_f32_16x16x32_bf16 v[140:143], v[128:131], v[164:167], v[140:143]
	v_mfma_f32_16x16x32_bf16 v[140:143], v[120:123], v[160:163], v[140:143]
	v_mfma_f32_16x16x32_bf16 v[132:135], v[144:147], v[160:163], v[132:135]
	v_mfma_f32_16x16x32_bf16 v[132:135], v[148:151], v[164:167], v[132:135]
	v_mfma_f32_16x16x32_bf16 v[124:127], v[156:159], v[164:167], v[124:127]
	v_mfma_f32_16x16x32_bf16 v[124:127], v[152:155], v[160:163], v[124:127]
	v_mfma_f32_16x16x32_bf16 v[96:99], v[152:155], v[168:171], v[96:99]
	v_mfma_f32_16x16x32_bf16 v[96:99], v[156:159], v[172:175], v[96:99]
	v_mfma_f32_16x16x32_bf16 v[100:103], v[148:151], v[172:175], v[100:103]
	v_mfma_f32_16x16x32_bf16 v[100:103], v[144:147], v[168:171], v[100:103]
	v_mfma_f32_16x16x32_bf16 v[104:107], v[120:123], v[168:171], v[104:107]
	v_mfma_f32_16x16x32_bf16 v[104:107], v[128:131], v[172:175], v[104:107]
	v_mfma_f32_16x16x32_bf16 v[108:111], v[116:119], v[172:175], v[108:111]
	v_mfma_f32_16x16x32_bf16 v[108:111], v[112:115], v[168:171], v[108:111]
	v_mfma_f32_16x16x32_bf16 v[92:95], v[112:115], v[188:191], v[92:95]
	v_mfma_f32_16x16x32_bf16 v[92:95], v[116:119], v[192:195], v[92:95]
	v_mfma_f32_16x16x32_bf16 v[88:91], v[128:131], v[192:195], v[88:91]
	v_mfma_f32_16x16x32_bf16 v[88:91], v[120:123], v[188:191], v[88:91]
	v_mfma_f32_16x16x32_bf16 v[84:87], v[144:147], v[188:191], v[84:87]
	v_mfma_f32_16x16x32_bf16 v[84:87], v[148:151], v[192:195], v[84:87]
	v_mfma_f32_16x16x32_bf16 v[80:83], v[156:159], v[192:195], v[80:83]
	v_mfma_f32_16x16x32_bf16 v[80:83], v[152:155], v[188:191], v[80:83]
	v_mfma_f32_16x16x32_bf16 v[64:67], v[152:155], v[196:199], v[64:67]
	v_mfma_f32_16x16x32_bf16 v[64:67], v[156:159], v[200:203], v[64:67]
	v_mfma_f32_16x16x32_bf16 v[68:71], v[148:151], v[200:203], v[68:71]
	v_mfma_f32_16x16x32_bf16 v[68:71], v[144:147], v[196:199], v[68:71]
	v_mfma_f32_16x16x32_bf16 v[72:75], v[120:123], v[196:199], v[72:75]
	v_mfma_f32_16x16x32_bf16 v[72:75], v[128:131], v[200:203], v[72:75]
	v_mfma_f32_16x16x32_bf16 v[76:79], v[116:119], v[200:203], v[76:79]
	v_mfma_f32_16x16x32_bf16 v[76:79], v[112:115], v[196:199], v[76:79]
	s_barrier
	s_add_i32 s63, s50, s37
	v_lshl_add_u64 v[204:205], s[64:65], 0, v[176:177]
	s_mov_b32 m0, s63
	ds_read_b128 v[160:163], v211 offset:16384
	ds_read_b128 v[164:167], v211 offset:17408
	ds_read_b128 v[168:171], v211 offset:18432
	ds_read_b128 v[172:175], v211 offset:19456
	ds_read_b128 v[188:191], v211 offset:20480
	ds_read_b128 v[192:195], v211 offset:21504
	ds_read_b128 v[196:199], v211 offset:22528
	ds_read_b128 v[200:203], v211 offset:23552
	global_load_lds_dwordx4 v[204:205], off
	s_add_i32 m0, s63, 0x2000
	v_lshl_add_u64 v[214:215], s[64:65], 0, v[178:179]
	s_add_u32 s64, s64, s10
	s_addc_u32 s65, s65, s11
	s_add_i32 s63, s51, s37
	global_load_lds_dwordx4 v[214:215], off
	v_lshl_add_u64 v[216:217], s[64:65], 0, v[176:177]
	s_mov_b32 m0, s63
	v_lshl_add_u64 v[218:219], s[64:65], 0, v[178:179]
	global_load_lds_dwordx4 v[216:217], off
	s_add_i32 m0, s63, 0x2000
	v_lshl_add_u64 v[222:223], s[30:31], 0, v[176:177]
	global_load_lds_dwordx4 v[218:219], off
	s_mov_b32 m0, s38
	v_lshl_add_u64 v[224:225], s[30:31], 0, v[178:179]
	global_load_lds_dwordx4 v[222:223], off
	s_mov_b32 m0, s39
	s_nop 0
	global_load_lds_dwordx4 v[224:225], off
	s_waitcnt vmcnt(8)
	s_waitcnt lgkmcnt(0)
	s_barrier
	s_waitcnt lgkmcnt(0)
	v_mfma_f32_16x16x32_bf16 v[60:63], v[112:115], v[160:163], v[60:63]
	v_mfma_f32_16x16x32_bf16 v[60:63], v[116:119], v[164:167], v[60:63]
	v_mfma_f32_16x16x32_bf16 v[56:59], v[128:131], v[164:167], v[56:59]
	v_mfma_f32_16x16x32_bf16 v[56:59], v[120:123], v[160:163], v[56:59]
	v_mfma_f32_16x16x32_bf16 v[52:55], v[144:147], v[160:163], v[52:55]
	v_mfma_f32_16x16x32_bf16 v[52:55], v[148:151], v[164:167], v[52:55]
	v_mfma_f32_16x16x32_bf16 v[48:51], v[156:159], v[164:167], v[48:51]
	v_mfma_f32_16x16x32_bf16 v[48:51], v[152:155], v[160:163], v[48:51]
	v_mfma_f32_16x16x32_bf16 v[32:35], v[152:155], v[168:171], v[32:35]
	v_mfma_f32_16x16x32_bf16 v[32:35], v[156:159], v[172:175], v[32:35]
	v_mfma_f32_16x16x32_bf16 v[36:39], v[148:151], v[172:175], v[36:39]
	v_mfma_f32_16x16x32_bf16 v[36:39], v[144:147], v[168:171], v[36:39]
	v_mfma_f32_16x16x32_bf16 v[40:43], v[120:123], v[168:171], v[40:43]
	v_mfma_f32_16x16x32_bf16 v[40:43], v[128:131], v[172:175], v[40:43]
	v_mfma_f32_16x16x32_bf16 v[44:47], v[116:119], v[172:175], v[44:47]
	v_mfma_f32_16x16x32_bf16 v[44:47], v[112:115], v[168:171], v[44:47]
	v_mfma_f32_16x16x32_bf16 v[28:31], v[112:115], v[188:191], v[28:31]
	v_mfma_f32_16x16x32_bf16 v[28:31], v[116:119], v[192:195], v[28:31]
	v_mfma_f32_16x16x32_bf16 v[24:27], v[128:131], v[192:195], v[24:27]
	v_mfma_f32_16x16x32_bf16 v[24:27], v[120:123], v[188:191], v[24:27]
	v_mfma_f32_16x16x32_bf16 v[20:23], v[144:147], v[188:191], v[20:23]
	v_mfma_f32_16x16x32_bf16 v[20:23], v[148:151], v[192:195], v[20:23]
	v_mfma_f32_16x16x32_bf16 v[16:19], v[156:159], v[192:195], v[16:19]
	v_mfma_f32_16x16x32_bf16 v[16:19], v[152:155], v[188:191], v[16:19]
	v_mfma_f32_16x16x32_bf16 v[0:3], v[152:155], v[196:199], v[0:3]
	v_mfma_f32_16x16x32_bf16 v[0:3], v[156:159], v[200:203], v[0:3]
	v_mfma_f32_16x16x32_bf16 v[4:7], v[148:151], v[200:203], v[4:7]
	v_mfma_f32_16x16x32_bf16 v[4:7], v[144:147], v[196:199], v[4:7]
	v_mfma_f32_16x16x32_bf16 v[8:11], v[120:123], v[196:199], v[8:11]
	v_mfma_f32_16x16x32_bf16 v[8:11], v[128:131], v[200:203], v[8:11]
	v_mfma_f32_16x16x32_bf16 v[12:15], v[116:119], v[200:203], v[12:15]
	v_mfma_f32_16x16x32_bf16 v[12:15], v[112:115], v[196:199], v[12:15]
	s_barrier
	s_add_i32 s63, 0, 0x18000
	s_add_i32 s64, 0, 0x1c000
	v_add_u32_e32 v128, s63, v207
	v_add_u32_e32 v156, s64, v207
	ds_read_b128 v[112:115], v128
	ds_read_b128 v[116:119], v128 offset:1024
	ds_read_b128 v[120:123], v128 offset:2048
	ds_read_b128 v[128:131], v128 offset:3072
	ds_read_b128 v[144:147], v156
	ds_read_b128 v[148:151], v156 offset:1024
	ds_read_b128 v[152:155], v156 offset:2048
	ds_read_b128 v[156:159], v156 offset:3072
	s_add_u32 s30, s30, s10
	s_addc_u32 s31, s31, s11
	s_mov_b32 m0, s40
	v_lshl_add_u64 v[226:227], s[30:31], 0, v[176:177]
	ds_read_b128 v[160:163], v211 offset:32768
	ds_read_b128 v[164:167], v211 offset:33792
	ds_read_b128 v[168:171], v211 offset:34816
	ds_read_b128 v[172:175], v211 offset:35840
	ds_read_b128 v[188:191], v211 offset:36864
	ds_read_b128 v[192:195], v211 offset:37888
	ds_read_b128 v[196:199], v211 offset:38912
	ds_read_b128 v[200:203], v211 offset:39936
	global_load_lds_dwordx4 v[226:227], off
	v_lshl_add_u64 v[226:227], s[30:31], 0, v[178:179]
	s_mov_b32 m0, s41
	s_nop 0
	global_load_lds_dwordx4 v[226:227], off
	s_waitcnt vmcnt(8)
	s_waitcnt lgkmcnt(0)
	s_barrier
	s_waitcnt lgkmcnt(0)
	v_mfma_f32_16x16x32_bf16 v[136:139], v[112:115], v[160:163], v[136:139]
	v_mfma_f32_16x16x32_bf16 v[136:139], v[116:119], v[164:167], v[136:139]
	v_mfma_f32_16x16x32_bf16 v[140:143], v[128:131], v[164:167], v[140:143]
	v_mfma_f32_16x16x32_bf16 v[140:143], v[120:123], v[160:163], v[140:143]
	v_mfma_f32_16x16x32_bf16 v[132:135], v[144:147], v[160:163], v[132:135]
	v_mfma_f32_16x16x32_bf16 v[132:135], v[148:151], v[164:167], v[132:135]
	v_mfma_f32_16x16x32_bf16 v[124:127], v[156:159], v[164:167], v[124:127]
	v_mfma_f32_16x16x32_bf16 v[124:127], v[152:155], v[160:163], v[124:127]
	v_mfma_f32_16x16x32_bf16 v[96:99], v[152:155], v[168:171], v[96:99]
	v_mfma_f32_16x16x32_bf16 v[96:99], v[156:159], v[172:175], v[96:99]
	v_mfma_f32_16x16x32_bf16 v[100:103], v[148:151], v[172:175], v[100:103]
	v_mfma_f32_16x16x32_bf16 v[100:103], v[144:147], v[168:171], v[100:103]
	v_mfma_f32_16x16x32_bf16 v[104:107], v[120:123], v[168:171], v[104:107]
	v_mfma_f32_16x16x32_bf16 v[104:107], v[128:131], v[172:175], v[104:107]
	v_mfma_f32_16x16x32_bf16 v[108:111], v[116:119], v[172:175], v[108:111]
	v_mfma_f32_16x16x32_bf16 v[108:111], v[112:115], v[168:171], v[108:111]
	v_mfma_f32_16x16x32_bf16 v[92:95], v[112:115], v[188:191], v[92:95]
	v_mfma_f32_16x16x32_bf16 v[92:95], v[116:119], v[192:195], v[92:95]
	v_mfma_f32_16x16x32_bf16 v[88:91], v[128:131], v[192:195], v[88:91]
	v_mfma_f32_16x16x32_bf16 v[88:91], v[120:123], v[188:191], v[88:91]
	v_mfma_f32_16x16x32_bf16 v[84:87], v[144:147], v[188:191], v[84:87]
	v_mfma_f32_16x16x32_bf16 v[84:87], v[148:151], v[192:195], v[84:87]
	v_mfma_f32_16x16x32_bf16 v[80:83], v[156:159], v[192:195], v[80:83]
	v_mfma_f32_16x16x32_bf16 v[80:83], v[152:155], v[188:191], v[80:83]
	v_mfma_f32_16x16x32_bf16 v[64:67], v[152:155], v[196:199], v[64:67]
	v_mfma_f32_16x16x32_bf16 v[64:67], v[156:159], v[200:203], v[64:67]
	v_mfma_f32_16x16x32_bf16 v[68:71], v[148:151], v[200:203], v[68:71]
	v_mfma_f32_16x16x32_bf16 v[68:71], v[144:147], v[196:199], v[68:71]
	v_mfma_f32_16x16x32_bf16 v[72:75], v[120:123], v[196:199], v[72:75]
	v_mfma_f32_16x16x32_bf16 v[72:75], v[128:131], v[200:203], v[72:75]
	v_mfma_f32_16x16x32_bf16 v[76:79], v[116:119], v[200:203], v[76:79]
	v_mfma_f32_16x16x32_bf16 v[76:79], v[112:115], v[196:199], v[76:79]
	s_barrier
	s_add_i32 s30, s63, s37
	v_lshl_add_u64 v[204:205], v[204:205], 0, s[18:19]
	s_mov_b32 m0, s30
	ds_read_b128 v[160:163], v211 offset:49152
	ds_read_b128 v[164:167], v211 offset:50176
	ds_read_b128 v[168:171], v211 offset:51200
	ds_read_b128 v[172:175], v211 offset:52224
	ds_read_b128 v[188:191], v211 offset:53248
	ds_read_b128 v[192:195], v211 offset:54272
	ds_read_b128 v[196:199], v211 offset:55296
	ds_read_b128 v[200:203], v211 offset:56320
	global_load_lds_dwordx4 v[204:205], off
	v_lshl_add_u64 v[204:205], v[214:215], 0, s[18:19]
	s_add_i32 m0, s30, 0x2000
	s_add_i32 s30, s64, s37
	global_load_lds_dwordx4 v[204:205], off
	v_lshl_add_u64 v[204:205], v[216:217], 0, s[18:19]
	s_mov_b32 m0, s30
	s_nop 0
	global_load_lds_dwordx4 v[204:205], off
	v_lshl_add_u64 v[204:205], v[218:219], 0, s[18:19]
	s_add_i32 m0, s30, 0x2000
	s_nop 0
	global_load_lds_dwordx4 v[204:205], off
	v_lshl_add_u64 v[204:205], v[222:223], 0, s[18:19]
	s_mov_b32 m0, s43
	s_nop 0
	global_load_lds_dwordx4 v[204:205], off
	v_lshl_add_u64 v[204:205], v[224:225], 0, s[18:19]
	s_mov_b32 m0, s44
	s_nop 0
	global_load_lds_dwordx4 v[204:205], off
	s_waitcnt vmcnt(8)
	s_waitcnt lgkmcnt(0)
	s_barrier
	s_waitcnt lgkmcnt(0)
	v_mfma_f32_16x16x32_bf16 v[60:63], v[112:115], v[160:163], v[60:63]
	v_mfma_f32_16x16x32_bf16 v[60:63], v[116:119], v[164:167], v[60:63]
	v_mfma_f32_16x16x32_bf16 v[56:59], v[128:131], v[164:167], v[56:59]
	v_mfma_f32_16x16x32_bf16 v[56:59], v[120:123], v[160:163], v[56:59]
	v_mfma_f32_16x16x32_bf16 v[52:55], v[144:147], v[160:163], v[52:55]
	v_mfma_f32_16x16x32_bf16 v[52:55], v[148:151], v[164:167], v[52:55]
	v_mfma_f32_16x16x32_bf16 v[48:51], v[156:159], v[164:167], v[48:51]
	v_mfma_f32_16x16x32_bf16 v[48:51], v[152:155], v[160:163], v[48:51]
	v_mfma_f32_16x16x32_bf16 v[32:35], v[152:155], v[168:171], v[32:35]
	v_mfma_f32_16x16x32_bf16 v[32:35], v[156:159], v[172:175], v[32:35]
	v_mfma_f32_16x16x32_bf16 v[36:39], v[148:151], v[172:175], v[36:39]
	v_mfma_f32_16x16x32_bf16 v[36:39], v[144:147], v[168:171], v[36:39]
	v_mfma_f32_16x16x32_bf16 v[40:43], v[120:123], v[168:171], v[40:43]
	v_mfma_f32_16x16x32_bf16 v[40:43], v[128:131], v[172:175], v[40:43]
	v_mfma_f32_16x16x32_bf16 v[44:47], v[116:119], v[172:175], v[44:47]
	v_mfma_f32_16x16x32_bf16 v[44:47], v[112:115], v[168:171], v[44:47]
	v_mfma_f32_16x16x32_bf16 v[28:31], v[112:115], v[188:191], v[28:31]
	v_mfma_f32_16x16x32_bf16 v[28:31], v[116:119], v[192:195], v[28:31]
	v_mfma_f32_16x16x32_bf16 v[24:27], v[128:131], v[192:195], v[24:27]
	v_mfma_f32_16x16x32_bf16 v[24:27], v[120:123], v[188:191], v[24:27]
	v_mfma_f32_16x16x32_bf16 v[20:23], v[144:147], v[188:191], v[20:23]
	v_mfma_f32_16x16x32_bf16 v[20:23], v[148:151], v[192:195], v[20:23]
	v_mfma_f32_16x16x32_bf16 v[16:19], v[156:159], v[192:195], v[16:19]
	v_mfma_f32_16x16x32_bf16 v[16:19], v[152:155], v[188:191], v[16:19]
	v_mfma_f32_16x16x32_bf16 v[0:3], v[152:155], v[196:199], v[0:3]
	v_mfma_f32_16x16x32_bf16 v[0:3], v[156:159], v[200:203], v[0:3]
	v_mfma_f32_16x16x32_bf16 v[4:7], v[148:151], v[200:203], v[4:7]
	v_mfma_f32_16x16x32_bf16 v[4:7], v[144:147], v[196:199], v[4:7]
	v_mfma_f32_16x16x32_bf16 v[8:11], v[120:123], v[196:199], v[8:11]
	v_mfma_f32_16x16x32_bf16 v[8:11], v[128:131], v[200:203], v[8:11]
	v_mfma_f32_16x16x32_bf16 v[12:15], v[116:119], v[200:203], v[12:15]
	v_mfma_f32_16x16x32_bf16 v[12:15], v[112:115], v[196:199], v[12:15]
	s_barrier
	s_add_u32 s28, s28, 0x100
	s_addc_u32 s29, s29, 0
	s_add_u32 s60, s60, 0x100
	s_addc_u32 s61, s61, 0
	s_cmp_ge_i32 s62, s45
	s_mov_b32 s30, s62
	s_cbranch_scc0 .LBB0_849

.LBB0_949:
	ds_read_b128 v[164:167], v157
	ds_read_b128 v[168:171], v157 offset:1024
	ds_read_b128 v[172:175], v157 offset:2048
	ds_read_b128 v[176:179], v157 offset:3072
	ds_read_b128 v[180:183], v162
	ds_read_b128 v[184:187], v162 offset:1024
	ds_read_b128 v[188:191], v162 offset:2048
	ds_read_b128 v[192:195], v162 offset:3072
	s_add_i32 s68, s34, 2
	s_add_u32 s69, s30, 0x80
	s_addc_u32 s35, s31, 0
	s_cmp_eq_u32 s49, s34
	s_cselect_b32 s34, s2, s69
	s_cselect_b32 s35, s3, s35
	s_cselect_b32 s71, s29, s67
	s_cselect_b32 s70, s28, s66
	v_lshl_add_u64 v[230:231], s[30:31], 0, v[136:137]
	s_add_i32 m0, s41, 0xc000
	ds_read_b128 v[196:199], v163
	ds_read_b128 v[200:203], v163 offset:1024
	ds_read_b128 v[204:207], v163 offset:2048
	ds_read_b128 v[208:211], v163 offset:3072
	ds_read_b128 v[212:215], v163 offset:4096
	ds_read_b128 v[216:219], v163 offset:5120
	ds_read_b128 v[222:225], v163 offset:6144
	ds_read_b128 v[226:229], v163 offset:7168
	global_load_lds_dwordx4 v[230:231], off
	v_lshl_add_u64 v[230:231], s[30:31], 0, v[138:139]
	s_add_i32 m0, s41, 0xe000
	s_nop 0
	global_load_lds_dwordx4 v[230:231], off
	s_waitcnt vmcnt(8)
	s_waitcnt lgkmcnt(0)
	s_barrier
	s_waitcnt lgkmcnt(0)
	v_mfma_f32_16x16x32_bf16 v[120:123], v[164:167], v[196:199], v[120:123]
	v_mfma_f32_16x16x32_bf16 v[120:123], v[168:171], v[200:203], v[120:123]
	v_mfma_f32_16x16x32_bf16 v[124:127], v[176:179], v[200:203], v[124:127]
	v_mfma_f32_16x16x32_bf16 v[124:127], v[172:175], v[196:199], v[124:127]
	v_mfma_f32_16x16x32_bf16 v[116:119], v[180:183], v[196:199], v[116:119]
	v_mfma_f32_16x16x32_bf16 v[116:119], v[184:187], v[200:203], v[116:119]
	v_mfma_f32_16x16x32_bf16 v[112:115], v[192:195], v[200:203], v[112:115]
	v_mfma_f32_16x16x32_bf16 v[112:115], v[188:191], v[196:199], v[112:115]
	v_mfma_f32_16x16x32_bf16 v[96:99], v[188:191], v[204:207], v[96:99]
	v_mfma_f32_16x16x32_bf16 v[96:99], v[192:195], v[208:211], v[96:99]
	v_mfma_f32_16x16x32_bf16 v[100:103], v[184:187], v[208:211], v[100:103]
	v_mfma_f32_16x16x32_bf16 v[100:103], v[180:183], v[204:207], v[100:103]
	v_mfma_f32_16x16x32_bf16 v[104:107], v[172:175], v[204:207], v[104:107]
	v_mfma_f32_16x16x32_bf16 v[104:107], v[176:179], v[208:211], v[104:107]
	v_mfma_f32_16x16x32_bf16 v[108:111], v[168:171], v[208:211], v[108:111]
	v_mfma_f32_16x16x32_bf16 v[108:111], v[164:167], v[204:207], v[108:111]
	v_mfma_f32_16x16x32_bf16 v[92:95], v[164:167], v[212:215], v[92:95]
	v_mfma_f32_16x16x32_bf16 v[92:95], v[168:171], v[216:219], v[92:95]
	v_mfma_f32_16x16x32_bf16 v[88:91], v[176:179], v[216:219], v[88:91]
	v_mfma_f32_16x16x32_bf16 v[88:91], v[172:175], v[212:215], v[88:91]
	v_mfma_f32_16x16x32_bf16 v[84:87], v[180:183], v[212:215], v[84:87]
	v_mfma_f32_16x16x32_bf16 v[84:87], v[184:187], v[216:219], v[84:87]
	v_mfma_f32_16x16x32_bf16 v[80:83], v[192:195], v[216:219], v[80:83]
	v_mfma_f32_16x16x32_bf16 v[80:83], v[188:191], v[212:215], v[80:83]
	v_mfma_f32_16x16x32_bf16 v[64:67], v[188:191], v[222:225], v[64:67]
	v_mfma_f32_16x16x32_bf16 v[64:67], v[192:195], v[226:229], v[64:67]
	v_mfma_f32_16x16x32_bf16 v[68:71], v[184:187], v[226:229], v[68:71]
	v_mfma_f32_16x16x32_bf16 v[68:71], v[180:183], v[222:225], v[68:71]
	v_mfma_f32_16x16x32_bf16 v[72:75], v[172:175], v[222:225], v[72:75]
	v_mfma_f32_16x16x32_bf16 v[72:75], v[176:179], v[226:229], v[72:75]
	v_mfma_f32_16x16x32_bf16 v[76:79], v[168:171], v[226:229], v[76:79]
	v_mfma_f32_16x16x32_bf16 v[76:79], v[164:167], v[222:225], v[76:79]
	s_barrier
	s_add_i32 s69, s52, s40
	v_lshl_add_u64 v[230:231], s[70:71], 0, v[130:131]
	s_mov_b32 m0, s69
	ds_read_b128 v[196:199], v163 offset:16384
	ds_read_b128 v[200:203], v163 offset:17408
	ds_read_b128 v[204:207], v163 offset:18432
	ds_read_b128 v[208:211], v163 offset:19456
	ds_read_b128 v[212:215], v163 offset:20480
	ds_read_b128 v[216:219], v163 offset:21504
	ds_read_b128 v[222:225], v163 offset:22528
	ds_read_b128 v[226:229], v163 offset:23552
	global_load_lds_dwordx4 v[230:231], off
	s_add_i32 m0, s69, 0x2000
	v_lshl_add_u64 v[232:233], s[70:71], 0, v[134:135]
	s_add_u32 s70, s70, s6
	s_addc_u32 s71, s71, s7
	s_add_i32 s69, s53, s40
	global_load_lds_dwordx4 v[232:233], off
	v_lshl_add_u64 v[234:235], s[70:71], 0, v[130:131]
	s_mov_b32 m0, s69
	v_lshl_add_u64 v[236:237], s[70:71], 0, v[134:135]
	global_load_lds_dwordx4 v[234:235], off
	s_add_i32 m0, s69, 0x2000
	v_lshl_add_u64 v[238:239], s[34:35], 0, v[128:129]
	global_load_lds_dwordx4 v[236:237], off
	s_mov_b32 m0, s41
	v_lshl_add_u64 v[240:241], s[34:35], 0, v[132:133]
	global_load_lds_dwordx4 v[238:239], off
	s_mov_b32 m0, s42
	s_nop 0
	global_load_lds_dwordx4 v[240:241], off
	s_waitcnt vmcnt(8)
	s_waitcnt lgkmcnt(0)
	s_barrier
	s_waitcnt lgkmcnt(0)
	v_mfma_f32_16x16x32_bf16 v[60:63], v[164:167], v[196:199], v[60:63]
	v_mfma_f32_16x16x32_bf16 v[60:63], v[168:171], v[200:203], v[60:63]
	v_mfma_f32_16x16x32_bf16 v[56:59], v[176:179], v[200:203], v[56:59]
	v_mfma_f32_16x16x32_bf16 v[56:59], v[172:175], v[196:199], v[56:59]
	v_mfma_f32_16x16x32_bf16 v[52:55], v[180:183], v[196:199], v[52:55]
	v_mfma_f32_16x16x32_bf16 v[52:55], v[184:187], v[200:203], v[52:55]
	v_mfma_f32_16x16x32_bf16 v[48:51], v[192:195], v[200:203], v[48:51]
	v_mfma_f32_16x16x32_bf16 v[48:51], v[188:191], v[196:199], v[48:51]
	v_mfma_f32_16x16x32_bf16 v[32:35], v[188:191], v[204:207], v[32:35]
	v_mfma_f32_16x16x32_bf16 v[32:35], v[192:195], v[208:211], v[32:35]
	v_mfma_f32_16x16x32_bf16 v[36:39], v[184:187], v[208:211], v[36:39]
	v_mfma_f32_16x16x32_bf16 v[36:39], v[180:183], v[204:207], v[36:39]
	v_mfma_f32_16x16x32_bf16 v[40:43], v[172:175], v[204:207], v[40:43]
	v_mfma_f32_16x16x32_bf16 v[40:43], v[176:179], v[208:211], v[40:43]
	v_mfma_f32_16x16x32_bf16 v[44:47], v[168:171], v[208:211], v[44:47]
	v_mfma_f32_16x16x32_bf16 v[44:47], v[164:167], v[204:207], v[44:47]
	v_mfma_f32_16x16x32_bf16 v[28:31], v[164:167], v[212:215], v[28:31]
	v_mfma_f32_16x16x32_bf16 v[28:31], v[168:171], v[216:219], v[28:31]
	v_mfma_f32_16x16x32_bf16 v[24:27], v[176:179], v[216:219], v[24:27]
	v_mfma_f32_16x16x32_bf16 v[24:27], v[172:175], v[212:215], v[24:27]
	v_mfma_f32_16x16x32_bf16 v[20:23], v[180:183], v[212:215], v[20:23]
	v_mfma_f32_16x16x32_bf16 v[20:23], v[184:187], v[216:219], v[20:23]
	v_mfma_f32_16x16x32_bf16 v[16:19], v[192:195], v[216:219], v[16:19]
	v_mfma_f32_16x16x32_bf16 v[16:19], v[188:191], v[212:215], v[16:19]
	v_mfma_f32_16x16x32_bf16 v[0:3], v[188:191], v[222:225], v[0:3]
	v_mfma_f32_16x16x32_bf16 v[0:3], v[192:195], v[226:229], v[0:3]
	v_mfma_f32_16x16x32_bf16 v[4:7], v[184:187], v[226:229], v[4:7]
	v_mfma_f32_16x16x32_bf16 v[4:7], v[180:183], v[222:225], v[4:7]
	v_mfma_f32_16x16x32_bf16 v[8:11], v[172:175], v[222:225], v[8:11]
	v_mfma_f32_16x16x32_bf16 v[8:11], v[176:179], v[226:229], v[8:11]
	v_mfma_f32_16x16x32_bf16 v[12:15], v[168:171], v[226:229], v[12:15]
	v_mfma_f32_16x16x32_bf16 v[12:15], v[164:167], v[222:225], v[12:15]
	s_barrier
	s_add_i32 s69, 0, 0x18000
	s_add_i32 s70, 0, 0x1c000
	v_add_u32_e32 v176, s69, v154
	v_add_u32_e32 v192, s70, v154
	ds_read_b128 v[164:167], v176
	ds_read_b128 v[168:171], v176 offset:1024
	ds_read_b128 v[172:175], v176 offset:2048
	ds_read_b128 v[176:179], v176 offset:3072
	ds_read_b128 v[180:183], v192
	ds_read_b128 v[184:187], v192 offset:1024
	ds_read_b128 v[188:191], v192 offset:2048
	ds_read_b128 v[192:195], v192 offset:3072
	s_add_u32 s34, s34, s6
	s_addc_u32 s35, s35, s7
	s_mov_b32 m0, s43
	v_lshl_add_u64 v[242:243], s[34:35], 0, v[128:129]
	ds_read_b128 v[196:199], v163 offset:32768
	ds_read_b128 v[200:203], v163 offset:33792
	ds_read_b128 v[204:207], v163 offset:34816
	ds_read_b128 v[208:211], v163 offset:35840
	ds_read_b128 v[212:215], v163 offset:36864
	ds_read_b128 v[216:219], v163 offset:37888
	ds_read_b128 v[222:225], v163 offset:38912
	ds_read_b128 v[226:229], v163 offset:39936
	global_load_lds_dwordx4 v[242:243], off
	v_lshl_add_u64 v[242:243], s[34:35], 0, v[132:133]
	s_mov_b32 m0, s44
	s_nop 0
	global_load_lds_dwordx4 v[242:243], off
	s_waitcnt vmcnt(8)
	s_waitcnt lgkmcnt(0)
	s_barrier
	s_waitcnt lgkmcnt(0)
	v_mfma_f32_16x16x32_bf16 v[120:123], v[164:167], v[196:199], v[120:123]
	v_mfma_f32_16x16x32_bf16 v[120:123], v[168:171], v[200:203], v[120:123]
	v_mfma_f32_16x16x32_bf16 v[124:127], v[176:179], v[200:203], v[124:127]
	v_mfma_f32_16x16x32_bf16 v[124:127], v[172:175], v[196:199], v[124:127]
	v_mfma_f32_16x16x32_bf16 v[116:119], v[180:183], v[196:199], v[116:119]
	v_mfma_f32_16x16x32_bf16 v[116:119], v[184:187], v[200:203], v[116:119]
	v_mfma_f32_16x16x32_bf16 v[112:115], v[192:195], v[200:203], v[112:115]
	v_mfma_f32_16x16x32_bf16 v[112:115], v[188:191], v[196:199], v[112:115]
	v_mfma_f32_16x16x32_bf16 v[96:99], v[188:191], v[204:207], v[96:99]
	v_mfma_f32_16x16x32_bf16 v[96:99], v[192:195], v[208:211], v[96:99]
	v_mfma_f32_16x16x32_bf16 v[100:103], v[184:187], v[208:211], v[100:103]
	v_mfma_f32_16x16x32_bf16 v[100:103], v[180:183], v[204:207], v[100:103]
	v_mfma_f32_16x16x32_bf16 v[104:107], v[172:175], v[204:207], v[104:107]
	v_mfma_f32_16x16x32_bf16 v[104:107], v[176:179], v[208:211], v[104:107]
	v_mfma_f32_16x16x32_bf16 v[108:111], v[168:171], v[208:211], v[108:111]
	v_mfma_f32_16x16x32_bf16 v[108:111], v[164:167], v[204:207], v[108:111]
	v_mfma_f32_16x16x32_bf16 v[92:95], v[164:167], v[212:215], v[92:95]
	v_mfma_f32_16x16x32_bf16 v[92:95], v[168:171], v[216:219], v[92:95]
	v_mfma_f32_16x16x32_bf16 v[88:91], v[176:179], v[216:219], v[88:91]
	v_mfma_f32_16x16x32_bf16 v[88:91], v[172:175], v[212:215], v[88:91]
	v_mfma_f32_16x16x32_bf16 v[84:87], v[180:183], v[212:215], v[84:87]
	v_mfma_f32_16x16x32_bf16 v[84:87], v[184:187], v[216:219], v[84:87]
	v_mfma_f32_16x16x32_bf16 v[80:83], v[192:195], v[216:219], v[80:83]
	v_mfma_f32_16x16x32_bf16 v[80:83], v[188:191], v[212:215], v[80:83]
	v_mfma_f32_16x16x32_bf16 v[64:67], v[188:191], v[222:225], v[64:67]
	v_mfma_f32_16x16x32_bf16 v[64:67], v[192:195], v[226:229], v[64:67]
	v_mfma_f32_16x16x32_bf16 v[68:71], v[184:187], v[226:229], v[68:71]
	v_mfma_f32_16x16x32_bf16 v[68:71], v[180:183], v[222:225], v[68:71]
	v_mfma_f32_16x16x32_bf16 v[72:75], v[172:175], v[222:225], v[72:75]
	v_mfma_f32_16x16x32_bf16 v[72:75], v[176:179], v[226:229], v[72:75]
	v_mfma_f32_16x16x32_bf16 v[76:79], v[168:171], v[226:229], v[76:79]
	v_mfma_f32_16x16x32_bf16 v[76:79], v[164:167], v[222:225], v[76:79]
	s_barrier
	s_add_i32 s34, s69, s40
	v_lshl_add_u64 v[230:231], v[230:231], 0, s[12:13]
	s_mov_b32 m0, s34
	ds_read_b128 v[196:199], v163 offset:49152
	ds_read_b128 v[200:203], v163 offset:50176
	ds_read_b128 v[204:207], v163 offset:51200
	ds_read_b128 v[208:211], v163 offset:52224
	ds_read_b128 v[212:215], v163 offset:53248
	ds_read_b128 v[216:219], v163 offset:54272
	ds_read_b128 v[222:225], v163 offset:55296
	ds_read_b128 v[226:229], v163 offset:56320
	global_load_lds_dwordx4 v[230:231], off
	v_lshl_add_u64 v[230:231], v[232:233], 0, s[12:13]
	s_add_i32 m0, s34, 0x2000
	s_add_i32 s34, s70, s40
	global_load_lds_dwordx4 v[230:231], off
	v_lshl_add_u64 v[230:231], v[234:235], 0, s[12:13]
	s_mov_b32 m0, s34
	s_nop 0
	global_load_lds_dwordx4 v[230:231], off
	v_lshl_add_u64 v[230:231], v[236:237], 0, s[12:13]
	s_add_i32 m0, s34, 0x2000
	s_nop 0
	global_load_lds_dwordx4 v[230:231], off
	v_lshl_add_u64 v[230:231], v[238:239], 0, s[12:13]
	s_mov_b32 m0, s46
	s_nop 0
	global_load_lds_dwordx4 v[230:231], off
	v_lshl_add_u64 v[230:231], v[240:241], 0, s[12:13]
	s_mov_b32 m0, s47
	s_nop 0
	global_load_lds_dwordx4 v[230:231], off
	s_waitcnt vmcnt(8)
	s_waitcnt lgkmcnt(0)
	s_barrier
	s_waitcnt lgkmcnt(0)
	v_mfma_f32_16x16x32_bf16 v[60:63], v[164:167], v[196:199], v[60:63]
	v_mfma_f32_16x16x32_bf16 v[60:63], v[168:171], v[200:203], v[60:63]
	v_mfma_f32_16x16x32_bf16 v[56:59], v[176:179], v[200:203], v[56:59]
	v_mfma_f32_16x16x32_bf16 v[56:59], v[172:175], v[196:199], v[56:59]
	v_mfma_f32_16x16x32_bf16 v[52:55], v[180:183], v[196:199], v[52:55]
	v_mfma_f32_16x16x32_bf16 v[52:55], v[184:187], v[200:203], v[52:55]
	v_mfma_f32_16x16x32_bf16 v[48:51], v[192:195], v[200:203], v[48:51]
	v_mfma_f32_16x16x32_bf16 v[48:51], v[188:191], v[196:199], v[48:51]
	v_mfma_f32_16x16x32_bf16 v[32:35], v[188:191], v[204:207], v[32:35]
	v_mfma_f32_16x16x32_bf16 v[32:35], v[192:195], v[208:211], v[32:35]
	v_mfma_f32_16x16x32_bf16 v[36:39], v[184:187], v[208:211], v[36:39]
	v_mfma_f32_16x16x32_bf16 v[36:39], v[180:183], v[204:207], v[36:39]
	v_mfma_f32_16x16x32_bf16 v[40:43], v[172:175], v[204:207], v[40:43]
	v_mfma_f32_16x16x32_bf16 v[40:43], v[176:179], v[208:211], v[40:43]
	v_mfma_f32_16x16x32_bf16 v[44:47], v[168:171], v[208:211], v[44:47]
	v_mfma_f32_16x16x32_bf16 v[44:47], v[164:167], v[204:207], v[44:47]
	v_mfma_f32_16x16x32_bf16 v[28:31], v[164:167], v[212:215], v[28:31]
	v_mfma_f32_16x16x32_bf16 v[28:31], v[168:171], v[216:219], v[28:31]
	v_mfma_f32_16x16x32_bf16 v[24:27], v[176:179], v[216:219], v[24:27]
	v_mfma_f32_16x16x32_bf16 v[24:27], v[172:175], v[212:215], v[24:27]
	v_mfma_f32_16x16x32_bf16 v[20:23], v[180:183], v[212:215], v[20:23]
	v_mfma_f32_16x16x32_bf16 v[20:23], v[184:187], v[216:219], v[20:23]
	v_mfma_f32_16x16x32_bf16 v[16:19], v[192:195], v[216:219], v[16:19]
	v_mfma_f32_16x16x32_bf16 v[16:19], v[188:191], v[212:215], v[16:19]
	v_mfma_f32_16x16x32_bf16 v[0:3], v[188:191], v[222:225], v[0:3]
	v_mfma_f32_16x16x32_bf16 v[0:3], v[192:195], v[226:229], v[0:3]
	v_mfma_f32_16x16x32_bf16 v[4:7], v[184:187], v[226:229], v[4:7]
	v_mfma_f32_16x16x32_bf16 v[4:7], v[180:183], v[222:225], v[4:7]
	v_mfma_f32_16x16x32_bf16 v[8:11], v[172:175], v[222:225], v[8:11]
	v_mfma_f32_16x16x32_bf16 v[8:11], v[176:179], v[226:229], v[8:11]
	v_mfma_f32_16x16x32_bf16 v[12:15], v[168:171], v[226:229], v[12:15]
	v_mfma_f32_16x16x32_bf16 v[12:15], v[164:167], v[222:225], v[12:15]
	s_barrier
	s_add_u32 s30, s30, 0x100
	s_addc_u32 s31, s31, 0
	s_add_u32 s66, s66, 0x100
	s_addc_u32 s67, s67, 0
	s_cmp_ge_i32 s68, s48
	s_mov_b32 s34, s68
	s_cbranch_scc0 .LBB0_949

.LBB0_970:
	ds_read_b128 v[170:173], v139
	ds_read_b128 v[174:177], v139 offset:1024
	ds_read_b128 v[178:181], v139 offset:2048
	ds_read_b128 v[182:185], v139 offset:3072
	ds_read_b128 v[186:189], v165
	ds_read_b128 v[190:193], v165 offset:1024
	ds_read_b128 v[194:197], v165 offset:2048
	ds_read_b128 v[198:201], v165 offset:3072
	s_add_i32 s8, s4, 2
	s_add_u32 s9, s2, 0x80
	s_addc_u32 s5, s3, 0
	s_cmp_eq_u32 s52, s4
	s_cselect_b32 s4, s30, s9
	s_cselect_b32 s5, s31, s5
	s_cselect_b32 s11, s35, s7
	s_cselect_b32 s10, s34, s6
	v_lshl_add_u64 v[218:219], s[2:3], 0, v[156:157]
	s_add_i32 m0, s42, 0xc000
	ds_read_b128 v[202:205], v166
	ds_read_b128 v[206:209], v166 offset:1024
	ds_read_b128 v[210:213], v166 offset:2048
	ds_read_b128 v[214:217], v166 offset:3072
	ds_read_b128 v[222:225], v166 offset:4096
	ds_read_b128 v[226:229], v166 offset:5120
	ds_read_b128 v[230:233], v166 offset:6144
	ds_read_b128 v[234:237], v166 offset:7168
	global_load_lds_dwordx4 v[218:219], off
	v_lshl_add_u64 v[218:219], s[2:3], 0, v[158:159]
	s_add_i32 m0, s42, 0xe000
	s_nop 0
	global_load_lds_dwordx4 v[218:219], off
	s_waitcnt vmcnt(8)
	s_waitcnt lgkmcnt(0)
	s_barrier
	s_waitcnt lgkmcnt(0)
	v_mfma_f32_16x16x32_bf16 v[124:127], v[170:173], v[202:205], v[124:127]
	v_mfma_f32_16x16x32_bf16 v[124:127], v[174:177], v[206:209], v[124:127]
	v_mfma_f32_16x16x32_bf16 v[120:123], v[182:185], v[206:209], v[120:123]
	v_mfma_f32_16x16x32_bf16 v[120:123], v[178:181], v[202:205], v[120:123]
	v_mfma_f32_16x16x32_bf16 v[116:119], v[186:189], v[202:205], v[116:119]
	v_mfma_f32_16x16x32_bf16 v[116:119], v[190:193], v[206:209], v[116:119]
	v_mfma_f32_16x16x32_bf16 v[112:115], v[198:201], v[206:209], v[112:115]
	v_mfma_f32_16x16x32_bf16 v[112:115], v[194:197], v[202:205], v[112:115]
	v_mfma_f32_16x16x32_bf16 v[96:99], v[194:197], v[210:213], v[96:99]
	v_mfma_f32_16x16x32_bf16 v[96:99], v[198:201], v[214:217], v[96:99]
	v_mfma_f32_16x16x32_bf16 v[100:103], v[190:193], v[214:217], v[100:103]
	v_mfma_f32_16x16x32_bf16 v[100:103], v[186:189], v[210:213], v[100:103]
	v_mfma_f32_16x16x32_bf16 v[104:107], v[178:181], v[210:213], v[104:107]
	v_mfma_f32_16x16x32_bf16 v[104:107], v[182:185], v[214:217], v[104:107]
	v_mfma_f32_16x16x32_bf16 v[108:111], v[174:177], v[214:217], v[108:111]
	v_mfma_f32_16x16x32_bf16 v[108:111], v[170:173], v[210:213], v[108:111]
	v_mfma_f32_16x16x32_bf16 v[92:95], v[170:173], v[222:225], v[92:95]
	v_mfma_f32_16x16x32_bf16 v[92:95], v[174:177], v[226:229], v[92:95]
	v_mfma_f32_16x16x32_bf16 v[88:91], v[182:185], v[226:229], v[88:91]
	v_mfma_f32_16x16x32_bf16 v[88:91], v[178:181], v[222:225], v[88:91]
	v_mfma_f32_16x16x32_bf16 v[84:87], v[186:189], v[222:225], v[84:87]
	v_mfma_f32_16x16x32_bf16 v[84:87], v[190:193], v[226:229], v[84:87]
	v_mfma_f32_16x16x32_bf16 v[80:83], v[198:201], v[226:229], v[80:83]
	v_mfma_f32_16x16x32_bf16 v[80:83], v[194:197], v[222:225], v[80:83]
	v_mfma_f32_16x16x32_bf16 v[64:67], v[194:197], v[230:233], v[64:67]
	v_mfma_f32_16x16x32_bf16 v[64:67], v[198:201], v[234:237], v[64:67]
	v_mfma_f32_16x16x32_bf16 v[68:71], v[190:193], v[234:237], v[68:71]
	v_mfma_f32_16x16x32_bf16 v[68:71], v[186:189], v[230:233], v[68:71]
	v_mfma_f32_16x16x32_bf16 v[72:75], v[178:181], v[230:233], v[72:75]
	v_mfma_f32_16x16x32_bf16 v[72:75], v[182:185], v[234:237], v[72:75]
	v_mfma_f32_16x16x32_bf16 v[76:79], v[174:177], v[234:237], v[76:79]
	v_mfma_f32_16x16x32_bf16 v[76:79], v[170:173], v[230:233], v[76:79]
	s_barrier
	s_add_i32 s9, s60, s39
	v_lshl_add_u64 v[218:219], s[10:11], 0, v[132:133]
	s_mov_b32 m0, s9
	ds_read_b128 v[202:205], v166 offset:16384
	ds_read_b128 v[206:209], v166 offset:17408
	ds_read_b128 v[210:213], v166 offset:18432
	ds_read_b128 v[214:217], v166 offset:19456
	ds_read_b128 v[222:225], v166 offset:20480
	ds_read_b128 v[226:229], v166 offset:21504
	ds_read_b128 v[230:233], v166 offset:22528
	ds_read_b128 v[234:237], v166 offset:23552
	global_load_lds_dwordx4 v[218:219], off
	s_add_i32 m0, s9, 0x2000
	v_lshl_add_u64 v[238:239], s[10:11], 0, v[128:129]
	s_add_u32 s10, s10, s18
	s_addc_u32 s11, s11, s19
	s_add_i32 s9, s61, s39
	global_load_lds_dwordx4 v[238:239], off
	v_lshl_add_u64 v[240:241], s[10:11], 0, v[132:133]
	s_mov_b32 m0, s9
	v_lshl_add_u64 v[242:243], s[10:11], 0, v[128:129]
	global_load_lds_dwordx4 v[240:241], off
	s_add_i32 m0, s9, 0x2000
	v_lshl_add_u64 v[244:245], s[4:5], 0, v[134:135]
	global_load_lds_dwordx4 v[242:243], off
	s_mov_b32 m0, s42
	v_lshl_add_u64 v[246:247], s[4:5], 0, v[130:131]
	global_load_lds_dwordx4 v[244:245], off
	s_mov_b32 m0, s43
	s_nop 0
	global_load_lds_dwordx4 v[246:247], off
	s_waitcnt vmcnt(8)
	s_waitcnt lgkmcnt(0)
	s_barrier
	s_waitcnt lgkmcnt(0)
	v_mfma_f32_16x16x32_bf16 v[60:63], v[170:173], v[202:205], v[60:63]
	v_mfma_f32_16x16x32_bf16 v[60:63], v[174:177], v[206:209], v[60:63]
	v_mfma_f32_16x16x32_bf16 v[56:59], v[182:185], v[206:209], v[56:59]
	v_mfma_f32_16x16x32_bf16 v[56:59], v[178:181], v[202:205], v[56:59]
	v_mfma_f32_16x16x32_bf16 v[52:55], v[186:189], v[202:205], v[52:55]
	v_mfma_f32_16x16x32_bf16 v[52:55], v[190:193], v[206:209], v[52:55]
	v_mfma_f32_16x16x32_bf16 v[48:51], v[198:201], v[206:209], v[48:51]
	v_mfma_f32_16x16x32_bf16 v[48:51], v[194:197], v[202:205], v[48:51]
	v_mfma_f32_16x16x32_bf16 v[32:35], v[194:197], v[210:213], v[32:35]
	v_mfma_f32_16x16x32_bf16 v[32:35], v[198:201], v[214:217], v[32:35]
	v_mfma_f32_16x16x32_bf16 v[36:39], v[190:193], v[214:217], v[36:39]
	v_mfma_f32_16x16x32_bf16 v[36:39], v[186:189], v[210:213], v[36:39]
	v_mfma_f32_16x16x32_bf16 v[40:43], v[178:181], v[210:213], v[40:43]
	v_mfma_f32_16x16x32_bf16 v[40:43], v[182:185], v[214:217], v[40:43]
	v_mfma_f32_16x16x32_bf16 v[44:47], v[174:177], v[214:217], v[44:47]
	v_mfma_f32_16x16x32_bf16 v[44:47], v[170:173], v[210:213], v[44:47]
	v_mfma_f32_16x16x32_bf16 v[28:31], v[170:173], v[222:225], v[28:31]
	v_mfma_f32_16x16x32_bf16 v[28:31], v[174:177], v[226:229], v[28:31]
	v_mfma_f32_16x16x32_bf16 v[24:27], v[182:185], v[226:229], v[24:27]
	v_mfma_f32_16x16x32_bf16 v[24:27], v[178:181], v[222:225], v[24:27]
	v_mfma_f32_16x16x32_bf16 v[20:23], v[186:189], v[222:225], v[20:23]
	v_mfma_f32_16x16x32_bf16 v[20:23], v[190:193], v[226:229], v[20:23]
	v_mfma_f32_16x16x32_bf16 v[16:19], v[198:201], v[226:229], v[16:19]
	v_mfma_f32_16x16x32_bf16 v[16:19], v[194:197], v[222:225], v[16:19]
	v_mfma_f32_16x16x32_bf16 v[0:3], v[194:197], v[230:233], v[0:3]
	v_mfma_f32_16x16x32_bf16 v[0:3], v[198:201], v[234:237], v[0:3]
	v_mfma_f32_16x16x32_bf16 v[4:7], v[190:193], v[234:237], v[4:7]
	v_mfma_f32_16x16x32_bf16 v[4:7], v[186:189], v[230:233], v[4:7]
	v_mfma_f32_16x16x32_bf16 v[8:11], v[178:181], v[230:233], v[8:11]
	v_mfma_f32_16x16x32_bf16 v[8:11], v[182:185], v[234:237], v[8:11]
	v_mfma_f32_16x16x32_bf16 v[12:15], v[174:177], v[234:237], v[12:15]
	v_mfma_f32_16x16x32_bf16 v[12:15], v[170:173], v[230:233], v[12:15]
	s_barrier
	s_add_i32 s9, 0, 0x18000
	v_add_u32_e32 v169, s9, v164
	s_add_i32 s10, 0, 0x1c000
	ds_read_b128 v[170:173], v169
	ds_read_b128 v[174:177], v169 offset:1024
	ds_read_b128 v[178:181], v169 offset:2048
	ds_read_b128 v[182:185], v169 offset:3072
	v_add_u32_e32 v169, s10, v164
	ds_read_b128 v[186:189], v169
	ds_read_b128 v[190:193], v169 offset:1024
	ds_read_b128 v[194:197], v169 offset:2048
	ds_read_b128 v[198:201], v169 offset:3072
	s_add_u32 s4, s4, s18
	s_addc_u32 s5, s5, s19
	s_mov_b32 m0, s44
	v_lshl_add_u64 v[248:249], s[4:5], 0, v[134:135]
	ds_read_b128 v[202:205], v166 offset:32768
	ds_read_b128 v[206:209], v166 offset:33792
	ds_read_b128 v[210:213], v166 offset:34816
	ds_read_b128 v[214:217], v166 offset:35840
	ds_read_b128 v[222:225], v166 offset:36864
	ds_read_b128 v[226:229], v166 offset:37888
	ds_read_b128 v[230:233], v166 offset:38912
	ds_read_b128 v[234:237], v166 offset:39936
	global_load_lds_dwordx4 v[248:249], off
	v_lshl_add_u64 v[248:249], s[4:5], 0, v[130:131]
	s_mov_b32 m0, s45
	s_nop 0
	global_load_lds_dwordx4 v[248:249], off
	s_waitcnt vmcnt(8)
	s_waitcnt lgkmcnt(0)
	s_barrier
	s_waitcnt lgkmcnt(0)
	v_mfma_f32_16x16x32_bf16 v[124:127], v[170:173], v[202:205], v[124:127]
	v_mfma_f32_16x16x32_bf16 v[124:127], v[174:177], v[206:209], v[124:127]
	v_mfma_f32_16x16x32_bf16 v[120:123], v[182:185], v[206:209], v[120:123]
	v_mfma_f32_16x16x32_bf16 v[120:123], v[178:181], v[202:205], v[120:123]
	v_mfma_f32_16x16x32_bf16 v[116:119], v[186:189], v[202:205], v[116:119]
	v_mfma_f32_16x16x32_bf16 v[116:119], v[190:193], v[206:209], v[116:119]
	v_mfma_f32_16x16x32_bf16 v[112:115], v[198:201], v[206:209], v[112:115]
	v_mfma_f32_16x16x32_bf16 v[112:115], v[194:197], v[202:205], v[112:115]
	v_mfma_f32_16x16x32_bf16 v[96:99], v[194:197], v[210:213], v[96:99]
	v_mfma_f32_16x16x32_bf16 v[96:99], v[198:201], v[214:217], v[96:99]
	v_mfma_f32_16x16x32_bf16 v[100:103], v[190:193], v[214:217], v[100:103]
	v_mfma_f32_16x16x32_bf16 v[100:103], v[186:189], v[210:213], v[100:103]
	v_mfma_f32_16x16x32_bf16 v[104:107], v[178:181], v[210:213], v[104:107]
	v_mfma_f32_16x16x32_bf16 v[104:107], v[182:185], v[214:217], v[104:107]
	v_mfma_f32_16x16x32_bf16 v[108:111], v[174:177], v[214:217], v[108:111]
	v_mfma_f32_16x16x32_bf16 v[108:111], v[170:173], v[210:213], v[108:111]
	v_mfma_f32_16x16x32_bf16 v[92:95], v[170:173], v[222:225], v[92:95]
	v_mfma_f32_16x16x32_bf16 v[92:95], v[174:177], v[226:229], v[92:95]
	v_mfma_f32_16x16x32_bf16 v[88:91], v[182:185], v[226:229], v[88:91]
	v_mfma_f32_16x16x32_bf16 v[88:91], v[178:181], v[222:225], v[88:91]
	v_mfma_f32_16x16x32_bf16 v[84:87], v[186:189], v[222:225], v[84:87]
	v_mfma_f32_16x16x32_bf16 v[84:87], v[190:193], v[226:229], v[84:87]
	v_mfma_f32_16x16x32_bf16 v[80:83], v[198:201], v[226:229], v[80:83]
	v_mfma_f32_16x16x32_bf16 v[80:83], v[194:197], v[222:225], v[80:83]
	v_mfma_f32_16x16x32_bf16 v[64:67], v[194:197], v[230:233], v[64:67]
	v_mfma_f32_16x16x32_bf16 v[64:67], v[198:201], v[234:237], v[64:67]
	v_mfma_f32_16x16x32_bf16 v[68:71], v[190:193], v[234:237], v[68:71]
	v_mfma_f32_16x16x32_bf16 v[68:71], v[186:189], v[230:233], v[68:71]
	v_mfma_f32_16x16x32_bf16 v[72:75], v[178:181], v[230:233], v[72:75]
	v_mfma_f32_16x16x32_bf16 v[72:75], v[182:185], v[234:237], v[72:75]
	v_mfma_f32_16x16x32_bf16 v[76:79], v[174:177], v[234:237], v[76:79]
	v_mfma_f32_16x16x32_bf16 v[76:79], v[170:173], v[230:233], v[76:79]
	s_barrier
	s_add_i32 s4, s9, s39
	v_lshl_add_u64 v[218:219], v[218:219], 0, s[24:25]
	s_mov_b32 m0, s4
	ds_read_b128 v[202:205], v166 offset:49152
	ds_read_b128 v[206:209], v166 offset:50176
	ds_read_b128 v[210:213], v166 offset:51200
	ds_read_b128 v[214:217], v166 offset:52224
	ds_read_b128 v[222:225], v166 offset:53248
	ds_read_b128 v[226:229], v166 offset:54272
	ds_read_b128 v[230:233], v166 offset:55296
	ds_read_b128 v[234:237], v166 offset:56320
	global_load_lds_dwordx4 v[218:219], off
	v_lshl_add_u64 v[218:219], v[238:239], 0, s[24:25]
	s_add_i32 m0, s4, 0x2000
	s_add_i32 s4, s10, s39
	global_load_lds_dwordx4 v[218:219], off
	v_lshl_add_u64 v[218:219], v[240:241], 0, s[24:25]
	s_mov_b32 m0, s4
	s_nop 0
	global_load_lds_dwordx4 v[218:219], off
	v_lshl_add_u64 v[218:219], v[242:243], 0, s[24:25]
	s_add_i32 m0, s4, 0x2000
	s_nop 0
	global_load_lds_dwordx4 v[218:219], off
	v_lshl_add_u64 v[218:219], v[244:245], 0, s[24:25]
	s_mov_b32 m0, s49
	s_nop 0
	global_load_lds_dwordx4 v[218:219], off
	v_lshl_add_u64 v[218:219], v[246:247], 0, s[24:25]
	s_mov_b32 m0, s50
	s_nop 0
	global_load_lds_dwordx4 v[218:219], off
	s_waitcnt vmcnt(8)
	s_waitcnt lgkmcnt(0)
	s_barrier
	s_waitcnt lgkmcnt(0)
	v_mfma_f32_16x16x32_bf16 v[60:63], v[170:173], v[202:205], v[60:63]
	v_mfma_f32_16x16x32_bf16 v[60:63], v[174:177], v[206:209], v[60:63]
	v_mfma_f32_16x16x32_bf16 v[56:59], v[182:185], v[206:209], v[56:59]
	v_mfma_f32_16x16x32_bf16 v[56:59], v[178:181], v[202:205], v[56:59]
	v_mfma_f32_16x16x32_bf16 v[52:55], v[186:189], v[202:205], v[52:55]
	v_mfma_f32_16x16x32_bf16 v[52:55], v[190:193], v[206:209], v[52:55]
	v_mfma_f32_16x16x32_bf16 v[48:51], v[198:201], v[206:209], v[48:51]
	v_mfma_f32_16x16x32_bf16 v[48:51], v[194:197], v[202:205], v[48:51]
	v_mfma_f32_16x16x32_bf16 v[32:35], v[194:197], v[210:213], v[32:35]
	v_mfma_f32_16x16x32_bf16 v[32:35], v[198:201], v[214:217], v[32:35]
	v_mfma_f32_16x16x32_bf16 v[36:39], v[190:193], v[214:217], v[36:39]
	v_mfma_f32_16x16x32_bf16 v[36:39], v[186:189], v[210:213], v[36:39]
	v_mfma_f32_16x16x32_bf16 v[40:43], v[178:181], v[210:213], v[40:43]
	v_mfma_f32_16x16x32_bf16 v[40:43], v[182:185], v[214:217], v[40:43]
	v_mfma_f32_16x16x32_bf16 v[44:47], v[174:177], v[214:217], v[44:47]
	v_mfma_f32_16x16x32_bf16 v[44:47], v[170:173], v[210:213], v[44:47]
	v_mfma_f32_16x16x32_bf16 v[28:31], v[170:173], v[222:225], v[28:31]
	v_mfma_f32_16x16x32_bf16 v[28:31], v[174:177], v[226:229], v[28:31]
	v_mfma_f32_16x16x32_bf16 v[24:27], v[182:185], v[226:229], v[24:27]
	v_mfma_f32_16x16x32_bf16 v[24:27], v[178:181], v[222:225], v[24:27]
	v_mfma_f32_16x16x32_bf16 v[20:23], v[186:189], v[222:225], v[20:23]
	v_mfma_f32_16x16x32_bf16 v[20:23], v[190:193], v[226:229], v[20:23]
	v_mfma_f32_16x16x32_bf16 v[16:19], v[198:201], v[226:229], v[16:19]
	v_mfma_f32_16x16x32_bf16 v[16:19], v[194:197], v[222:225], v[16:19]
	v_mfma_f32_16x16x32_bf16 v[0:3], v[194:197], v[230:233], v[0:3]
	v_mfma_f32_16x16x32_bf16 v[0:3], v[198:201], v[234:237], v[0:3]
	v_mfma_f32_16x16x32_bf16 v[4:7], v[190:193], v[234:237], v[4:7]
	v_mfma_f32_16x16x32_bf16 v[4:7], v[186:189], v[230:233], v[4:7]
	v_mfma_f32_16x16x32_bf16 v[8:11], v[178:181], v[230:233], v[8:11]
	v_mfma_f32_16x16x32_bf16 v[8:11], v[182:185], v[234:237], v[8:11]
	v_mfma_f32_16x16x32_bf16 v[12:15], v[174:177], v[234:237], v[12:15]
	v_mfma_f32_16x16x32_bf16 v[12:15], v[170:173], v[230:233], v[12:15]
	s_barrier
	s_add_u32 s2, s2, 0x100
	s_addc_u32 s3, s3, 0
	s_add_u32 s6, s6, 0x100
	s_addc_u32 s7, s7, 0
	s_cmp_ge_i32 s8, s51
	s_mov_b32 s4, s8
	s_cbranch_scc0 .LBB0_970

.LBB0_1056:
	ds_read_b128 v[140:143], v222
	ds_read_b128 v[144:147], v222 offset:1024
	ds_read_b128 v[148:151], v222 offset:2048
	ds_read_b128 v[152:155], v222 offset:3072
	ds_read_b128 v[156:159], v223
	ds_read_b128 v[160:163], v223 offset:1024
	ds_read_b128 v[164:167], v223 offset:2048
	ds_read_b128 v[168:171], v223 offset:3072
	s_add_i32 s62, s26, 2
	s_add_u32 s27, s24, 0x4000
	s_addc_u32 s28, s25, 0
	s_cmp_eq_u32 s46, s26
	s_cselect_b32 s30, s0, s27
	s_cselect_b32 s31, s1, s28
	s_cselect_b32 s28, s22, s60
	s_cselect_b32 s29, s23, s61
	s_add_u32 s26, s30, 0x8000
	s_addc_u32 s27, s31, 0
	v_lshl_add_u64 v[204:205], s[24:25], 0, v[132:133]
	s_add_i32 m0, s38, 0xc000
	ds_read_b128 v[172:175], v224
	ds_read_b128 v[176:179], v224 offset:1024
	ds_read_b128 v[180:183], v224 offset:2048
	ds_read_b128 v[184:187], v224 offset:3072
	ds_read_b128 v[188:191], v224 offset:4096
	ds_read_b128 v[192:195], v224 offset:5120
	ds_read_b128 v[196:199], v224 offset:6144
	ds_read_b128 v[200:203], v224 offset:7168
	global_load_lds_dwordx4 v[204:205], off
	v_lshl_add_u64 v[204:205], s[24:25], 0, v[134:135]
	s_add_i32 m0, s38, 0xe000
	s_nop 0
	global_load_lds_dwordx4 v[204:205], off
	s_waitcnt vmcnt(8)
	s_waitcnt lgkmcnt(0)
	s_barrier
	s_waitcnt lgkmcnt(0)
	v_mfma_f32_16x16x32_bf16 v[124:127], v[140:143], v[172:175], v[124:127]
	v_mfma_f32_16x16x32_bf16 v[124:127], v[144:147], v[176:179], v[124:127]
	v_mfma_f32_16x16x32_bf16 v[120:123], v[152:155], v[176:179], v[120:123]
	v_mfma_f32_16x16x32_bf16 v[120:123], v[148:151], v[172:175], v[120:123]
	v_mfma_f32_16x16x32_bf16 v[108:111], v[156:159], v[172:175], v[108:111]
	v_mfma_f32_16x16x32_bf16 v[108:111], v[160:163], v[176:179], v[108:111]
	v_mfma_f32_16x16x32_bf16 v[100:103], v[168:171], v[176:179], v[100:103]
	v_mfma_f32_16x16x32_bf16 v[100:103], v[164:167], v[172:175], v[100:103]
	v_mfma_f32_16x16x32_bf16 v[84:87], v[164:167], v[180:183], v[84:87]
	v_mfma_f32_16x16x32_bf16 v[84:87], v[168:171], v[184:187], v[84:87]
	v_mfma_f32_16x16x32_bf16 v[92:95], v[160:163], v[184:187], v[92:95]
	v_mfma_f32_16x16x32_bf16 v[92:95], v[156:159], v[180:183], v[92:95]
	v_mfma_f32_16x16x32_bf16 v[112:115], v[148:151], v[180:183], v[112:115]
	v_mfma_f32_16x16x32_bf16 v[112:115], v[152:155], v[184:187], v[112:115]
	v_mfma_f32_16x16x32_bf16 v[116:119], v[144:147], v[184:187], v[116:119]
	v_mfma_f32_16x16x32_bf16 v[116:119], v[140:143], v[180:183], v[116:119]
	v_mfma_f32_16x16x32_bf16 v[104:107], v[140:143], v[188:191], v[104:107]
	v_mfma_f32_16x16x32_bf16 v[104:107], v[144:147], v[192:195], v[104:107]
	v_mfma_f32_16x16x32_bf16 v[96:99], v[152:155], v[192:195], v[96:99]
	v_mfma_f32_16x16x32_bf16 v[96:99], v[148:151], v[188:191], v[96:99]
	v_mfma_f32_16x16x32_bf16 v[76:79], v[156:159], v[188:191], v[76:79]
	v_mfma_f32_16x16x32_bf16 v[76:79], v[160:163], v[192:195], v[76:79]
	v_mfma_f32_16x16x32_bf16 v[72:75], v[168:171], v[192:195], v[72:75]
	v_mfma_f32_16x16x32_bf16 v[72:75], v[164:167], v[188:191], v[72:75]
	v_mfma_f32_16x16x32_bf16 v[64:67], v[164:167], v[196:199], v[64:67]
	v_mfma_f32_16x16x32_bf16 v[64:67], v[168:171], v[200:203], v[64:67]
	v_mfma_f32_16x16x32_bf16 v[68:71], v[160:163], v[200:203], v[68:71]
	v_mfma_f32_16x16x32_bf16 v[68:71], v[156:159], v[196:199], v[68:71]
	v_mfma_f32_16x16x32_bf16 v[80:83], v[148:151], v[196:199], v[80:83]
	v_mfma_f32_16x16x32_bf16 v[80:83], v[152:155], v[200:203], v[80:83]
	v_mfma_f32_16x16x32_bf16 v[88:91], v[144:147], v[200:203], v[88:91]
	v_mfma_f32_16x16x32_bf16 v[88:91], v[140:143], v[196:199], v[88:91]
	s_barrier
	s_add_i32 s63, s50, s37
	v_lshl_add_u64 v[204:205], s[28:29], 0, v[128:129]
	s_mov_b32 m0, s63
	ds_read_b128 v[172:175], v224 offset:16384
	ds_read_b128 v[176:179], v224 offset:17408
	ds_read_b128 v[180:183], v224 offset:18432
	ds_read_b128 v[184:187], v224 offset:19456
	ds_read_b128 v[188:191], v224 offset:20480
	ds_read_b128 v[192:195], v224 offset:21504
	ds_read_b128 v[196:199], v224 offset:22528
	ds_read_b128 v[200:203], v224 offset:23552
	global_load_lds_dwordx4 v[204:205], off
	s_add_i32 m0, s63, 0x2000
	s_add_u32 s64, s28, 0x4000
	v_lshl_add_u64 v[204:205], s[28:29], 0, v[130:131]
	s_addc_u32 s65, s29, 0
	s_add_i32 s63, s51, s37
	global_load_lds_dwordx4 v[204:205], off
	v_lshl_add_u64 v[204:205], s[64:65], 0, v[128:129]
	s_mov_b32 m0, s63
	s_nop 0
	global_load_lds_dwordx4 v[204:205], off
	v_lshl_add_u64 v[204:205], s[64:65], 0, v[130:131]
	s_add_i32 m0, s63, 0x2000
	s_nop 0
	global_load_lds_dwordx4 v[204:205], off
	v_lshl_add_u64 v[204:205], s[30:31], 0, v[128:129]
	s_mov_b32 m0, s38
	s_nop 0
	global_load_lds_dwordx4 v[204:205], off
	v_lshl_add_u64 v[204:205], s[30:31], 0, v[130:131]
	s_mov_b32 m0, s39
	s_nop 0
	global_load_lds_dwordx4 v[204:205], off
	s_waitcnt vmcnt(8)
	s_waitcnt lgkmcnt(0)
	s_barrier
	s_waitcnt lgkmcnt(0)
	v_mfma_f32_16x16x32_bf16 v[60:63], v[140:143], v[172:175], v[60:63]
	v_mfma_f32_16x16x32_bf16 v[60:63], v[144:147], v[176:179], v[60:63]
	v_mfma_f32_16x16x32_bf16 v[56:59], v[152:155], v[176:179], v[56:59]
	v_mfma_f32_16x16x32_bf16 v[56:59], v[148:151], v[172:175], v[56:59]
	v_mfma_f32_16x16x32_bf16 v[44:47], v[156:159], v[172:175], v[44:47]
	v_mfma_f32_16x16x32_bf16 v[44:47], v[160:163], v[176:179], v[44:47]
	v_mfma_f32_16x16x32_bf16 v[36:39], v[168:171], v[176:179], v[36:39]
	v_mfma_f32_16x16x32_bf16 v[36:39], v[164:167], v[172:175], v[36:39]
	v_mfma_f32_16x16x32_bf16 v[20:23], v[164:167], v[180:183], v[20:23]
	v_mfma_f32_16x16x32_bf16 v[20:23], v[168:171], v[184:187], v[20:23]
	v_mfma_f32_16x16x32_bf16 v[28:31], v[160:163], v[184:187], v[28:31]
	v_mfma_f32_16x16x32_bf16 v[28:31], v[156:159], v[180:183], v[28:31]
	v_mfma_f32_16x16x32_bf16 v[48:51], v[148:151], v[180:183], v[48:51]
	v_mfma_f32_16x16x32_bf16 v[48:51], v[152:155], v[184:187], v[48:51]
	v_mfma_f32_16x16x32_bf16 v[52:55], v[144:147], v[184:187], v[52:55]
	v_mfma_f32_16x16x32_bf16 v[52:55], v[140:143], v[180:183], v[52:55]
	v_mfma_f32_16x16x32_bf16 v[40:43], v[140:143], v[188:191], v[40:43]
	v_mfma_f32_16x16x32_bf16 v[40:43], v[144:147], v[192:195], v[40:43]
	v_mfma_f32_16x16x32_bf16 v[32:35], v[152:155], v[192:195], v[32:35]
	v_mfma_f32_16x16x32_bf16 v[32:35], v[148:151], v[188:191], v[32:35]
	v_mfma_f32_16x16x32_bf16 v[12:15], v[156:159], v[188:191], v[12:15]
	v_mfma_f32_16x16x32_bf16 v[12:15], v[160:163], v[192:195], v[12:15]
	v_mfma_f32_16x16x32_bf16 v[8:11], v[168:171], v[192:195], v[8:11]
	v_mfma_f32_16x16x32_bf16 v[8:11], v[164:167], v[188:191], v[8:11]
	v_mfma_f32_16x16x32_bf16 v[0:3], v[164:167], v[196:199], v[0:3]
	v_mfma_f32_16x16x32_bf16 v[0:3], v[168:171], v[200:203], v[0:3]
	v_mfma_f32_16x16x32_bf16 v[4:7], v[160:163], v[200:203], v[4:7]
	v_mfma_f32_16x16x32_bf16 v[4:7], v[156:159], v[196:199], v[4:7]
	v_mfma_f32_16x16x32_bf16 v[16:19], v[148:151], v[196:199], v[16:19]
	v_mfma_f32_16x16x32_bf16 v[16:19], v[152:155], v[200:203], v[16:19]
	v_mfma_f32_16x16x32_bf16 v[24:27], v[144:147], v[200:203], v[24:27]
	v_mfma_f32_16x16x32_bf16 v[24:27], v[140:143], v[196:199], v[24:27]
	s_barrier
	s_add_i32 s63, 0, 0x18000
	s_add_i32 s64, 0, 0x1c000
	v_add_u32_e32 v152, s63, v219
	v_add_u32_e32 v168, s64, v219
	ds_read_b128 v[140:143], v152
	ds_read_b128 v[144:147], v152 offset:1024
	ds_read_b128 v[148:151], v152 offset:2048
	ds_read_b128 v[152:155], v152 offset:3072
	ds_read_b128 v[156:159], v168
	ds_read_b128 v[160:163], v168 offset:1024
	ds_read_b128 v[164:167], v168 offset:2048
	ds_read_b128 v[168:171], v168 offset:3072
	s_add_u32 s30, s30, 0x4000
	s_addc_u32 s31, s31, 0
	s_mov_b32 m0, s40
	v_lshl_add_u64 v[204:205], s[30:31], 0, v[128:129]
	ds_read_b128 v[172:175], v224 offset:32768
	ds_read_b128 v[176:179], v224 offset:33792
	ds_read_b128 v[180:183], v224 offset:34816
	ds_read_b128 v[184:187], v224 offset:35840
	ds_read_b128 v[188:191], v224 offset:36864
	ds_read_b128 v[192:195], v224 offset:37888
	ds_read_b128 v[196:199], v224 offset:38912
	ds_read_b128 v[200:203], v224 offset:39936
	global_load_lds_dwordx4 v[204:205], off
	v_lshl_add_u64 v[204:205], s[30:31], 0, v[130:131]
	s_mov_b32 m0, s41
	s_nop 0
	global_load_lds_dwordx4 v[204:205], off
	s_waitcnt vmcnt(8)
	s_waitcnt lgkmcnt(0)
	s_barrier
	s_waitcnt lgkmcnt(0)
	v_mfma_f32_16x16x32_bf16 v[124:127], v[140:143], v[172:175], v[124:127]
	v_mfma_f32_16x16x32_bf16 v[124:127], v[144:147], v[176:179], v[124:127]
	v_mfma_f32_16x16x32_bf16 v[120:123], v[152:155], v[176:179], v[120:123]
	v_mfma_f32_16x16x32_bf16 v[120:123], v[148:151], v[172:175], v[120:123]
	v_mfma_f32_16x16x32_bf16 v[108:111], v[156:159], v[172:175], v[108:111]
	v_mfma_f32_16x16x32_bf16 v[108:111], v[160:163], v[176:179], v[108:111]
	v_mfma_f32_16x16x32_bf16 v[100:103], v[168:171], v[176:179], v[100:103]
	v_mfma_f32_16x16x32_bf16 v[100:103], v[164:167], v[172:175], v[100:103]
	v_mfma_f32_16x16x32_bf16 v[84:87], v[164:167], v[180:183], v[84:87]
	v_mfma_f32_16x16x32_bf16 v[84:87], v[168:171], v[184:187], v[84:87]
	v_mfma_f32_16x16x32_bf16 v[92:95], v[160:163], v[184:187], v[92:95]
	v_mfma_f32_16x16x32_bf16 v[92:95], v[156:159], v[180:183], v[92:95]
	v_mfma_f32_16x16x32_bf16 v[112:115], v[148:151], v[180:183], v[112:115]
	v_mfma_f32_16x16x32_bf16 v[112:115], v[152:155], v[184:187], v[112:115]
	v_mfma_f32_16x16x32_bf16 v[116:119], v[144:147], v[184:187], v[116:119]
	v_mfma_f32_16x16x32_bf16 v[116:119], v[140:143], v[180:183], v[116:119]
	v_mfma_f32_16x16x32_bf16 v[104:107], v[140:143], v[188:191], v[104:107]
	v_mfma_f32_16x16x32_bf16 v[104:107], v[144:147], v[192:195], v[104:107]
	v_mfma_f32_16x16x32_bf16 v[96:99], v[152:155], v[192:195], v[96:99]
	v_mfma_f32_16x16x32_bf16 v[96:99], v[148:151], v[188:191], v[96:99]
	v_mfma_f32_16x16x32_bf16 v[76:79], v[156:159], v[188:191], v[76:79]
	v_mfma_f32_16x16x32_bf16 v[76:79], v[160:163], v[192:195], v[76:79]
	v_mfma_f32_16x16x32_bf16 v[72:75], v[168:171], v[192:195], v[72:75]
	v_mfma_f32_16x16x32_bf16 v[72:75], v[164:167], v[188:191], v[72:75]
	v_mfma_f32_16x16x32_bf16 v[64:67], v[164:167], v[196:199], v[64:67]
	v_mfma_f32_16x16x32_bf16 v[64:67], v[168:171], v[200:203], v[64:67]
	v_mfma_f32_16x16x32_bf16 v[68:71], v[160:163], v[200:203], v[68:71]
	v_mfma_f32_16x16x32_bf16 v[68:71], v[156:159], v[196:199], v[68:71]
	v_mfma_f32_16x16x32_bf16 v[80:83], v[148:151], v[196:199], v[80:83]
	v_mfma_f32_16x16x32_bf16 v[80:83], v[152:155], v[200:203], v[80:83]
	v_mfma_f32_16x16x32_bf16 v[88:91], v[144:147], v[200:203], v[88:91]
	v_mfma_f32_16x16x32_bf16 v[88:91], v[140:143], v[196:199], v[88:91]
	s_barrier
	s_add_u32 s30, s28, 0x8000
	s_addc_u32 s31, s29, 0
	s_add_i32 s63, s63, s37
	v_lshl_add_u64 v[204:205], s[30:31], 0, v[128:129]
	s_mov_b32 m0, s63
	ds_read_b128 v[172:175], v224 offset:49152
	ds_read_b128 v[176:179], v224 offset:50176
	ds_read_b128 v[180:183], v224 offset:51200
	ds_read_b128 v[184:187], v224 offset:52224
	ds_read_b128 v[188:191], v224 offset:53248
	ds_read_b128 v[192:195], v224 offset:54272
	ds_read_b128 v[196:199], v224 offset:55296
	ds_read_b128 v[200:203], v224 offset:56320
	global_load_lds_dwordx4 v[204:205], off
	s_add_i32 m0, s63, 0x2000
	s_add_u32 s28, s28, 0xc000
	v_lshl_add_u64 v[204:205], s[30:31], 0, v[130:131]
	s_addc_u32 s29, s29, 0
	s_add_i32 s30, s64, s37
	global_load_lds_dwordx4 v[204:205], off
	v_lshl_add_u64 v[204:205], s[28:29], 0, v[128:129]
	s_mov_b32 m0, s30
	s_nop 0
	global_load_lds_dwordx4 v[204:205], off
	v_lshl_add_u64 v[204:205], s[28:29], 0, v[130:131]
	s_add_i32 m0, s30, 0x2000
	s_nop 0
	global_load_lds_dwordx4 v[204:205], off
	v_lshl_add_u64 v[204:205], s[26:27], 0, v[128:129]
	s_mov_b32 m0, s44
	s_nop 0
	global_load_lds_dwordx4 v[204:205], off
	v_lshl_add_u64 v[204:205], s[26:27], 0, v[130:131]
	s_mov_b32 m0, s45
	s_nop 0
	global_load_lds_dwordx4 v[204:205], off
	s_waitcnt vmcnt(8)
	s_waitcnt lgkmcnt(0)
	s_barrier
	s_waitcnt lgkmcnt(0)
	v_mfma_f32_16x16x32_bf16 v[60:63], v[140:143], v[172:175], v[60:63]
	v_mfma_f32_16x16x32_bf16 v[60:63], v[144:147], v[176:179], v[60:63]
	v_mfma_f32_16x16x32_bf16 v[56:59], v[152:155], v[176:179], v[56:59]
	v_mfma_f32_16x16x32_bf16 v[56:59], v[148:151], v[172:175], v[56:59]
	v_mfma_f32_16x16x32_bf16 v[44:47], v[156:159], v[172:175], v[44:47]
	v_mfma_f32_16x16x32_bf16 v[44:47], v[160:163], v[176:179], v[44:47]
	v_mfma_f32_16x16x32_bf16 v[36:39], v[168:171], v[176:179], v[36:39]
	v_mfma_f32_16x16x32_bf16 v[36:39], v[164:167], v[172:175], v[36:39]
	v_mfma_f32_16x16x32_bf16 v[20:23], v[164:167], v[180:183], v[20:23]
	v_mfma_f32_16x16x32_bf16 v[20:23], v[168:171], v[184:187], v[20:23]
	v_mfma_f32_16x16x32_bf16 v[28:31], v[160:163], v[184:187], v[28:31]
	v_mfma_f32_16x16x32_bf16 v[28:31], v[156:159], v[180:183], v[28:31]
	v_mfma_f32_16x16x32_bf16 v[48:51], v[148:151], v[180:183], v[48:51]
	v_mfma_f32_16x16x32_bf16 v[48:51], v[152:155], v[184:187], v[48:51]
	v_mfma_f32_16x16x32_bf16 v[52:55], v[144:147], v[184:187], v[52:55]
	v_mfma_f32_16x16x32_bf16 v[52:55], v[140:143], v[180:183], v[52:55]
	v_mfma_f32_16x16x32_bf16 v[40:43], v[140:143], v[188:191], v[40:43]
	v_mfma_f32_16x16x32_bf16 v[40:43], v[144:147], v[192:195], v[40:43]
	v_mfma_f32_16x16x32_bf16 v[32:35], v[152:155], v[192:195], v[32:35]
	v_mfma_f32_16x16x32_bf16 v[32:35], v[148:151], v[188:191], v[32:35]
	v_mfma_f32_16x16x32_bf16 v[12:15], v[156:159], v[188:191], v[12:15]
	v_mfma_f32_16x16x32_bf16 v[12:15], v[160:163], v[192:195], v[12:15]
	v_mfma_f32_16x16x32_bf16 v[8:11], v[168:171], v[192:195], v[8:11]
	v_mfma_f32_16x16x32_bf16 v[8:11], v[164:167], v[188:191], v[8:11]
	v_mfma_f32_16x16x32_bf16 v[0:3], v[164:167], v[196:199], v[0:3]
	v_mfma_f32_16x16x32_bf16 v[0:3], v[168:171], v[200:203], v[0:3]
	v_mfma_f32_16x16x32_bf16 v[4:7], v[160:163], v[200:203], v[4:7]
	v_mfma_f32_16x16x32_bf16 v[4:7], v[156:159], v[196:199], v[4:7]
	v_mfma_f32_16x16x32_bf16 v[16:19], v[148:151], v[196:199], v[16:19]
	v_mfma_f32_16x16x32_bf16 v[16:19], v[152:155], v[200:203], v[16:19]
	v_mfma_f32_16x16x32_bf16 v[24:27], v[144:147], v[200:203], v[24:27]
	v_mfma_f32_16x16x32_bf16 v[24:27], v[140:143], v[196:199], v[24:27]
	s_barrier
	s_add_u32 s24, s24, 0x10000
	s_addc_u32 s25, s25, 0
	s_add_u32 s60, s60, 0x10000
	s_addc_u32 s61, s61, 0
	s_cmp_ge_i32 s62, s43
	s_mov_b32 s26, s62
	s_cbranch_scc0 .LBB0_1056
	v_pk_mul_f32 v[198:199], v[126:127], 0.5 op_sel_hi:[1,0]
	v_pk_mul_f32 v[200:201], v[124:125], 0.5 op_sel_hi:[1,0]
	v_pk_mul_f32 v[202:203], v[122:123], 0.5 op_sel_hi:[1,0]
	v_pk_mul_f32 v[204:205], v[120:121], 0.5 op_sel_hi:[1,0]
	v_pk_mul_f32 v[208:209], v[110:111], 0.5 op_sel_hi:[1,0]
	v_pk_mul_f32 v[206:207], v[108:109], 0.5 op_sel_hi:[1,0]
	v_pk_mul_f32 v[196:197], v[102:103], 0.5 op_sel_hi:[1,0]
	v_pk_mul_f32 v[194:195], v[100:101], 0.5 op_sel_hi:[1,0]
	v_pk_mul_f32 v[192:193], v[118:119], 0.5 op_sel_hi:[1,0]
	v_pk_mul_f32 v[190:191], v[116:117], 0.5 op_sel_hi:[1,0]
	v_pk_mul_f32 v[188:189], v[114:115], 0.5 op_sel_hi:[1,0]
	v_pk_mul_f32 v[186:187], v[112:113], 0.5 op_sel_hi:[1,0]
	v_pk_mul_f32 v[184:185], v[94:95], 0.5 op_sel_hi:[1,0]
	v_pk_mul_f32 v[182:183], v[92:93], 0.5 op_sel_hi:[1,0]
	v_pk_mul_f32 v[180:181], v[86:87], 0.5 op_sel_hi:[1,0]
	v_pk_mul_f32 v[178:179], v[84:85], 0.5 op_sel_hi:[1,0]
	v_pk_mul_f32 v[176:177], v[106:107], 0.5 op_sel_hi:[1,0]
	v_pk_mul_f32 v[174:175], v[104:105], 0.5 op_sel_hi:[1,0]
	v_pk_mul_f32 v[172:173], v[98:99], 0.5 op_sel_hi:[1,0]
	v_pk_mul_f32 v[170:171], v[96:97], 0.5 op_sel_hi:[1,0]
	v_pk_mul_f32 v[168:169], v[78:79], 0.5 op_sel_hi:[1,0]
	v_pk_mul_f32 v[166:167], v[76:77], 0.5 op_sel_hi:[1,0]
	v_pk_mul_f32 v[164:165], v[74:75], 0.5 op_sel_hi:[1,0]
	v_pk_mul_f32 v[162:163], v[72:73], 0.5 op_sel_hi:[1,0]
	v_pk_mul_f32 v[160:161], v[90:91], 0.5 op_sel_hi:[1,0]
	v_pk_mul_f32 v[158:159], v[88:89], 0.5 op_sel_hi:[1,0]
	v_pk_mul_f32 v[156:157], v[82:83], 0.5 op_sel_hi:[1,0]
	v_pk_mul_f32 v[154:155], v[80:81], 0.5 op_sel_hi:[1,0]
	v_pk_mul_f32 v[152:153], v[70:71], 0.5 op_sel_hi:[1,0]
	v_pk_mul_f32 v[150:151], v[68:69], 0.5 op_sel_hi:[1,0]
	v_pk_mul_f32 v[148:149], v[66:67], 0.5 op_sel_hi:[1,0]
	v_pk_mul_f32 v[146:147], v[64:65], 0.5 op_sel_hi:[1,0]
	v_pk_mul_f32 v[142:143], v[62:63], 0.5 op_sel_hi:[1,0]
	v_pk_mul_f32 v[140:141], v[60:61], 0.5 op_sel_hi:[1,0]
	v_pk_mul_f32 v[126:127], v[58:59], 0.5 op_sel_hi:[1,0]
	v_pk_mul_f32 v[124:125], v[56:57], 0.5 op_sel_hi:[1,0]
	v_pk_mul_f32 v[122:123], v[46:47], 0.5 op_sel_hi:[1,0]
	v_pk_mul_f32 v[120:121], v[44:45], 0.5 op_sel_hi:[1,0]
	v_pk_mul_f32 v[118:119], v[38:39], 0.5 op_sel_hi:[1,0]
	v_pk_mul_f32 v[116:117], v[36:37], 0.5 op_sel_hi:[1,0]
	v_pk_mul_f32 v[114:115], v[54:55], 0.5 op_sel_hi:[1,0]
	v_pk_mul_f32 v[112:113], v[52:53], 0.5 op_sel_hi:[1,0]
	v_pk_mul_f32 v[110:111], v[50:51], 0.5 op_sel_hi:[1,0]
	v_pk_mul_f32 v[108:109], v[48:49], 0.5 op_sel_hi:[1,0]
	v_pk_mul_f32 v[106:107], v[30:31], 0.5 op_sel_hi:[1,0]
	v_pk_mul_f32 v[104:105], v[28:29], 0.5 op_sel_hi:[1,0]
	v_pk_mul_f32 v[102:103], v[22:23], 0.5 op_sel_hi:[1,0]
	v_pk_mul_f32 v[100:101], v[20:21], 0.5 op_sel_hi:[1,0]
	v_pk_mul_f32 v[98:99], v[42:43], 0.5 op_sel_hi:[1,0]
	v_pk_mul_f32 v[96:97], v[40:41], 0.5 op_sel_hi:[1,0]
	v_pk_mul_f32 v[94:95], v[34:35], 0.5 op_sel_hi:[1,0]
	v_pk_mul_f32 v[92:93], v[32:33], 0.5 op_sel_hi:[1,0]
	v_pk_mul_f32 v[90:91], v[14:15], 0.5 op_sel_hi:[1,0]
	v_pk_mul_f32 v[88:89], v[12:13], 0.5 op_sel_hi:[1,0]
	v_pk_mul_f32 v[86:87], v[10:11], 0.5 op_sel_hi:[1,0]
	v_pk_mul_f32 v[84:85], v[8:9], 0.5 op_sel_hi:[1,0]
	v_pk_mul_f32 v[82:83], v[26:27], 0.5 op_sel_hi:[1,0]
	v_pk_mul_f32 v[80:81], v[24:25], 0.5 op_sel_hi:[1,0]
	v_pk_mul_f32 v[78:79], v[18:19], 0.5 op_sel_hi:[1,0]
	v_pk_mul_f32 v[76:77], v[16:17], 0.5 op_sel_hi:[1,0]
	v_pk_mul_f32 v[74:75], v[6:7], 0.5 op_sel_hi:[1,0]
	v_pk_mul_f32 v[72:73], v[4:5], 0.5 op_sel_hi:[1,0]
	v_pk_mul_f32 v[70:71], v[2:3], 0.5 op_sel_hi:[1,0]
	v_pk_mul_f32 v[68:69], v[0:1], 0.5 op_sel_hi:[1,0]

.LBB0_1159:
	ds_read_b128 v[128:131], v205
	ds_read_b128 v[132:135], v205 offset:1024
	ds_read_b128 v[136:139], v205 offset:2048
	ds_read_b128 v[140:143], v205 offset:3072
	ds_read_b128 v[144:147], v206
	ds_read_b128 v[160:163], v206 offset:1024
	ds_read_b128 v[164:167], v206 offset:2048
	ds_read_b128 v[168:171], v206 offset:3072
	s_add_i32 s41, s6, 2
	s_add_u32 s68, s0, 0x80
	s_addc_u32 s7, s1, 0
	s_cmp_eq_u32 s57, s6
	s_cselect_b32 s6, s34, s68
	s_cselect_b32 s7, s35, s7
	s_cselect_b32 s69, s37, s39
	s_cselect_b32 s68, s36, s38
	v_lshl_add_u64 v[200:201], s[0:1], 0, v[152:153]
	s_add_i32 m0, s47, 0xc000
	ds_read_b128 v[172:175], v207
	ds_read_b128 v[176:179], v207 offset:1024
	ds_read_b128 v[180:183], v207 offset:2048
	ds_read_b128 v[184:187], v207 offset:3072
	ds_read_b128 v[188:191], v207 offset:4096
	ds_read_b128 v[192:195], v207 offset:5120
	ds_read_b128 v[196:199], v207 offset:6144
	ds_read_b128 v[212:215], v207 offset:7168
	global_load_lds_dwordx4 v[200:201], off
	v_lshl_add_u64 v[200:201], s[0:1], 0, v[154:155]
	s_add_i32 m0, s47, 0xe000
	s_nop 0
	global_load_lds_dwordx4 v[200:201], off
	s_waitcnt vmcnt(8)
	s_waitcnt lgkmcnt(0)
	s_barrier
	s_waitcnt lgkmcnt(0)
	v_mfma_f32_16x16x32_bf16 v[124:127], v[128:131], v[172:175], v[124:127]
	v_mfma_f32_16x16x32_bf16 v[124:127], v[132:135], v[176:179], v[124:127]
	v_mfma_f32_16x16x32_bf16 v[120:123], v[140:143], v[176:179], v[120:123]
	v_mfma_f32_16x16x32_bf16 v[120:123], v[136:139], v[172:175], v[120:123]
	v_mfma_f32_16x16x32_bf16 v[116:119], v[144:147], v[172:175], v[116:119]
	v_mfma_f32_16x16x32_bf16 v[116:119], v[160:163], v[176:179], v[116:119]
	v_mfma_f32_16x16x32_bf16 v[112:115], v[168:171], v[176:179], v[112:115]
	v_mfma_f32_16x16x32_bf16 v[112:115], v[164:167], v[172:175], v[112:115]
	v_mfma_f32_16x16x32_bf16 v[96:99], v[164:167], v[180:183], v[96:99]
	v_mfma_f32_16x16x32_bf16 v[96:99], v[168:171], v[184:187], v[96:99]
	v_mfma_f32_16x16x32_bf16 v[100:103], v[160:163], v[184:187], v[100:103]
	v_mfma_f32_16x16x32_bf16 v[100:103], v[144:147], v[180:183], v[100:103]
	v_mfma_f32_16x16x32_bf16 v[104:107], v[136:139], v[180:183], v[104:107]
	v_mfma_f32_16x16x32_bf16 v[104:107], v[140:143], v[184:187], v[104:107]
	v_mfma_f32_16x16x32_bf16 v[108:111], v[132:135], v[184:187], v[108:111]
	v_mfma_f32_16x16x32_bf16 v[108:111], v[128:131], v[180:183], v[108:111]
	v_mfma_f32_16x16x32_bf16 v[92:95], v[128:131], v[188:191], v[92:95]
	v_mfma_f32_16x16x32_bf16 v[92:95], v[132:135], v[192:195], v[92:95]
	v_mfma_f32_16x16x32_bf16 v[88:91], v[140:143], v[192:195], v[88:91]
	v_mfma_f32_16x16x32_bf16 v[88:91], v[136:139], v[188:191], v[88:91]
	v_mfma_f32_16x16x32_bf16 v[84:87], v[144:147], v[188:191], v[84:87]
	v_mfma_f32_16x16x32_bf16 v[84:87], v[160:163], v[192:195], v[84:87]
	v_mfma_f32_16x16x32_bf16 v[80:83], v[168:171], v[192:195], v[80:83]
	v_mfma_f32_16x16x32_bf16 v[80:83], v[164:167], v[188:191], v[80:83]
	v_mfma_f32_16x16x32_bf16 v[64:67], v[164:167], v[196:199], v[64:67]
	v_mfma_f32_16x16x32_bf16 v[64:67], v[168:171], v[212:215], v[64:67]
	v_mfma_f32_16x16x32_bf16 v[68:71], v[160:163], v[212:215], v[68:71]
	v_mfma_f32_16x16x32_bf16 v[68:71], v[144:147], v[196:199], v[68:71]
	v_mfma_f32_16x16x32_bf16 v[72:75], v[136:139], v[196:199], v[72:75]
	v_mfma_f32_16x16x32_bf16 v[72:75], v[140:143], v[212:215], v[72:75]
	v_mfma_f32_16x16x32_bf16 v[76:79], v[132:135], v[212:215], v[76:79]
	v_mfma_f32_16x16x32_bf16 v[76:79], v[128:131], v[196:199], v[76:79]
	s_barrier
	s_add_i32 s70, s60, s46
	v_lshl_add_u64 v[200:201], s[68:69], 0, v[148:149]
	s_mov_b32 m0, s70
	ds_read_b128 v[172:175], v207 offset:16384
	ds_read_b128 v[176:179], v207 offset:17408
	ds_read_b128 v[180:183], v207 offset:18432
	ds_read_b128 v[184:187], v207 offset:19456
	ds_read_b128 v[188:191], v207 offset:20480
	ds_read_b128 v[192:195], v207 offset:21504
	ds_read_b128 v[196:199], v207 offset:22528
	ds_read_b128 v[212:215], v207 offset:23552
	global_load_lds_dwordx4 v[200:201], off
	s_add_i32 m0, s70, 0x2000
	v_lshl_add_u64 v[216:217], s[68:69], 0, v[150:151]
	s_add_u32 s68, s68, s10
	s_addc_u32 s69, s69, s11
	s_add_i32 s70, s61, s46
	global_load_lds_dwordx4 v[216:217], off
	v_lshl_add_u64 v[218:219], s[68:69], 0, v[148:149]
	s_mov_b32 m0, s70
	v_lshl_add_u64 v[220:221], s[68:69], 0, v[150:151]
	global_load_lds_dwordx4 v[218:219], off
	s_add_i32 m0, s70, 0x2000
	v_lshl_add_u64 v[222:223], s[6:7], 0, v[148:149]
	global_load_lds_dwordx4 v[220:221], off
	s_mov_b32 m0, s47
	v_lshl_add_u64 v[224:225], s[6:7], 0, v[150:151]
	global_load_lds_dwordx4 v[222:223], off
	s_mov_b32 m0, s48
	s_nop 0
	global_load_lds_dwordx4 v[224:225], off
	s_waitcnt vmcnt(8)
	s_waitcnt lgkmcnt(0)
	s_barrier
	s_waitcnt lgkmcnt(0)
	v_mfma_f32_16x16x32_bf16 v[60:63], v[128:131], v[172:175], v[60:63]
	v_mfma_f32_16x16x32_bf16 v[60:63], v[132:135], v[176:179], v[60:63]
	v_mfma_f32_16x16x32_bf16 v[56:59], v[140:143], v[176:179], v[56:59]
	v_mfma_f32_16x16x32_bf16 v[56:59], v[136:139], v[172:175], v[56:59]
	v_mfma_f32_16x16x32_bf16 v[52:55], v[144:147], v[172:175], v[52:55]
	v_mfma_f32_16x16x32_bf16 v[52:55], v[160:163], v[176:179], v[52:55]
	v_mfma_f32_16x16x32_bf16 v[48:51], v[168:171], v[176:179], v[48:51]
	v_mfma_f32_16x16x32_bf16 v[48:51], v[164:167], v[172:175], v[48:51]
	v_mfma_f32_16x16x32_bf16 v[32:35], v[164:167], v[180:183], v[32:35]
	v_mfma_f32_16x16x32_bf16 v[32:35], v[168:171], v[184:187], v[32:35]
	v_mfma_f32_16x16x32_bf16 v[36:39], v[160:163], v[184:187], v[36:39]
	v_mfma_f32_16x16x32_bf16 v[36:39], v[144:147], v[180:183], v[36:39]
	v_mfma_f32_16x16x32_bf16 v[40:43], v[136:139], v[180:183], v[40:43]
	v_mfma_f32_16x16x32_bf16 v[40:43], v[140:143], v[184:187], v[40:43]
	v_mfma_f32_16x16x32_bf16 v[44:47], v[132:135], v[184:187], v[44:47]
	v_mfma_f32_16x16x32_bf16 v[44:47], v[128:131], v[180:183], v[44:47]
	v_mfma_f32_16x16x32_bf16 v[28:31], v[128:131], v[188:191], v[28:31]
	v_mfma_f32_16x16x32_bf16 v[28:31], v[132:135], v[192:195], v[28:31]
	v_mfma_f32_16x16x32_bf16 v[24:27], v[140:143], v[192:195], v[24:27]
	v_mfma_f32_16x16x32_bf16 v[24:27], v[136:139], v[188:191], v[24:27]
	v_mfma_f32_16x16x32_bf16 v[20:23], v[144:147], v[188:191], v[20:23]
	v_mfma_f32_16x16x32_bf16 v[20:23], v[160:163], v[192:195], v[20:23]
	v_mfma_f32_16x16x32_bf16 v[16:19], v[168:171], v[192:195], v[16:19]
	v_mfma_f32_16x16x32_bf16 v[16:19], v[164:167], v[188:191], v[16:19]
	v_mfma_f32_16x16x32_bf16 v[0:3], v[164:167], v[196:199], v[0:3]
	v_mfma_f32_16x16x32_bf16 v[0:3], v[168:171], v[212:215], v[0:3]
	v_mfma_f32_16x16x32_bf16 v[4:7], v[160:163], v[212:215], v[4:7]
	v_mfma_f32_16x16x32_bf16 v[4:7], v[144:147], v[196:199], v[4:7]
	v_mfma_f32_16x16x32_bf16 v[8:11], v[136:139], v[196:199], v[8:11]
	v_mfma_f32_16x16x32_bf16 v[8:11], v[140:143], v[212:215], v[8:11]
	v_mfma_f32_16x16x32_bf16 v[12:15], v[132:135], v[212:215], v[12:15]
	v_mfma_f32_16x16x32_bf16 v[12:15], v[128:131], v[196:199], v[12:15]
	s_barrier
	s_add_i32 s68, 0, 0x18000
	s_add_i32 s69, 0, 0x1c000
	v_add_u32_e32 v140, s68, v203
	v_add_u32_e32 v168, s69, v203
	ds_read_b128 v[128:131], v140
	ds_read_b128 v[132:135], v140 offset:1024
	ds_read_b128 v[136:139], v140 offset:2048
	ds_read_b128 v[140:143], v140 offset:3072
	ds_read_b128 v[144:147], v168
	ds_read_b128 v[160:163], v168 offset:1024
	ds_read_b128 v[164:167], v168 offset:2048
	ds_read_b128 v[168:171], v168 offset:3072
	s_add_u32 s6, s6, s10
	s_addc_u32 s7, s7, s11
	s_mov_b32 m0, s49
	v_lshl_add_u64 v[226:227], s[6:7], 0, v[148:149]
	ds_read_b128 v[172:175], v207 offset:32768
	ds_read_b128 v[176:179], v207 offset:33792
	ds_read_b128 v[180:183], v207 offset:34816
	ds_read_b128 v[184:187], v207 offset:35840
	ds_read_b128 v[188:191], v207 offset:36864
	ds_read_b128 v[192:195], v207 offset:37888
	ds_read_b128 v[196:199], v207 offset:38912
	ds_read_b128 v[212:215], v207 offset:39936
	global_load_lds_dwordx4 v[226:227], off
	v_lshl_add_u64 v[226:227], s[6:7], 0, v[150:151]
	s_mov_b32 m0, s50
	s_nop 0
	global_load_lds_dwordx4 v[226:227], off
	s_waitcnt vmcnt(8)
	s_waitcnt lgkmcnt(0)
	s_barrier
	s_waitcnt lgkmcnt(0)
	v_mfma_f32_16x16x32_bf16 v[124:127], v[128:131], v[172:175], v[124:127]
	v_mfma_f32_16x16x32_bf16 v[124:127], v[132:135], v[176:179], v[124:127]
	v_mfma_f32_16x16x32_bf16 v[120:123], v[140:143], v[176:179], v[120:123]
	v_mfma_f32_16x16x32_bf16 v[120:123], v[136:139], v[172:175], v[120:123]
	v_mfma_f32_16x16x32_bf16 v[116:119], v[144:147], v[172:175], v[116:119]
	v_mfma_f32_16x16x32_bf16 v[116:119], v[160:163], v[176:179], v[116:119]
	v_mfma_f32_16x16x32_bf16 v[112:115], v[168:171], v[176:179], v[112:115]
	v_mfma_f32_16x16x32_bf16 v[112:115], v[164:167], v[172:175], v[112:115]
	v_mfma_f32_16x16x32_bf16 v[96:99], v[164:167], v[180:183], v[96:99]
	v_mfma_f32_16x16x32_bf16 v[96:99], v[168:171], v[184:187], v[96:99]
	v_mfma_f32_16x16x32_bf16 v[100:103], v[160:163], v[184:187], v[100:103]
	v_mfma_f32_16x16x32_bf16 v[100:103], v[144:147], v[180:183], v[100:103]
	v_mfma_f32_16x16x32_bf16 v[104:107], v[136:139], v[180:183], v[104:107]
	v_mfma_f32_16x16x32_bf16 v[104:107], v[140:143], v[184:187], v[104:107]
	v_mfma_f32_16x16x32_bf16 v[108:111], v[132:135], v[184:187], v[108:111]
	v_mfma_f32_16x16x32_bf16 v[108:111], v[128:131], v[180:183], v[108:111]
	v_mfma_f32_16x16x32_bf16 v[92:95], v[128:131], v[188:191], v[92:95]
	v_mfma_f32_16x16x32_bf16 v[92:95], v[132:135], v[192:195], v[92:95]
	v_mfma_f32_16x16x32_bf16 v[88:91], v[140:143], v[192:195], v[88:91]
	v_mfma_f32_16x16x32_bf16 v[88:91], v[136:139], v[188:191], v[88:91]
	v_mfma_f32_16x16x32_bf16 v[84:87], v[144:147], v[188:191], v[84:87]
	v_mfma_f32_16x16x32_bf16 v[84:87], v[160:163], v[192:195], v[84:87]
	v_mfma_f32_16x16x32_bf16 v[80:83], v[168:171], v[192:195], v[80:83]
	v_mfma_f32_16x16x32_bf16 v[80:83], v[164:167], v[188:191], v[80:83]
	v_mfma_f32_16x16x32_bf16 v[64:67], v[164:167], v[196:199], v[64:67]
	v_mfma_f32_16x16x32_bf16 v[64:67], v[168:171], v[212:215], v[64:67]
	v_mfma_f32_16x16x32_bf16 v[68:71], v[160:163], v[212:215], v[68:71]
	v_mfma_f32_16x16x32_bf16 v[68:71], v[144:147], v[196:199], v[68:71]
	v_mfma_f32_16x16x32_bf16 v[72:75], v[136:139], v[196:199], v[72:75]
	v_mfma_f32_16x16x32_bf16 v[72:75], v[140:143], v[212:215], v[72:75]
	v_mfma_f32_16x16x32_bf16 v[76:79], v[132:135], v[212:215], v[76:79]
	v_mfma_f32_16x16x32_bf16 v[76:79], v[128:131], v[196:199], v[76:79]
	s_barrier
	s_add_i32 s6, s68, s46
	v_lshl_add_u64 v[200:201], v[200:201], 0, s[20:21]
	s_mov_b32 m0, s6
	ds_read_b128 v[172:175], v207 offset:49152
	ds_read_b128 v[176:179], v207 offset:50176
	ds_read_b128 v[180:183], v207 offset:51200
	ds_read_b128 v[184:187], v207 offset:52224
	ds_read_b128 v[188:191], v207 offset:53248
	ds_read_b128 v[192:195], v207 offset:54272
	ds_read_b128 v[196:199], v207 offset:55296
	ds_read_b128 v[212:215], v207 offset:56320
	global_load_lds_dwordx4 v[200:201], off
	v_lshl_add_u64 v[200:201], v[216:217], 0, s[20:21]
	s_add_i32 m0, s6, 0x2000
	s_add_i32 s6, s69, s46
	global_load_lds_dwordx4 v[200:201], off
	v_lshl_add_u64 v[200:201], v[218:219], 0, s[20:21]
	s_mov_b32 m0, s6
	s_nop 0
	global_load_lds_dwordx4 v[200:201], off
	v_lshl_add_u64 v[200:201], v[220:221], 0, s[20:21]
	s_add_i32 m0, s6, 0x2000
	s_nop 0
	global_load_lds_dwordx4 v[200:201], off
	v_lshl_add_u64 v[200:201], v[222:223], 0, s[20:21]
	s_mov_b32 m0, s54
	s_nop 0
	global_load_lds_dwordx4 v[200:201], off
	v_lshl_add_u64 v[200:201], v[224:225], 0, s[20:21]
	s_mov_b32 m0, s55
	s_nop 0
	global_load_lds_dwordx4 v[200:201], off
	s_waitcnt vmcnt(8)
	s_waitcnt lgkmcnt(0)
	s_barrier
	s_waitcnt lgkmcnt(0)
	v_mfma_f32_16x16x32_bf16 v[60:63], v[128:131], v[172:175], v[60:63]
	v_mfma_f32_16x16x32_bf16 v[60:63], v[132:135], v[176:179], v[60:63]
	v_mfma_f32_16x16x32_bf16 v[56:59], v[140:143], v[176:179], v[56:59]
	v_mfma_f32_16x16x32_bf16 v[56:59], v[136:139], v[172:175], v[56:59]
	v_mfma_f32_16x16x32_bf16 v[52:55], v[144:147], v[172:175], v[52:55]
	v_mfma_f32_16x16x32_bf16 v[52:55], v[160:163], v[176:179], v[52:55]
	v_mfma_f32_16x16x32_bf16 v[48:51], v[168:171], v[176:179], v[48:51]
	v_mfma_f32_16x16x32_bf16 v[48:51], v[164:167], v[172:175], v[48:51]
	v_mfma_f32_16x16x32_bf16 v[32:35], v[164:167], v[180:183], v[32:35]
	v_mfma_f32_16x16x32_bf16 v[32:35], v[168:171], v[184:187], v[32:35]
	v_mfma_f32_16x16x32_bf16 v[36:39], v[160:163], v[184:187], v[36:39]
	v_mfma_f32_16x16x32_bf16 v[36:39], v[144:147], v[180:183], v[36:39]
	v_mfma_f32_16x16x32_bf16 v[40:43], v[136:139], v[180:183], v[40:43]
	v_mfma_f32_16x16x32_bf16 v[40:43], v[140:143], v[184:187], v[40:43]
	v_mfma_f32_16x16x32_bf16 v[44:47], v[132:135], v[184:187], v[44:47]
	v_mfma_f32_16x16x32_bf16 v[44:47], v[128:131], v[180:183], v[44:47]
	v_mfma_f32_16x16x32_bf16 v[28:31], v[128:131], v[188:191], v[28:31]
	v_mfma_f32_16x16x32_bf16 v[28:31], v[132:135], v[192:195], v[28:31]
	v_mfma_f32_16x16x32_bf16 v[24:27], v[140:143], v[192:195], v[24:27]
	v_mfma_f32_16x16x32_bf16 v[24:27], v[136:139], v[188:191], v[24:27]
	v_mfma_f32_16x16x32_bf16 v[20:23], v[144:147], v[188:191], v[20:23]
	v_mfma_f32_16x16x32_bf16 v[20:23], v[160:163], v[192:195], v[20:23]
	v_mfma_f32_16x16x32_bf16 v[16:19], v[168:171], v[192:195], v[16:19]
	v_mfma_f32_16x16x32_bf16 v[16:19], v[164:167], v[188:191], v[16:19]
	v_mfma_f32_16x16x32_bf16 v[0:3], v[164:167], v[196:199], v[0:3]
	v_mfma_f32_16x16x32_bf16 v[0:3], v[168:171], v[212:215], v[0:3]
	v_mfma_f32_16x16x32_bf16 v[4:7], v[160:163], v[212:215], v[4:7]
	v_mfma_f32_16x16x32_bf16 v[4:7], v[144:147], v[196:199], v[4:7]
	v_mfma_f32_16x16x32_bf16 v[8:11], v[136:139], v[196:199], v[8:11]
	v_mfma_f32_16x16x32_bf16 v[8:11], v[140:143], v[212:215], v[8:11]
	v_mfma_f32_16x16x32_bf16 v[12:15], v[132:135], v[212:215], v[12:15]
	v_mfma_f32_16x16x32_bf16 v[12:15], v[128:131], v[196:199], v[12:15]
	s_barrier
	s_add_u32 s0, s0, 0x100
	s_addc_u32 s1, s1, 0
	s_add_u32 s38, s38, 0x100
	s_addc_u32 s39, s39, 0
	s_cmp_ge_i32 s41, s56
	s_mov_b32 s6, s41
	s_cbranch_scc0 .LBB0_1159
